# GLA scan LDS offsets; GU/proj epilogue rcp+cvt_pk_bf16; combine gate GEMV LDS reads pipelined before vmcnt wait
# speedup vs baseline: 1.0148x; 1.0148x over previous
; #define G_STAGE(bufoff, gbase, voff) do { _Pragma("unroll") for (int _i = 0; _i < 2; ++_i) \
;     __builtin_amdgcn_global_load_lds((const unsigned*)((const char*)(gbase) + (voff)[_i]), (LAS unsigned*)(lds + (bufoff) + ldsw + _i * 8192), 16, 0, 0); } while (0)
; #define G_LDA(dst, b, h) do { _Pragma("unroll") for (int m = 0; m < 4; ++m) _Pragma("unroll") for (int k = 0; k < 2; ++k) dst[m][k] = *(const LAS bf16x8*)(lds + G_SA(b, h) + aoff + m * 2048 + k * 1024); } while (0)
; #define G_LDB(dst, b, h) do { _Pragma("unroll") for (int n = 0; n < 2; ++n) _Pragma("unroll") for (int k = 0; k < 2; ++k) dst[n][k] = *(const LAS bf16x8*)(lds + G_SB(b, h) + boff + n * 2048 + k * 1024); } while (0)
; #define G_MMA(ai, bj, At, Bt) do { __builtin_amdgcn_s_setprio(1); _Pragma("unroll") for (int m = 0; m < 4; ++m) _Pragma("unroll") for (int n = 0; n < 2; ++n) _Pragma("unroll") for (int k = 0; k < 2; ++k) \
;     acc[ai][bj][m][n] = __builtin_amdgcn_mfma_f32_16x16x32_bf16(Bt[n][k], At[m][k], acc[ai][bj][m][n], 0, 0, 0); __builtin_amdgcn_s_setprio(0); } while (0)
; #define G_WAIT_V(n) asm volatile("s_waitcnt vmcnt(" #n ")" ::: "memory")
; #define G_WAIT_L(n) asm volatile("s_waitcnt lgkmcnt(" #n ")" ::: "memory")
; #define G_BAR __builtin_amdgcn_s_barrier()
; #define G_SCHED __builtin_amdgcn_sched_barrier(0)
; template <class Epi>
; __device__ __forceinline__ void gemm_phase(LAS unsigned char* lds, const u16* gA, const u16* gBt, int M, int N, int K, const Epi& E) {
;     ...
;     for (int t = 0; t < nt; t += 2) {
;       const bool last = (t == nt - 2);
;       const char* a1 = cA + (size_t)(t + 1) * kstep;
;       const char* a2 = last ? nA : cA + (size_t)(t + 2) * kstep; const char* b2 = last ? nB : cB + (size_t)(t + 2) * kstep;
;       const char* a3 = a2 + kstep; const char* b3 = b2 + kstep;
;       G_LDB(B0, 0, 0); G_SCHED; G_LDA(At, 0, 0); G_STAGE(G_SA(1, 1), a1 + hstep, voffA);
;       G_WAIT_L(8); G_BAR; G_WAIT_L(0); G_MMA(0, 0, At, B0); G_BAR; G_SCHED;
;       G_LDB(B1, 0, 1); G_STAGE(G_SB(0, 0), b2, voffB);
;       G_BAR; G_WAIT_L(0); G_MMA(0, 1, At, B1); G_BAR;
;       G_LDA(At, 0, 1); G_STAGE(G_SA(0, 0), a2, voffA);
;       G_BAR; G_WAIT_L(0); G_MMA(1, 0, At, B0); G_BAR; G_SCHED;
;       G_STAGE(G_SB(0, 1), b2 + hstep, voffB);
;       G_WAIT_V(6); G_BAR; G_MMA(1, 1, At, B1); G_BAR;
.LBB0_56:
	s_add_u32 s20, s50, 0xfff80080
	s_addc_u32 s22, s51, -1
	s_add_i32 s24, 0, 0x10000
	v_add_u32_e32 v144, s24, v147
	ds_read_b128 v[140:143], v144
	ds_read_b128 v[150:153], v144 offset:1024
	ds_read_b128 v[154:157], v144 offset:2048
	ds_read_b128 v[158:161], v144 offset:3072
	s_cmp_eq_u32 s45, 28
	s_cselect_b32 s55, s26, s22
	s_cselect_b32 s54, s27, s20
	s_cselect_b32 s53, s30, s41
	s_cselect_b32 s52, s31, s33
	v_lshl_add_u64 v[144:145], s[50:51], 0, v[136:137]
	s_add_i32 m0, s3, 0xc000
	ds_read_b128 v[162:165], v149
	ds_read_b128 v[190:193], v149 offset:1024
	ds_read_b128 v[194:197], v149 offset:2048
	ds_read_b128 v[198:201], v149 offset:3072
	ds_read_b128 v[202:205], v149 offset:4096
	ds_read_b128 v[206:209], v149 offset:5120
	ds_read_b128 v[210:213], v149 offset:6144
	ds_read_b128 v[214:217], v149 offset:7168
	global_load_lds_dwordx4 v[144:145], off
	v_lshl_add_u64 v[144:145], s[50:51], 0, v[138:139]
	s_add_i32 m0, s3, 0xe000
	s_nop 0
	global_load_lds_dwordx4 v[144:145], off
	s_waitcnt lgkmcnt(8)
	s_barrier
	s_waitcnt lgkmcnt(0)
	s_setprio 1
	s_waitcnt lgkmcnt(0)
	v_mfma_f32_16x16x32_bf16 v[124:127], v[140:143], v[162:165], v[124:127]
	v_mfma_f32_16x16x32_bf16 v[116:119], v[154:157], v[162:165], v[116:119]
	v_mfma_f32_16x16x32_bf16 v[108:111], v[140:143], v[194:197], v[108:111]
	v_mfma_f32_16x16x32_bf16 v[100:103], v[154:157], v[194:197], v[100:103]
	v_mfma_f32_16x16x32_bf16 v[92:95], v[140:143], v[202:205], v[92:95]
	v_mfma_f32_16x16x32_bf16 v[84:87], v[154:157], v[202:205], v[84:87]
	v_mfma_f32_16x16x32_bf16 v[76:79], v[140:143], v[210:213], v[76:79]
	v_mfma_f32_16x16x32_bf16 v[68:71], v[154:157], v[210:213], v[68:71]
	v_mfma_f32_16x16x32_bf16 v[124:127], v[150:153], v[190:193], v[124:127]
	v_mfma_f32_16x16x32_bf16 v[116:119], v[158:161], v[190:193], v[116:119]
	v_mfma_f32_16x16x32_bf16 v[108:111], v[150:153], v[198:201], v[108:111]
	v_mfma_f32_16x16x32_bf16 v[100:103], v[158:161], v[198:201], v[100:103]
	v_mfma_f32_16x16x32_bf16 v[92:95], v[150:153], v[206:209], v[92:95]
	v_mfma_f32_16x16x32_bf16 v[84:87], v[158:161], v[206:209], v[84:87]
	v_mfma_f32_16x16x32_bf16 v[76:79], v[150:153], v[214:217], v[76:79]
	v_mfma_f32_16x16x32_bf16 v[68:71], v[158:161], v[214:217], v[68:71]
	s_setprio 0
	s_barrier
	s_add_i32 s20, 0, 0x14000
	v_add_u32_e32 v144, s20, v147
	s_add_i32 s22, s24, s64
	ds_read_b128 v[218:221], v144
	ds_read_b128 v[222:225], v144 offset:1024
	ds_read_b128 v[226:229], v144 offset:2048
	ds_read_b128 v[230:233], v144 offset:3072
	v_lshl_add_u64 v[144:145], s[52:53], 0, v[128:129]
	s_mov_b32 m0, s22
	v_lshl_add_u64 v[166:167], s[52:53], 0, v[134:135]
	global_load_lds_dwordx4 v[144:145], off
	s_add_i32 m0, s22, 0x2000
	s_nop 0
	global_load_lds_dwordx4 v[166:167], off
	s_barrier
	s_waitcnt lgkmcnt(0)
	s_setprio 1
	s_waitcnt lgkmcnt(0)
	v_mfma_f32_16x16x32_bf16 v[120:123], v[218:221], v[162:165], v[120:123]
	v_mfma_f32_16x16x32_bf16 v[112:115], v[226:229], v[162:165], v[112:115]
	v_mfma_f32_16x16x32_bf16 v[104:107], v[218:221], v[194:197], v[104:107]
	v_mfma_f32_16x16x32_bf16 v[96:99], v[226:229], v[194:197], v[96:99]
	v_mfma_f32_16x16x32_bf16 v[88:91], v[218:221], v[202:205], v[88:91]
	v_mfma_f32_16x16x32_bf16 v[80:83], v[226:229], v[202:205], v[80:83]
	v_mfma_f32_16x16x32_bf16 v[72:75], v[218:221], v[210:213], v[72:75]
	v_mfma_f32_16x16x32_bf16 v[64:67], v[226:229], v[210:213], v[64:67]
	v_mfma_f32_16x16x32_bf16 v[120:123], v[222:225], v[190:193], v[120:123]
	v_mfma_f32_16x16x32_bf16 v[112:115], v[230:233], v[190:193], v[112:115]
	v_mfma_f32_16x16x32_bf16 v[104:107], v[222:225], v[198:201], v[104:107]
	v_mfma_f32_16x16x32_bf16 v[96:99], v[230:233], v[198:201], v[96:99]
	v_mfma_f32_16x16x32_bf16 v[88:91], v[222:225], v[206:209], v[88:91]
	v_mfma_f32_16x16x32_bf16 v[80:83], v[230:233], v[206:209], v[80:83]
	v_mfma_f32_16x16x32_bf16 v[72:75], v[222:225], v[214:217], v[72:75]
	v_mfma_f32_16x16x32_bf16 v[64:67], v[230:233], v[214:217], v[64:67]
	s_setprio 0
	s_mov_b32 m0, s3
	v_lshl_add_u64 v[234:235], s[54:55], 0, v[128:129]
	s_barrier
	ds_read_b128 v[162:165], v149 offset:16384
	ds_read_b128 v[190:193], v149 offset:17408
	ds_read_b128 v[194:197], v149 offset:18432
	ds_read_b128 v[198:201], v149 offset:19456
	ds_read_b128 v[202:205], v149 offset:20480
	ds_read_b128 v[206:209], v149 offset:21504
	ds_read_b128 v[210:213], v149 offset:22528
	ds_read_b128 v[214:217], v149 offset:23552
	global_load_lds_dwordx4 v[234:235], off
	v_lshl_add_u64 v[236:237], s[54:55], 0, v[134:135]
	s_mov_b32 m0, s67
	s_nop 0
	global_load_lds_dwordx4 v[236:237], off
	s_barrier
	s_waitcnt lgkmcnt(0)
	s_setprio 1
	s_waitcnt lgkmcnt(0)
	v_mfma_f32_16x16x32_bf16 v[60:63], v[140:143], v[162:165], v[60:63]
	v_mfma_f32_16x16x32_bf16 v[52:55], v[154:157], v[162:165], v[52:55]
	v_mfma_f32_16x16x32_bf16 v[44:47], v[140:143], v[194:197], v[44:47]
	v_mfma_f32_16x16x32_bf16 v[36:39], v[154:157], v[194:197], v[36:39]
	v_mfma_f32_16x16x32_bf16 v[28:31], v[140:143], v[202:205], v[28:31]
	v_mfma_f32_16x16x32_bf16 v[20:23], v[154:157], v[202:205], v[20:23]
	v_mfma_f32_16x16x32_bf16 v[12:15], v[140:143], v[210:213], v[12:15]
	v_mfma_f32_16x16x32_bf16 v[4:7], v[154:157], v[210:213], v[4:7]
	v_mfma_f32_16x16x32_bf16 v[60:63], v[150:153], v[190:193], v[60:63]
	v_mfma_f32_16x16x32_bf16 v[52:55], v[158:161], v[190:193], v[52:55]
	v_mfma_f32_16x16x32_bf16 v[44:47], v[150:153], v[198:201], v[44:47]
	v_mfma_f32_16x16x32_bf16 v[36:39], v[158:161], v[198:201], v[36:39]
	v_mfma_f32_16x16x32_bf16 v[28:31], v[150:153], v[206:209], v[28:31]
	v_mfma_f32_16x16x32_bf16 v[20:23], v[158:161], v[206:209], v[20:23]
	v_mfma_f32_16x16x32_bf16 v[12:15], v[150:153], v[214:217], v[12:15]
	v_mfma_f32_16x16x32_bf16 v[4:7], v[158:161], v[214:217], v[4:7]
	s_setprio 0
	s_barrier
; #define G_STAGE(bufoff, gbase, voff) do { _Pragma("unroll") for (int _i = 0; _i < 2; ++_i) \
;     __builtin_amdgcn_global_load_lds((const unsigned*)((const char*)(gbase) + (voff)[_i]), (LAS unsigned*)(lds + (bufoff) + ldsw + _i * 8192), 16, 0, 0); } while (0)
; #define G_LDA(dst, b, h) do { _Pragma("unroll") for (int m = 0; m < 4; ++m) _Pragma("unroll") for (int k = 0; k < 2; ++k) dst[m][k] = *(const LAS bf16x8*)(lds + G_SA(b, h) + aoff + m * 2048 + k * 1024); } while (0)
; #define G_LDB(dst, b, h) do { _Pragma("unroll") for (int n = 0; n < 2; ++n) _Pragma("unroll") for (int k = 0; k < 2; ++k) dst[n][k] = *(const LAS bf16x8*)(lds + G_SB(b, h) + boff + n * 2048 + k * 1024); } while (0)
; #define G_MMA(ai, bj, At, Bt) do { __builtin_amdgcn_s_setprio(1); _Pragma("unroll") for (int m = 0; m < 4; ++m) _Pragma("unroll") for (int n = 0; n < 2; ++n) _Pragma("unroll") for (int k = 0; k < 2; ++k) \
;     acc[ai][bj][m][n] = __builtin_amdgcn_mfma_f32_16x16x32_bf16(Bt[n][k], At[m][k], acc[ai][bj][m][n], 0, 0, 0); __builtin_amdgcn_s_setprio(0); } while (0)
; #define G_WAIT_V(n) asm volatile("s_waitcnt vmcnt(" #n ")" ::: "memory")
; #define G_WAIT_L(n) asm volatile("s_waitcnt lgkmcnt(" #n ")" ::: "memory")
; #define G_BAR __builtin_amdgcn_s_barrier()
; #define G_SCHED __builtin_amdgcn_sched_barrier(0)
; template <class Epi>
; __device__ __forceinline__ void gemm_phase(LAS unsigned char* lds, const u16* gA, const u16* gBt, int M, int N, int K, const Epi& E) {
;     ...
;       G_LDB(B0, 1, 0); G_SCHED; G_LDA(At, 1, 0); G_STAGE(G_SA(0, 1), a2 + hstep, voffA);
;       G_WAIT_L(8); G_BAR; G_WAIT_L(0); G_MMA(0, 0, At, B0); G_BAR; G_SCHED;
;       G_LDB(B1, 1, 1); G_STAGE(G_SB(1, 0), b3, voffB);
;       G_BAR; G_WAIT_L(0); G_MMA(0, 1, At, B1); G_BAR;
;       G_LDA(At, 1, 1); G_STAGE(G_SA(1, 0), a3, voffA);
;       G_BAR; G_WAIT_L(0); G_MMA(1, 0, At, B0); G_BAR; G_SCHED;
;       G_STAGE(G_SB(1, 1), b3 + hstep, voffB);
;       G_WAIT_V(6); G_BAR; G_MMA(1, 1, At, B1); G_BAR;
	s_add_u32 s24, s52, 0x80000
	s_addc_u32 s25, s53, 0
	s_add_i32 s20, s20, s64
	v_lshl_add_u64 v[140:141], s[24:25], 0, v[128:129]
	s_mov_b32 m0, s20
	s_nop 0
	global_load_lds_dwordx4 v[140:141], off
	v_lshl_add_u64 v[140:141], s[24:25], 0, v[134:135]
	s_add_i32 m0, s20, 0x2000
	s_nop 0
	global_load_lds_dwordx4 v[140:141], off
	s_waitcnt vmcnt(6)
	s_barrier
	s_setprio 1
	v_mfma_f32_16x16x32_bf16 v[56:59], v[218:221], v[162:165], v[56:59]
	v_mfma_f32_16x16x32_bf16 v[48:51], v[226:229], v[162:165], v[48:51]
	v_mfma_f32_16x16x32_bf16 v[40:43], v[218:221], v[194:197], v[40:43]
	v_mfma_f32_16x16x32_bf16 v[32:35], v[226:229], v[194:197], v[32:35]
	v_mfma_f32_16x16x32_bf16 v[24:27], v[218:221], v[202:205], v[24:27]
	v_mfma_f32_16x16x32_bf16 v[16:19], v[226:229], v[202:205], v[16:19]
	v_mfma_f32_16x16x32_bf16 v[8:11], v[218:221], v[210:213], v[8:11]
	v_mfma_f32_16x16x32_bf16 v[0:3], v[226:229], v[210:213], v[0:3]
	v_mfma_f32_16x16x32_bf16 v[56:59], v[222:225], v[190:193], v[56:59]
	v_mfma_f32_16x16x32_bf16 v[48:51], v[230:233], v[190:193], v[48:51]
	v_mfma_f32_16x16x32_bf16 v[40:43], v[222:225], v[198:201], v[40:43]
	v_mfma_f32_16x16x32_bf16 v[32:35], v[230:233], v[198:201], v[32:35]
	v_mfma_f32_16x16x32_bf16 v[24:27], v[222:225], v[206:209], v[24:27]
	v_mfma_f32_16x16x32_bf16 v[16:19], v[230:233], v[206:209], v[16:19]
	v_mfma_f32_16x16x32_bf16 v[8:11], v[222:225], v[214:217], v[8:11]
	v_mfma_f32_16x16x32_bf16 v[0:3], v[230:233], v[214:217], v[0:3]
	s_setprio 0
	s_add_i32 s20, 0, 0x18000
	v_add_u32_e32 v158, s20, v147
	s_barrier
	ds_read_b128 v[140:143], v158
	ds_read_b128 v[150:153], v158 offset:1024
	ds_read_b128 v[154:157], v158 offset:2048
	ds_read_b128 v[158:161], v158 offset:3072
	s_add_u32 s24, s54, 0x80000
	s_addc_u32 s25, s55, 0
	s_mov_b32 m0, s68
	v_lshl_add_u64 v[218:219], s[24:25], 0, v[128:129]
	ds_read_b128 v[162:165], v149 offset:32768
	ds_read_b128 v[190:193], v149 offset:33792
	ds_read_b128 v[194:197], v149 offset:34816
	ds_read_b128 v[198:201], v149 offset:35840
	ds_read_b128 v[202:205], v149 offset:36864
	ds_read_b128 v[206:209], v149 offset:37888
	ds_read_b128 v[210:213], v149 offset:38912
	ds_read_b128 v[214:217], v149 offset:39936
	global_load_lds_dwordx4 v[218:219], off
	v_lshl_add_u64 v[218:219], s[24:25], 0, v[134:135]
	s_mov_b32 m0, s69
	s_nop 0
	global_load_lds_dwordx4 v[218:219], off
	s_waitcnt lgkmcnt(8)
	s_barrier
	s_waitcnt lgkmcnt(0)
	s_setprio 1
	s_waitcnt lgkmcnt(0)
	v_mfma_f32_16x16x32_bf16 v[124:127], v[140:143], v[162:165], v[124:127]
	v_mfma_f32_16x16x32_bf16 v[116:119], v[154:157], v[162:165], v[116:119]
	v_mfma_f32_16x16x32_bf16 v[108:111], v[140:143], v[194:197], v[108:111]
	v_mfma_f32_16x16x32_bf16 v[100:103], v[154:157], v[194:197], v[100:103]
	v_mfma_f32_16x16x32_bf16 v[92:95], v[140:143], v[202:205], v[92:95]
	v_mfma_f32_16x16x32_bf16 v[84:87], v[154:157], v[202:205], v[84:87]
	v_mfma_f32_16x16x32_bf16 v[76:79], v[140:143], v[210:213], v[76:79]
	v_mfma_f32_16x16x32_bf16 v[68:71], v[154:157], v[210:213], v[68:71]
	v_mfma_f32_16x16x32_bf16 v[124:127], v[150:153], v[190:193], v[124:127]
	v_mfma_f32_16x16x32_bf16 v[116:119], v[158:161], v[190:193], v[116:119]
	v_mfma_f32_16x16x32_bf16 v[108:111], v[150:153], v[198:201], v[108:111]
	v_mfma_f32_16x16x32_bf16 v[100:103], v[158:161], v[198:201], v[100:103]
	v_mfma_f32_16x16x32_bf16 v[92:95], v[150:153], v[206:209], v[92:95]
	v_mfma_f32_16x16x32_bf16 v[84:87], v[158:161], v[206:209], v[84:87]
	v_mfma_f32_16x16x32_bf16 v[76:79], v[150:153], v[214:217], v[76:79]
	v_mfma_f32_16x16x32_bf16 v[68:71], v[158:161], v[214:217], v[68:71]
	s_setprio 0
	s_barrier
	s_add_i32 s22, 0, 0x1c000
	s_add_i32 s20, s20, s64
	v_add_u32_e32 v230, s22, v147
	v_lshl_add_u64 v[144:145], v[144:145], 0, s[34:35]
	s_mov_b32 m0, s20
	ds_read_b128 v[218:221], v230
	ds_read_b128 v[222:225], v230 offset:1024
	ds_read_b128 v[226:229], v230 offset:2048
	ds_read_b128 v[230:233], v230 offset:3072
	global_load_lds_dwordx4 v[144:145], off
	v_lshl_add_u64 v[144:145], v[166:167], 0, s[34:35]
	s_add_i32 m0, s20, 0x2000
	s_nop 0
	global_load_lds_dwordx4 v[144:145], off
	s_barrier
	s_waitcnt lgkmcnt(0)
	s_setprio 1
	s_waitcnt lgkmcnt(0)
	v_mfma_f32_16x16x32_bf16 v[120:123], v[218:221], v[162:165], v[120:123]
	v_mfma_f32_16x16x32_bf16 v[112:115], v[226:229], v[162:165], v[112:115]
	v_mfma_f32_16x16x32_bf16 v[104:107], v[218:221], v[194:197], v[104:107]
	v_mfma_f32_16x16x32_bf16 v[96:99], v[226:229], v[194:197], v[96:99]
	v_mfma_f32_16x16x32_bf16 v[88:91], v[218:221], v[202:205], v[88:91]
	v_mfma_f32_16x16x32_bf16 v[80:83], v[226:229], v[202:205], v[80:83]
	v_mfma_f32_16x16x32_bf16 v[72:75], v[218:221], v[210:213], v[72:75]
	v_mfma_f32_16x16x32_bf16 v[64:67], v[226:229], v[210:213], v[64:67]
	v_mfma_f32_16x16x32_bf16 v[120:123], v[222:225], v[190:193], v[120:123]
	v_mfma_f32_16x16x32_bf16 v[112:115], v[230:233], v[190:193], v[112:115]
	v_mfma_f32_16x16x32_bf16 v[104:107], v[222:225], v[198:201], v[104:107]
	v_mfma_f32_16x16x32_bf16 v[96:99], v[230:233], v[198:201], v[96:99]
	v_mfma_f32_16x16x32_bf16 v[88:91], v[222:225], v[206:209], v[88:91]
	v_mfma_f32_16x16x32_bf16 v[80:83], v[230:233], v[206:209], v[80:83]
	v_mfma_f32_16x16x32_bf16 v[72:75], v[222:225], v[214:217], v[72:75]
	v_mfma_f32_16x16x32_bf16 v[64:67], v[230:233], v[214:217], v[64:67]
	s_setprio 0
	s_mov_b32 m0, s71
	v_lshl_add_u64 v[144:145], v[234:235], 0, s[34:35]
	s_barrier
	ds_read_b128 v[162:165], v149 offset:49152
	ds_read_b128 v[190:193], v149 offset:50176
	ds_read_b128 v[194:197], v149 offset:51200
	ds_read_b128 v[198:201], v149 offset:52224
	ds_read_b128 v[202:205], v149 offset:53248
	ds_read_b128 v[206:209], v149 offset:54272
	ds_read_b128 v[210:213], v149 offset:55296
	ds_read_b128 v[214:217], v149 offset:56320
	global_load_lds_dwordx4 v[144:145], off
	v_lshl_add_u64 v[144:145], v[236:237], 0, s[34:35]
	s_mov_b32 m0, s72
	s_nop 0
	global_load_lds_dwordx4 v[144:145], off
	s_barrier
; __device__ __forceinline__ float siluf_(float x) { return x / (1.f + __expf(-x)); }
; __device__ __forceinline__ unsigned pk_bf16(float lo, float hi) { return (unsigned)f2bf(lo) | ((unsigned)f2bf(hi) << 16); }
; #define G_STAGE(bufoff, gbase, voff) do { _Pragma("unroll") for (int _i = 0; _i < 2; ++_i) \
;     __builtin_amdgcn_global_load_lds((const unsigned*)((const char*)(gbase) + (voff)[_i]), (LAS unsigned*)(lds + (bufoff) + ldsw + _i * 8192), 16, 0, 0); } while (0)
; #define G_MMA(ai, bj, At, Bt) do { __builtin_amdgcn_s_setprio(1); _Pragma("unroll") for (int m = 0; m < 4; ++m) _Pragma("unroll") for (int n = 0; n < 2; ++n) _Pragma("unroll") for (int k = 0; k < 2; ++k) \
;     acc[ai][bj][m][n] = __builtin_amdgcn_mfma_f32_16x16x32_bf16(Bt[n][k], At[m][k], acc[ai][bj][m][n], 0, 0, 0); __builtin_amdgcn_s_setprio(0); } while (0)
; #define G_WAIT_V(n) asm volatile("s_waitcnt vmcnt(" #n ")" ::: "memory")
; #define G_WAIT_L(n) asm volatile("s_waitcnt lgkmcnt(" #n ")" ::: "memory")
; #define G_BAR __builtin_amdgcn_s_barrier()
; #define G_SCHED __builtin_amdgcn_sched_barrier(0)
;   __device__ __forceinline__ void operator()(const f32x4 (&acc)[2][2][4][2], const Unit& u, int wr, int wc, int fr, int fq) const {
;     const int row0 = u.pm * BM + wr * 64 + fr, col0 = u.pn * HALF + wc * 32 + 4 * fq;
; #pragma unroll
;     for (int ai = 0; ai < 2; ++ai)
; #pragma unroll
;       for (int m = 0; m < 4; ++m) {
;         u16* rowp = O + (size_t)(row0 + ai * HALF + m * 16) * FFN + col0;
; #pragma unroll
;         for (int n = 0; n < 2; ++n) {
;           f32x4 g = acc[ai][0][m][n], up = acc[ai][1][m][n];
;           uint2 w;
;           w.x = pk_bf16(siluf_(g[0]) * up[0], siluf_(g[1]) * up[1]);
;           w.y = pk_bf16(siluf_(g[2]) * up[2], siluf_(g[3]) * up[3]);
;           *reinterpret_cast<uint2*>(rowp + n * 16) = w;
;         }
;       }
;   }
; template <class Epi>
; __device__ __forceinline__ void gemm_phase(LAS unsigned char* lds, const u16* gA, const u16* gBt, int M, int N, int K, const Epi& E) {
;     ...
;       G_BAR; G_WAIT_L(0); G_MMA(1, 0, At, B0); G_BAR; G_SCHED;
;       G_STAGE(G_SB(1, 1), b3 + hstep, voffB);
;       G_WAIT_V(6); G_BAR; G_MMA(1, 1, At, B1); G_BAR;
;     }
;     E(acc, cur, wr, wc, fr, fq);
;     if (!has_next) break;
	s_waitcnt lgkmcnt(0)
	s_setprio 1
	s_waitcnt lgkmcnt(0)
	v_mfma_f32_16x16x32_bf16 v[60:63], v[140:143], v[162:165], v[60:63]
	v_mfma_f32_16x16x32_bf16 v[52:55], v[154:157], v[162:165], v[52:55]
	v_mfma_f32_16x16x32_bf16 v[44:47], v[140:143], v[194:197], v[44:47]
	v_mfma_f32_16x16x32_bf16 v[36:39], v[154:157], v[194:197], v[36:39]
	v_mfma_f32_16x16x32_bf16 v[28:31], v[140:143], v[202:205], v[28:31]
	v_mfma_f32_16x16x32_bf16 v[20:23], v[154:157], v[202:205], v[20:23]
	v_mfma_f32_16x16x32_bf16 v[12:15], v[140:143], v[210:213], v[12:15]
	v_mfma_f32_16x16x32_bf16 v[4:7], v[154:157], v[210:213], v[4:7]
	v_mfma_f32_16x16x32_bf16 v[60:63], v[150:153], v[190:193], v[60:63]
	v_mfma_f32_16x16x32_bf16 v[52:55], v[158:161], v[190:193], v[52:55]
	v_mfma_f32_16x16x32_bf16 v[44:47], v[150:153], v[198:201], v[44:47]
	v_mfma_f32_16x16x32_bf16 v[36:39], v[158:161], v[198:201], v[36:39]
	v_mfma_f32_16x16x32_bf16 v[28:31], v[150:153], v[206:209], v[28:31]
	v_mfma_f32_16x16x32_bf16 v[20:23], v[158:161], v[206:209], v[20:23]
	v_mfma_f32_16x16x32_bf16 v[12:15], v[150:153], v[214:217], v[12:15]
	v_mfma_f32_16x16x32_bf16 v[4:7], v[158:161], v[214:217], v[4:7]
	s_setprio 0
	s_barrier
	s_add_u32 s24, s52, 0x80080
	s_addc_u32 s25, s53, 0
	s_add_i32 s20, s22, s64
	v_lshl_add_u64 v[140:141], s[24:25], 0, v[128:129]
	s_mov_b32 m0, s20
	s_nop 0
	global_load_lds_dwordx4 v[140:141], off
	v_lshl_add_u64 v[140:141], s[24:25], 0, v[134:135]
	s_add_i32 m0, s20, 0x2000
	s_nop 0
	global_load_lds_dwordx4 v[140:141], off
	s_waitcnt vmcnt(6)
	s_barrier
	s_setprio 1
	v_mfma_f32_16x16x32_bf16 v[56:59], v[218:221], v[162:165], v[56:59]
	v_mfma_f32_16x16x32_bf16 v[48:51], v[226:229], v[162:165], v[48:51]
	v_mfma_f32_16x16x32_bf16 v[40:43], v[218:221], v[194:197], v[40:43]
	v_mfma_f32_16x16x32_bf16 v[32:35], v[226:229], v[194:197], v[32:35]
	v_mfma_f32_16x16x32_bf16 v[24:27], v[218:221], v[202:205], v[24:27]
	v_mfma_f32_16x16x32_bf16 v[16:19], v[226:229], v[202:205], v[16:19]
	v_mfma_f32_16x16x32_bf16 v[8:11], v[218:221], v[210:213], v[8:11]
	v_mfma_f32_16x16x32_bf16 v[0:3], v[226:229], v[210:213], v[0:3]
	v_mfma_f32_16x16x32_bf16 v[56:59], v[222:225], v[190:193], v[56:59]
	v_mfma_f32_16x16x32_bf16 v[48:51], v[230:233], v[190:193], v[48:51]
	v_mfma_f32_16x16x32_bf16 v[40:43], v[222:225], v[198:201], v[40:43]
	v_mfma_f32_16x16x32_bf16 v[32:35], v[230:233], v[198:201], v[32:35]
	v_mfma_f32_16x16x32_bf16 v[24:27], v[222:225], v[206:209], v[24:27]
	v_mfma_f32_16x16x32_bf16 v[16:19], v[230:233], v[206:209], v[16:19]
	v_mfma_f32_16x16x32_bf16 v[8:11], v[222:225], v[214:217], v[8:11]
	v_mfma_f32_16x16x32_bf16 v[0:3], v[230:233], v[214:217], v[0:3]
	s_setprio 0
	s_add_i32 s45, s45, 2
	s_add_u32 s50, s50, 0x100
	s_addc_u32 s51, s51, 0
	s_add_u32 s33, s33, 0x100
	s_addc_u32 s41, s41, 0
	s_cmp_gt_u32 s45, 29
	s_barrier
	s_cbranch_scc0 .LBB0_56
	v_mul_f32_e32 v151, 0xbfb8aa3b, v124
	v_exp_f32_e32 v152, v151
	v_mul_f32_e32 v151, 0xbfb8aa3b, v125
	v_exp_f32_e32 v154, v151
	v_mul_f32_e32 v151, 0xbfb8aa3b, v126
	v_exp_f32_e32 v153, v151
	v_mul_f32_e32 v151, 0xbfb8aa3b, v127
	v_lshl_or_b32 v142, s23, 7, v148
	v_exp_f32_e32 v155, v151
	v_pk_add_f32 v[152:153], v[152:153], 1.0 op_sel_hi:[1,0]
	v_lshl_add_u32 v150, s2, 8, v146
	v_pk_add_f32 v[154:155], v[154:155], 1.0 op_sel_hi:[1,0]
	v_ashrrev_i32_e32 v143, 31, v142
	v_mov_b64_e32 v[140:141], s[94:95]
	v_rcp_f32_e32 v151, v153
	s_nop 0
	v_mul_f32_e32 v153, v126, v151
	s_movk_i32 s2, 0x2c00
	v_mad_i64_i32 v[144:145], s[22:23], v150, s2, v[140:141]
	v_mov_b32_e32 v156, v120
	v_mov_b32_e32 v157, v122
	v_rcp_f32_e32 v126, v152
	s_nop 0
	v_mul_f32_e32 v152, v124, v126
	v_pk_mul_f32 v[152:153], v[152:153], v[156:157]
	v_lshlrev_b64 v[142:143], 1, v[142:143]
	v_rcp_f32_e32 v120, v155
	s_nop 0
	v_mul_f32_e32 v127, v127, v120
	v_lshl_add_u64 v[144:145], v[144:145], 0, v[142:143]
	s_mov_b64 s[52:53], s[48:49]
	s_mov_b64 s[50:51], s[46:47]
	v_rcp_f32_e32 v120, v154
	s_nop 0
	v_mul_f32_e32 v126, v125, v120
	v_mov_b32_e32 v122, v121
	v_pk_mul_f32 v[120:121], v[126:127], v[122:123]
	s_nop 0
	v_cvt_pk_bf16_f32 v121, v153, v121
	v_cvt_pk_bf16_f32 v120, v152, v120
	global_store_dwordx2 v[144:145], v[120:121], off
	v_mul_f32_e32 v121, 0xbfb8aa3b, v117
	v_mul_f32_e32 v120, 0xbfb8aa3b, v116
	v_exp_f32_e32 v122, v121
	v_mul_f32_e32 v121, 0xbfb8aa3b, v118
	v_exp_f32_e32 v120, v120
	v_exp_f32_e32 v121, v121
	v_mul_f32_e32 v123, 0xbfb8aa3b, v119
	v_exp_f32_e32 v123, v123
	v_pk_add_f32 v[120:121], v[120:121], 1.0 op_sel_hi:[1,0]
	s_nop 0
	v_pk_add_f32 v[122:123], v[122:123], 1.0 op_sel_hi:[1,0]
	v_rcp_f32_e32 v124, v121
	s_nop 0
	v_mul_f32_e32 v121, v118, v124
	s_nop 0
	v_mov_b32_e32 v124, v112
	v_mov_b32_e32 v125, v114
	v_rcp_f32_e32 v118, v120
	s_nop 0
	v_mul_f32_e32 v120, v116, v118
	v_pk_mul_f32 v[120:121], v[120:121], v[124:125]
	v_rcp_f32_e32 v112, v123
	s_nop 0
	v_mul_f32_e32 v119, v119, v112
	s_nop 0
	v_rcp_f32_e32 v112, v122
	s_nop 0
	v_mul_f32_e32 v118, v117, v112
	v_mov_b32_e32 v114, v113
	v_pk_mul_f32 v[112:113], v[118:119], v[114:115]
	s_nop 0
	v_cvt_pk_bf16_f32 v112, v120, v112
	v_mul_f32_e32 v115, 0xbfb8aa3b, v109
	v_cvt_pk_bf16_f32 v113, v121, v113
	v_mul_f32_e32 v114, 0xbfb8aa3b, v108
	v_exp_f32_e32 v116, v115
	v_mul_f32_e32 v115, 0xbfb8aa3b, v110
	v_exp_f32_e32 v114, v114
	v_exp_f32_e32 v115, v115
	v_mul_f32_e32 v117, 0xbfb8aa3b, v111
	v_exp_f32_e32 v117, v117
	global_store_dwordx2 v[144:145], v[112:113], off offset:32
	v_pk_add_f32 v[114:115], v[114:115], 1.0 op_sel_hi:[1,0]
	v_or_b32_e32 v112, 16, v150
	v_pk_add_f32 v[116:117], v[116:117], 1.0 op_sel_hi:[1,0]
	v_mad_i64_i32 v[112:113], s[22:23], v112, s2, v[140:141]
	v_rcp_f32_e32 v118, v115
	s_nop 0
; __device__ __forceinline__ float siluf_(float x) { return x / (1.f + __expf(-x)); }
; __device__ __forceinline__ unsigned pk_bf16(float lo, float hi) { return (unsigned)f2bf(lo) | ((unsigned)f2bf(hi) << 16); }
;   __device__ __forceinline__ void operator()(const f32x4 (&acc)[2][2][4][2], const Unit& u, int wr, int wc, int fr, int fq) const {
;     const int row0 = u.pm * BM + wr * 64 + fr, col0 = u.pn * HALF + wc * 32 + 4 * fq;
; #pragma unroll
;     for (int ai = 0; ai < 2; ++ai)
; #pragma unroll
;       for (int m = 0; m < 4; ++m) {
;         u16* rowp = O + (size_t)(row0 + ai * HALF + m * 16) * FFN + col0;
; #pragma unroll
;         for (int n = 0; n < 2; ++n) {
;           f32x4 g = acc[ai][0][m][n], up = acc[ai][1][m][n];
;           uint2 w;
;           w.x = pk_bf16(siluf_(g[0]) * up[0], siluf_(g[1]) * up[1]);
;           w.y = pk_bf16(siluf_(g[2]) * up[2], siluf_(g[3]) * up[3]);
;           *reinterpret_cast<uint2*>(rowp + n * 16) = w;
;         }
;       }
;   }
	v_mul_f32_e32 v115, v110, v118
	v_lshl_add_u64 v[112:113], v[112:113], 0, v[142:143]
	v_mov_b32_e32 v118, v104
	v_mov_b32_e32 v119, v106
	v_rcp_f32_e32 v110, v114
	s_nop 0
	v_mul_f32_e32 v114, v108, v110
	v_pk_mul_f32 v[114:115], v[114:115], v[118:119]
	v_rcp_f32_e32 v104, v117
	s_nop 0
	v_mul_f32_e32 v111, v111, v104
	s_nop 0
	v_rcp_f32_e32 v104, v116
	s_nop 0
	v_mul_f32_e32 v110, v109, v104
	v_mov_b32_e32 v106, v105
	v_pk_mul_f32 v[104:105], v[110:111], v[106:107]
	s_nop 0
	v_cvt_pk_bf16_f32 v105, v115, v105
	v_cvt_pk_bf16_f32 v104, v114, v104
	global_store_dwordx2 v[112:113], v[104:105], off
	v_mul_f32_e32 v105, 0xbfb8aa3b, v101
	v_mul_f32_e32 v104, 0xbfb8aa3b, v100
	v_exp_f32_e32 v106, v105
	v_mul_f32_e32 v105, 0xbfb8aa3b, v102
	v_exp_f32_e32 v104, v104
	v_exp_f32_e32 v105, v105
	v_mul_f32_e32 v107, 0xbfb8aa3b, v103
	v_exp_f32_e32 v107, v107
	v_pk_add_f32 v[104:105], v[104:105], 1.0 op_sel_hi:[1,0]
	s_nop 0
	v_pk_add_f32 v[106:107], v[106:107], 1.0 op_sel_hi:[1,0]
	v_rcp_f32_e32 v108, v105
	s_nop 0
	v_mul_f32_e32 v105, v102, v108
	s_nop 0
	v_mov_b32_e32 v108, v96
	v_mov_b32_e32 v109, v98
	v_rcp_f32_e32 v102, v104
	s_nop 0
	v_mul_f32_e32 v104, v100, v102
	v_pk_mul_f32 v[104:105], v[104:105], v[108:109]
	v_rcp_f32_e32 v96, v107
	s_nop 0
	v_mul_f32_e32 v103, v103, v96
	s_nop 0
	v_rcp_f32_e32 v96, v106
	s_nop 0
	v_mul_f32_e32 v102, v101, v96
	v_mov_b32_e32 v98, v97
	v_pk_mul_f32 v[96:97], v[102:103], v[98:99]
	s_nop 0
	v_cvt_pk_bf16_f32 v96, v104, v96
	v_mul_f32_e32 v99, 0xbfb8aa3b, v93
	v_cvt_pk_bf16_f32 v97, v105, v97
	v_mul_f32_e32 v98, 0xbfb8aa3b, v92
	v_exp_f32_e32 v100, v99
	v_mul_f32_e32 v99, 0xbfb8aa3b, v94
	v_exp_f32_e32 v98, v98
	v_exp_f32_e32 v99, v99
	v_mul_f32_e32 v101, 0xbfb8aa3b, v95
	v_exp_f32_e32 v101, v101
	global_store_dwordx2 v[112:113], v[96:97], off offset:32
	v_pk_add_f32 v[98:99], v[98:99], 1.0 op_sel_hi:[1,0]
	v_or_b32_e32 v96, 32, v150
	v_pk_add_f32 v[100:101], v[100:101], 1.0 op_sel_hi:[1,0]
	v_mad_i64_i32 v[96:97], s[22:23], v96, s2, v[140:141]
	v_rcp_f32_e32 v102, v99
	s_nop 0
	v_mul_f32_e32 v99, v94, v102
	v_lshl_add_u64 v[96:97], v[96:97], 0, v[142:143]
	v_mov_b32_e32 v102, v88
	v_mov_b32_e32 v103, v90
	v_rcp_f32_e32 v94, v98
	s_nop 0
	v_mul_f32_e32 v98, v92, v94
	v_pk_mul_f32 v[98:99], v[98:99], v[102:103]
	v_rcp_f32_e32 v88, v101
	s_nop 0
	v_mul_f32_e32 v95, v95, v88
	s_nop 0
	v_rcp_f32_e32 v88, v100
	s_nop 0
	v_mul_f32_e32 v94, v93, v88
	v_mov_b32_e32 v90, v89
	v_pk_mul_f32 v[88:89], v[94:95], v[90:91]
	s_nop 0
	v_cvt_pk_bf16_f32 v89, v99, v89
	v_cvt_pk_bf16_f32 v88, v98, v88
	global_store_dwordx2 v[96:97], v[88:89], off
	v_mul_f32_e32 v89, 0xbfb8aa3b, v85
	v_mul_f32_e32 v88, 0xbfb8aa3b, v84
	v_exp_f32_e32 v90, v89
	v_mul_f32_e32 v89, 0xbfb8aa3b, v86
	v_exp_f32_e32 v88, v88
	v_exp_f32_e32 v89, v89
	v_mul_f32_e32 v91, 0xbfb8aa3b, v87
	v_exp_f32_e32 v91, v91
	v_pk_add_f32 v[88:89], v[88:89], 1.0 op_sel_hi:[1,0]
	s_nop 0
	v_pk_add_f32 v[90:91], v[90:91], 1.0 op_sel_hi:[1,0]
	v_rcp_f32_e32 v92, v89
	s_nop 0
	v_mul_f32_e32 v89, v86, v92
	s_nop 0
	v_mov_b32_e32 v92, v80
	v_mov_b32_e32 v93, v82
	v_rcp_f32_e32 v86, v88
	s_nop 0
	v_mul_f32_e32 v88, v84, v86
	v_pk_mul_f32 v[88:89], v[88:89], v[92:93]
	v_rcp_f32_e32 v80, v91
	s_nop 0
	v_mul_f32_e32 v87, v87, v80
	s_nop 0
	v_rcp_f32_e32 v80, v90
	s_nop 0
	v_mul_f32_e32 v86, v85, v80
	v_mov_b32_e32 v82, v81
	v_pk_mul_f32 v[80:81], v[86:87], v[82:83]
	s_nop 0
	v_cvt_pk_bf16_f32 v80, v88, v80
	v_mul_f32_e32 v83, 0xbfb8aa3b, v77
	v_cvt_pk_bf16_f32 v81, v89, v81
	v_mul_f32_e32 v82, 0xbfb8aa3b, v76
	v_exp_f32_e32 v84, v83
	v_mul_f32_e32 v83, 0xbfb8aa3b, v78
	v_exp_f32_e32 v82, v82
	v_exp_f32_e32 v83, v83
	v_mul_f32_e32 v85, 0xbfb8aa3b, v79
	v_exp_f32_e32 v85, v85
	global_store_dwordx2 v[96:97], v[80:81], off offset:32
	v_pk_add_f32 v[82:83], v[82:83], 1.0 op_sel_hi:[1,0]
	v_or_b32_e32 v80, 48, v150
	v_pk_add_f32 v[84:85], v[84:85], 1.0 op_sel_hi:[1,0]
	v_mad_i64_i32 v[80:81], s[22:23], v80, s2, v[140:141]
	v_rcp_f32_e32 v86, v83
	s_nop 0
	v_mul_f32_e32 v83, v78, v86
	v_lshl_add_u64 v[80:81], v[80:81], 0, v[142:143]
	v_mov_b32_e32 v86, v72
	v_mov_b32_e32 v87, v74
	v_rcp_f32_e32 v78, v82
	s_nop 0
	v_mul_f32_e32 v82, v76, v78
	v_pk_mul_f32 v[82:83], v[82:83], v[86:87]
	v_rcp_f32_e32 v72, v85
	s_nop 0
	v_mul_f32_e32 v79, v79, v72
	s_nop 0
	v_rcp_f32_e32 v72, v84
	s_nop 0
	v_mul_f32_e32 v78, v77, v72
	v_mov_b32_e32 v74, v73
	v_pk_mul_f32 v[72:73], v[78:79], v[74:75]
	s_nop 0
	v_cvt_pk_bf16_f32 v73, v83, v73
	v_cvt_pk_bf16_f32 v72, v82, v72
	global_store_dwordx2 v[80:81], v[72:73], off
	v_mul_f32_e32 v73, 0xbfb8aa3b, v69
	v_mul_f32_e32 v72, 0xbfb8aa3b, v68
	v_exp_f32_e32 v74, v73
	v_mul_f32_e32 v73, 0xbfb8aa3b, v70
	v_exp_f32_e32 v72, v72
	v_exp_f32_e32 v73, v73
	v_mul_f32_e32 v75, 0xbfb8aa3b, v71
	v_exp_f32_e32 v75, v75
	v_pk_add_f32 v[72:73], v[72:73], 1.0 op_sel_hi:[1,0]
	s_nop 0
	v_pk_add_f32 v[74:75], v[74:75], 1.0 op_sel_hi:[1,0]
	v_rcp_f32_e32 v76, v73
	s_nop 0
	v_mul_f32_e32 v73, v70, v76
	s_nop 0
	v_mov_b32_e32 v76, v64
	v_mov_b32_e32 v77, v66
	v_rcp_f32_e32 v70, v72
	s_nop 0
	v_mul_f32_e32 v72, v68, v70
	v_pk_mul_f32 v[72:73], v[72:73], v[76:77]
	v_rcp_f32_e32 v64, v75
	s_nop 0
	v_mul_f32_e32 v71, v71, v64
	s_nop 0
	v_rcp_f32_e32 v64, v74
	s_nop 0
	v_mul_f32_e32 v70, v69, v64
	v_mov_b32_e32 v66, v65
	v_pk_mul_f32 v[64:65], v[70:71], v[66:67]
	s_nop 0
	v_cvt_pk_bf16_f32 v64, v72, v64
	v_mul_f32_e32 v67, 0xbfb8aa3b, v61
	v_cvt_pk_bf16_f32 v65, v73, v65
	v_mul_f32_e32 v66, 0xbfb8aa3b, v60
	v_exp_f32_e32 v68, v67
	v_mul_f32_e32 v67, 0xbfb8aa3b, v62
	v_exp_f32_e32 v66, v66
	v_exp_f32_e32 v67, v67
	v_mul_f32_e32 v69, 0xbfb8aa3b, v63
	v_exp_f32_e32 v69, v69
; __device__ __forceinline__ float siluf_(float x) { return x / (1.f + __expf(-x)); }
; __device__ __forceinline__ unsigned pk_bf16(float lo, float hi) { return (unsigned)f2bf(lo) | ((unsigned)f2bf(hi) << 16); }
;   __device__ __forceinline__ void operator()(const f32x4 (&acc)[2][2][4][2], const Unit& u, int wr, int wc, int fr, int fq) const {
;     const int row0 = u.pm * BM + wr * 64 + fr, col0 = u.pn * HALF + wc * 32 + 4 * fq;
; #pragma unroll
;     for (int ai = 0; ai < 2; ++ai)
; #pragma unroll
;       for (int m = 0; m < 4; ++m) {
;         u16* rowp = O + (size_t)(row0 + ai * HALF + m * 16) * FFN + col0;
; #pragma unroll
;         for (int n = 0; n < 2; ++n) {
;           f32x4 g = acc[ai][0][m][n], up = acc[ai][1][m][n];
;           uint2 w;
;           w.x = pk_bf16(siluf_(g[0]) * up[0], siluf_(g[1]) * up[1]);
;           w.y = pk_bf16(siluf_(g[2]) * up[2], siluf_(g[3]) * up[3]);
;           *reinterpret_cast<uint2*>(rowp + n * 16) = w;
;         }
;       }
;   }
	global_store_dwordx2 v[80:81], v[64:65], off offset:32
	v_pk_add_f32 v[66:67], v[66:67], 1.0 op_sel_hi:[1,0]
	v_add_u32_e32 v64, 0x80, v150
	v_pk_add_f32 v[68:69], v[68:69], 1.0 op_sel_hi:[1,0]
	v_mad_i64_i32 v[64:65], s[22:23], v64, s2, v[140:141]
	v_rcp_f32_e32 v70, v67
	s_nop 0
	v_mul_f32_e32 v67, v62, v70
	v_lshl_add_u64 v[64:65], v[64:65], 0, v[142:143]
	v_mov_b32_e32 v70, v56
	v_mov_b32_e32 v71, v58
	v_rcp_f32_e32 v62, v66
	s_nop 0
	v_mul_f32_e32 v66, v60, v62
	v_pk_mul_f32 v[66:67], v[66:67], v[70:71]
	v_rcp_f32_e32 v56, v69
	s_nop 0
	v_mul_f32_e32 v63, v63, v56
	s_nop 0
	v_rcp_f32_e32 v56, v68
	s_nop 0
	v_mul_f32_e32 v62, v61, v56
	v_mov_b32_e32 v58, v57
	v_pk_mul_f32 v[56:57], v[62:63], v[58:59]
	s_nop 0
	v_cvt_pk_bf16_f32 v57, v67, v57
	v_cvt_pk_bf16_f32 v56, v66, v56
	global_store_dwordx2 v[64:65], v[56:57], off
	v_mul_f32_e32 v57, 0xbfb8aa3b, v53
	v_mul_f32_e32 v56, 0xbfb8aa3b, v52
	v_exp_f32_e32 v58, v57
	v_mul_f32_e32 v57, 0xbfb8aa3b, v54
	v_exp_f32_e32 v56, v56
	v_exp_f32_e32 v57, v57
	v_mul_f32_e32 v59, 0xbfb8aa3b, v55
	v_exp_f32_e32 v59, v59
	v_pk_add_f32 v[56:57], v[56:57], 1.0 op_sel_hi:[1,0]
	s_nop 0
	v_pk_add_f32 v[58:59], v[58:59], 1.0 op_sel_hi:[1,0]
	v_rcp_f32_e32 v60, v57
	s_nop 0
	v_mul_f32_e32 v57, v54, v60
	s_nop 0
	v_mov_b32_e32 v60, v48
	v_mov_b32_e32 v61, v50
	v_rcp_f32_e32 v54, v56
	s_nop 0
	v_mul_f32_e32 v56, v52, v54
	v_pk_mul_f32 v[56:57], v[56:57], v[60:61]
	v_rcp_f32_e32 v48, v59
	s_nop 0
	v_mul_f32_e32 v55, v55, v48
	s_nop 0
	v_rcp_f32_e32 v48, v58
	s_nop 0
	v_mul_f32_e32 v54, v53, v48
	v_mov_b32_e32 v50, v49
	v_pk_mul_f32 v[48:49], v[54:55], v[50:51]
	s_nop 0
	v_cvt_pk_bf16_f32 v48, v56, v48
	v_mul_f32_e32 v51, 0xbfb8aa3b, v45
	v_cvt_pk_bf16_f32 v49, v57, v49
	v_mul_f32_e32 v50, 0xbfb8aa3b, v44
	v_exp_f32_e32 v52, v51
	v_mul_f32_e32 v51, 0xbfb8aa3b, v46
	v_exp_f32_e32 v50, v50
	v_exp_f32_e32 v51, v51
	v_mul_f32_e32 v53, 0xbfb8aa3b, v47
	v_exp_f32_e32 v53, v53
	global_store_dwordx2 v[64:65], v[48:49], off offset:32
	v_pk_add_f32 v[50:51], v[50:51], 1.0 op_sel_hi:[1,0]
	v_add_u32_e32 v48, 0x90, v150
	v_pk_add_f32 v[52:53], v[52:53], 1.0 op_sel_hi:[1,0]
	v_mad_i64_i32 v[48:49], s[22:23], v48, s2, v[140:141]
	v_rcp_f32_e32 v54, v51
	s_nop 0
	v_mul_f32_e32 v51, v46, v54
	v_lshl_add_u64 v[48:49], v[48:49], 0, v[142:143]
	v_mov_b32_e32 v54, v40
	v_mov_b32_e32 v55, v42
	v_rcp_f32_e32 v46, v50
	s_nop 0
	v_mul_f32_e32 v50, v44, v46
	v_pk_mul_f32 v[50:51], v[50:51], v[54:55]
	v_rcp_f32_e32 v40, v53
	s_nop 0
	v_mul_f32_e32 v47, v47, v40
	s_nop 0
	v_rcp_f32_e32 v40, v52
	s_nop 0
	v_mul_f32_e32 v46, v45, v40
	v_mov_b32_e32 v42, v41
	v_pk_mul_f32 v[40:41], v[46:47], v[42:43]
	s_nop 0
	v_cvt_pk_bf16_f32 v41, v51, v41
	v_cvt_pk_bf16_f32 v40, v50, v40
	global_store_dwordx2 v[48:49], v[40:41], off
	v_mul_f32_e32 v41, 0xbfb8aa3b, v37
	v_mul_f32_e32 v40, 0xbfb8aa3b, v36
	v_exp_f32_e32 v42, v41
	v_mul_f32_e32 v41, 0xbfb8aa3b, v38
	v_exp_f32_e32 v40, v40
	v_exp_f32_e32 v41, v41
	v_mul_f32_e32 v43, 0xbfb8aa3b, v39
	v_exp_f32_e32 v43, v43
	v_pk_add_f32 v[40:41], v[40:41], 1.0 op_sel_hi:[1,0]
	s_nop 0
	v_pk_add_f32 v[42:43], v[42:43], 1.0 op_sel_hi:[1,0]
	v_rcp_f32_e32 v44, v41
	s_nop 0
	v_mul_f32_e32 v41, v38, v44
	s_nop 0
	v_mov_b32_e32 v44, v32
	v_mov_b32_e32 v45, v34
	v_rcp_f32_e32 v38, v40
	s_nop 0
	v_mul_f32_e32 v40, v36, v38
	v_pk_mul_f32 v[40:41], v[40:41], v[44:45]
	v_rcp_f32_e32 v32, v43
	s_nop 0
	v_mul_f32_e32 v39, v39, v32
	s_nop 0
	v_rcp_f32_e32 v32, v42
	s_nop 0
	v_mul_f32_e32 v38, v37, v32
	v_mov_b32_e32 v34, v33
	v_pk_mul_f32 v[32:33], v[38:39], v[34:35]
	s_nop 0
	v_cvt_pk_bf16_f32 v32, v40, v32
	v_mul_f32_e32 v35, 0xbfb8aa3b, v29
	v_cvt_pk_bf16_f32 v33, v41, v33
	v_mul_f32_e32 v34, 0xbfb8aa3b, v28
	v_exp_f32_e32 v36, v35
	v_mul_f32_e32 v35, 0xbfb8aa3b, v30
	v_exp_f32_e32 v34, v34
	v_exp_f32_e32 v35, v35
; __device__ __forceinline__ float siluf_(float x) { return x / (1.f + __expf(-x)); }
; __device__ __forceinline__ unsigned pk_bf16(float lo, float hi) { return (unsigned)f2bf(lo) | ((unsigned)f2bf(hi) << 16); }
; #define G_WAIT_V(n) asm volatile("s_waitcnt vmcnt(" #n ")" ::: "memory")
; #define G_BAR __builtin_amdgcn_s_barrier()
;   __device__ __forceinline__ void operator()(const f32x4 (&acc)[2][2][4][2], const Unit& u, int wr, int wc, int fr, int fq) const {
;     const int row0 = u.pm * BM + wr * 64 + fr, col0 = u.pn * HALF + wc * 32 + 4 * fq;
; #pragma unroll
;     for (int ai = 0; ai < 2; ++ai)
; #pragma unroll
;       for (int m = 0; m < 4; ++m) {
;         u16* rowp = O + (size_t)(row0 + ai * HALF + m * 16) * FFN + col0;
; #pragma unroll
;         for (int n = 0; n < 2; ++n) {
;           f32x4 g = acc[ai][0][m][n], up = acc[ai][1][m][n];
;           uint2 w;
;           w.x = pk_bf16(siluf_(g[0]) * up[0], siluf_(g[1]) * up[1]);
;           w.y = pk_bf16(siluf_(g[2]) * up[2], siluf_(g[3]) * up[3]);
;           *reinterpret_cast<uint2*>(rowp + n * 16) = w;
;         }
;       }
;   }
; template <class Epi>
; __device__ __forceinline__ void gemm_phase(LAS unsigned char* lds, const u16* gA, const u16* gBt, int M, int N, int K, const Epi& E) {
;     ...
;     E(acc, cur, wr, wc, fr, fq);
;     if (!has_next) break;
; #pragma unroll
;     for (int a = 0; a < 2; ++a)
; #pragma unroll
;       for (int b = 0; b < 2; ++b)
; #pragma unroll
;         for (int m = 0; m < 4; ++m)
; #pragma unroll
;           for (int n = 0; n < 2; ++n) acc[a][b][m][n] = (f32x4){0.f, 0.f, 0.f, 0.f};
;     cur = nxt; cA = nA; cB = nB; ++ui;
;   }
;   G_WAIT_V(0);
;   if (wr == 0) G_BAR;
;   G_BAR;
	v_mul_f32_e32 v37, 0xbfb8aa3b, v31
	v_exp_f32_e32 v37, v37
	global_store_dwordx2 v[48:49], v[32:33], off offset:32
	v_pk_add_f32 v[34:35], v[34:35], 1.0 op_sel_hi:[1,0]
	v_add_u32_e32 v32, 0xa0, v150
	v_pk_add_f32 v[36:37], v[36:37], 1.0 op_sel_hi:[1,0]
	v_mad_i64_i32 v[32:33], s[22:23], v32, s2, v[140:141]
	v_rcp_f32_e32 v38, v35
	s_nop 0
	v_mul_f32_e32 v35, v30, v38
	v_lshl_add_u64 v[32:33], v[32:33], 0, v[142:143]
	v_mov_b32_e32 v38, v24
	v_mov_b32_e32 v39, v26
	v_rcp_f32_e32 v30, v34
	s_nop 0
	v_mul_f32_e32 v34, v28, v30
	v_pk_mul_f32 v[34:35], v[34:35], v[38:39]
	v_rcp_f32_e32 v24, v37
	s_nop 0
	v_mul_f32_e32 v31, v31, v24
	s_nop 0
	v_rcp_f32_e32 v24, v36
	s_nop 0
	v_mul_f32_e32 v30, v29, v24
	v_mov_b32_e32 v26, v25
	v_pk_mul_f32 v[24:25], v[30:31], v[26:27]
	s_nop 0
	v_cvt_pk_bf16_f32 v25, v35, v25
	v_cvt_pk_bf16_f32 v24, v34, v24
	global_store_dwordx2 v[32:33], v[24:25], off
	v_mul_f32_e32 v25, 0xbfb8aa3b, v21
	v_mul_f32_e32 v24, 0xbfb8aa3b, v20
	v_exp_f32_e32 v26, v25
	v_mul_f32_e32 v25, 0xbfb8aa3b, v22
	v_exp_f32_e32 v24, v24
	v_exp_f32_e32 v25, v25
	v_mul_f32_e32 v27, 0xbfb8aa3b, v23
	v_exp_f32_e32 v27, v27
	v_pk_add_f32 v[24:25], v[24:25], 1.0 op_sel_hi:[1,0]
	s_nop 0
	v_pk_add_f32 v[26:27], v[26:27], 1.0 op_sel_hi:[1,0]
	v_rcp_f32_e32 v28, v25
	s_nop 0
	v_mul_f32_e32 v25, v22, v28
	s_nop 0
	v_mov_b32_e32 v28, v16
	v_mov_b32_e32 v29, v18
	v_rcp_f32_e32 v22, v24
	s_nop 0
	v_mul_f32_e32 v24, v20, v22
	v_pk_mul_f32 v[24:25], v[24:25], v[28:29]
	v_rcp_f32_e32 v16, v27
	s_nop 0
	v_mul_f32_e32 v23, v23, v16
	s_nop 0
	v_rcp_f32_e32 v16, v26
	s_nop 0
	v_mul_f32_e32 v22, v21, v16
	v_mov_b32_e32 v18, v17
	v_pk_mul_f32 v[16:17], v[22:23], v[18:19]
	s_nop 0
	v_cvt_pk_bf16_f32 v16, v24, v16
	v_mul_f32_e32 v19, 0xbfb8aa3b, v13
	v_cvt_pk_bf16_f32 v17, v25, v17
	v_mul_f32_e32 v18, 0xbfb8aa3b, v12
	v_exp_f32_e32 v20, v19
	v_mul_f32_e32 v19, 0xbfb8aa3b, v14
	v_exp_f32_e32 v18, v18
	v_exp_f32_e32 v19, v19
	v_mul_f32_e32 v21, 0xbfb8aa3b, v15
	v_exp_f32_e32 v21, v21
	global_store_dwordx2 v[32:33], v[16:17], off offset:32
	v_pk_add_f32 v[18:19], v[18:19], 1.0 op_sel_hi:[1,0]
	v_add_u32_e32 v16, 0xb0, v150
	v_pk_add_f32 v[20:21], v[20:21], 1.0 op_sel_hi:[1,0]
	v_mad_i64_i32 v[16:17], s[22:23], v16, s2, v[140:141]
	v_rcp_f32_e32 v22, v19
	s_nop 0
	v_mul_f32_e32 v19, v14, v22
	v_lshl_add_u64 v[16:17], v[16:17], 0, v[142:143]
	s_mov_b32 s2, s44
	v_mov_b32_e32 v22, v8
	v_mov_b32_e32 v23, v10
	v_rcp_f32_e32 v14, v18
	s_nop 0
	v_mul_f32_e32 v18, v12, v14
	v_pk_mul_f32 v[18:19], v[18:19], v[22:23]
	v_rcp_f32_e32 v8, v21
	s_nop 0
	v_mul_f32_e32 v15, v15, v8
	s_nop 0
	v_rcp_f32_e32 v8, v20
	s_nop 0
	v_mul_f32_e32 v14, v13, v8
	v_mov_b32_e32 v10, v9
	v_pk_mul_f32 v[8:9], v[14:15], v[10:11]
	s_nop 0
	v_cvt_pk_bf16_f32 v9, v19, v9
	v_cvt_pk_bf16_f32 v8, v18, v8
	global_store_dwordx2 v[16:17], v[8:9], off
	v_mul_f32_e32 v9, 0xbfb8aa3b, v5
	v_mul_f32_e32 v8, 0xbfb8aa3b, v4
	v_exp_f32_e32 v10, v9
	v_mul_f32_e32 v9, 0xbfb8aa3b, v6
	v_exp_f32_e32 v8, v8
	v_exp_f32_e32 v9, v9
	v_mul_f32_e32 v11, 0xbfb8aa3b, v7
	v_exp_f32_e32 v11, v11
	v_pk_add_f32 v[8:9], v[8:9], 1.0 op_sel_hi:[1,0]
	s_nop 0
	v_pk_add_f32 v[10:11], v[10:11], 1.0 op_sel_hi:[1,0]
	v_rcp_f32_e32 v12, v9
	s_nop 0
	v_mul_f32_e32 v9, v6, v12
	s_nop 0
	v_mov_b32_e32 v12, v0
	v_mov_b32_e32 v13, v2
	v_rcp_f32_e32 v6, v8
	s_nop 0
	v_mul_f32_e32 v8, v4, v6
	v_pk_mul_f32 v[8:9], v[8:9], v[12:13]
	v_rcp_f32_e32 v0, v11
	s_nop 0
	v_mul_f32_e32 v7, v7, v0
	s_mov_b32 s23, s40
	v_rcp_f32_e32 v0, v10
	s_nop 0
	v_mul_f32_e32 v6, v5, v0
	v_mov_b32_e32 v2, v1
	v_pk_mul_f32 v[0:1], v[6:7], v[2:3]
	s_nop 0
	v_cvt_pk_bf16_f32 v1, v9, v1
	v_cvt_pk_bf16_f32 v0, v8, v0
	s_and_b64 vcc, exec, s[38:39]
	global_store_dwordx2 v[16:17], v[0:1], off offset:32
	s_cbranch_vccz .LBB0_53
	s_waitcnt vmcnt(0)
	s_cmpk_gt_u32 s63, 0xff
	s_cbranch_scc1 .LBB0_60
	s_barrier

; __device__ void phase_combine(const P& p, int l, int ntok, float* lds) {
;     ...
;     for (int i0 = 0; i0 < 16; i0 += 4) {
;       float sf[4], sb[4];
;       unsigned y0[4], y1[4], a0[4], a1[4], a2[4], a3[4], vc[4], vp[4], vn[4], g0r[4], g1r[4], cbr[4], ucc[6], uch[6];
; #pragma unroll
;       for (int i = 0; i < 4; ++i) {
;         int row = r0 + i0 + i, t = tb + i0 + i;
;         y0[i] = or0[(size_t)row * 512 + tid]; y1[i] = or1[(size_t)row * 512 + tid];
;         const u16* pv = p.projb + (size_t)row * PROJP + O_RKV + 1024 + tid;
;         vc[i] = pv[0]; vp[i] = pv[t > 0 ? -PROJP : 0]; vn[i] = pv[t < T - 1 ? PROJP : 0];
;         sf[i] = p.sbon[(size_t)row * 8 + wv]; sb[i] = p.sbon[(size_t)NT * 8 + (size_t)row * 8 + wv];
;         size_t ob = (size_t)row * 512 + hh * 128 + lane;
;         a0[i] = om0[ob]; a1[i] = om1[ob]; a2[i] = om0[ob + 64]; a3[i] = om1[ob + 64];
;         const u16* pg = p.projb + (size_t)row * PROJP + gch;
;         g0r[i] = pg[0]; g1r[i] = pg[64];
;         cbr[i] = p.projb[(size_t)row * PROJP + O_CB + tid];
;       }
;       {
;         const u16* pc = p.projb + (size_t)(r0 + i0) * PROJP;
; #pragma unroll
;         for (int j = 0; j < 6; ++j) {
;           int t = tb + i0 + j - 1;
;           int off = (t < 0 ? 0 : (t > T - 1 ? T - 1 : t)) - (tb + i0);
;           const u16* pr = pc + (long)off * PROJP;
;           ucc[j] = pr[O_CC + tid]; uch[j] = pr[O_CH + tid];
;         }
;       }
.LBB0_94:
	s_or_b32 s46, s60, s56
	s_ashr_i32 s47, s46, 31
	s_lshl_b64 s[0:1], s[46:47], 9
	s_or_b32 s2, s60, s59
	v_lshl_add_u64 v[0:1], s[0:1], 0, v[4:5]
	s_mul_i32 s20, s46, 0x3600
	v_lshlrev_b64 v[0:1], 1, v[0:1]
	s_mul_hi_i32 s3, s46, 0x3600
	s_add_u32 s22, s94, s20
	v_lshl_add_u64 v[2:3], s[34:35], 0, v[0:1]
	v_lshl_add_u64 v[0:1], s[62:63], 0, v[0:1]
	s_addc_u32 s23, s95, s3
	v_lshlrev_b64 v[22:23], 1, v[4:5]
	v_sub_co_u32_e64 v139, s[52:53], s2, 1
	global_load_ushort v201, v[2:3], off
	global_load_ushort v202, v[0:1], off
	v_lshl_add_u64 v[0:1], s[22:23], 0, v[22:23]
	s_and_b64 s[24:25], s[52:53], exec
	v_add_co_u32_e32 v18, vcc, s75, v0
	s_cselect_b32 s25, 0, -1
	s_cselect_b32 s24, 0, 0xffffca00
	s_cmp_lt_u32 s2, s57
	v_lshl_add_u64 v[2:3], v[0:1], 0, s[68:69]
	v_addc_co_u32_e32 v19, vcc, 0, v1, vcc
	s_cselect_b64 s[44:45], -1, 0
	global_load_ushort v199, v[18:19], off offset:64
	v_lshl_add_u64 v[18:19], v[2:3], 0, s[24:25]
	s_and_b64 s[24:25], s[44:45], exec
	s_cselect_b32 s28, 0x3600, 0
	v_lshl_add_u64 v[2:3], v[2:3], 0, s[28:29]
	s_lshl_b64 s[24:25], s[46:47], 5
	global_load_ushort v208, v[18:19], off
	global_load_ushort v210, v[2:3], off
	s_add_u32 s24, s10, s24
	v_mov_b32_e32 v19, s1
	v_or_b32_e32 v18, s0, v10
	s_addc_u32 s25, s11, s25
	v_lshlrev_b64 v[18:19], 1, v[18:19]
	s_or_b32 s50, s46, 1
	v_lshl_add_u64 v[20:21], v[6:7], 0, v[18:19]
	v_lshl_add_u64 v[18:19], v[8:9], 0, v[18:19]
	s_ashr_i32 s51, s50, 31
	global_load_ushort v195, v[20:21], off
	global_load_ushort v193, v[18:19], off
	global_load_ushort v196, v[20:21], off offset:128
	global_load_ushort v194, v[18:19], off offset:128
	global_load_ushort v192, v134, s[22:23]
	global_load_ushort v191, v134, s[22:23] offset:128
	v_add_co_u32_e32 v18, vcc, s96, v0
	s_or_b32 s3, s2, 1
	s_lshl_b64 s[0:1], s[50:51], 9
	s_mul_i32 s22, s50, 0x3600
	v_addc_co_u32_e32 v19, vcc, 0, v1, vcc
	s_mul_hi_i32 s20, s50, 0x3600
	s_add_u32 s22, s94, s22
	global_load_ushort v138, v[18:19], off offset:3136
	v_lshl_add_u64 v[18:19], s[0:1], 0, v[4:5]
	s_addc_u32 s23, s95, s20
	v_lshlrev_b64 v[18:19], 1, v[18:19]
	s_cmp_lt_u32 s3, s57
	v_lshl_add_u64 v[20:21], s[34:35], 0, v[18:19]
	v_lshl_add_u64 v[18:19], s[62:63], 0, v[18:19]
	s_cselect_b64 s[42:43], -1, 0
	v_lshl_add_u64 v[2:3], s[24:25], 0, v[16:17]
	global_load_ushort v212, v[20:21], off
	global_load_ushort v213, v[18:19], off
	v_lshl_add_u64 v[20:21], s[22:23], 0, v[22:23]
	s_and_b64 s[24:25], s[42:43], exec
	v_lshl_add_u64 v[18:19], v[20:21], 0, s[68:69]
	v_add_co_u32_e32 v136, vcc, s75, v20
	s_cselect_b32 s28, 0x3600, 0
	s_nop 0
	v_addc_co_u32_e32 v137, vcc, 0, v21, vcc
	v_lshl_add_u64 v[18:19], v[18:19], 0, s[28:29]
	s_lshl_b64 s[24:25], s[50:51], 5
	global_load_ushort v198, v[136:137], off offset:64
	global_load_ushort v206, v[18:19], off
	s_add_u32 s24, s10, s24
	v_mov_b32_e32 v137, s1
	v_or_b32_e32 v136, s0, v10
	s_addc_u32 s25, s11, s25
	v_lshlrev_b64 v[136:137], 1, v[136:137]
	s_or_b32 s48, s46, 2
	v_lshl_add_u64 v[140:141], v[6:7], 0, v[136:137]
	v_lshl_add_u64 v[136:137], v[8:9], 0, v[136:137]
	s_ashr_i32 s49, s48, 31
	global_load_ushort v167, v[140:141], off
	global_load_ushort v165, v[136:137], off
	global_load_ushort v190, v[140:141], off offset:128
	global_load_ushort v166, v[136:137], off offset:128
	global_load_ushort v164, v134, s[22:23]
	global_load_ushort v163, v134, s[22:23] offset:128
	v_add_co_u32_e32 v20, vcc, s96, v20
	s_or_b32 s23, s2, 2
	s_lshl_b64 s[0:1], s[48:49], 9
	s_mul_i32 s22, s48, 0x3600
	v_lshl_add_u64 v[18:19], s[24:25], 0, v[16:17]
	v_addc_co_u32_e32 v21, vcc, 0, v21, vcc
	s_mul_hi_i32 s20, s48, 0x3600
	s_add_u32 s24, s94, s22
	global_load_ushort v137, v[20:21], off offset:3136
	v_lshl_add_u64 v[20:21], s[0:1], 0, v[4:5]
	s_addc_u32 s25, s95, s20
	v_lshlrev_b64 v[20:21], 1, v[20:21]
	s_cmp_lt_u32 s23, s57
	v_lshl_add_u64 v[140:141], s[34:35], 0, v[20:21]
	v_lshl_add_u64 v[20:21], s[62:63], 0, v[20:21]
	s_cselect_b64 s[40:41], -1, 0
	global_load_ushort v209, v[140:141], off
	global_load_ushort v211, v[20:21], off
	v_lshl_add_u64 v[140:141], s[24:25], 0, v[22:23]
	s_and_b64 s[26:27], s[40:41], exec
	v_lshl_add_u64 v[20:21], v[140:141], 0, s[68:69]
	v_add_co_u32_e32 v142, vcc, s75, v140
	s_cselect_b32 s28, 0x3600, 0
	s_lshl_b64 s[26:27], s[48:49], 5
	v_addc_co_u32_e32 v143, vcc, 0, v141, vcc
	v_lshl_add_u64 v[20:21], v[20:21], 0, s[28:29]
	s_add_u32 s26, s10, s26
	global_load_ushort v197, v[142:143], off offset:64
	global_load_ushort v204, v[20:21], off
	s_addc_u32 s27, s11, s27
	v_mov_b32_e32 v143, s1
	v_or_b32_e32 v142, s0, v10
	s_or_b32 s36, s46, 3
	v_lshlrev_b64 v[142:143], 1, v[142:143]
	v_add_co_u32_e32 v140, vcc, s96, v140
	s_ashr_i32 s37, s36, 31
	v_lshl_add_u64 v[144:145], v[6:7], 0, v[142:143]
	v_lshl_add_u64 v[142:143], v[8:9], 0, v[142:143]
	v_addc_co_u32_e32 v141, vcc, 0, v141, vcc
	s_lshl_b64 s[0:1], s[36:37], 9
	v_lshl_add_u64 v[20:21], s[26:27], 0, v[16:17]
	global_load_ushort v161, v[144:145], off
	global_load_ushort v159, v[142:143], off
	global_load_ushort v162, v[144:145], off offset:128
	global_load_ushort v160, v[142:143], off offset:128
	global_load_ushort v158, v134, s[24:25]
	global_load_ushort v157, v134, s[24:25] offset:128
	global_load_ushort v136, v[140:141], off offset:3136
	s_or_b32 s26, s2, 3
	v_lshl_add_u64 v[140:141], s[0:1], 0, v[4:5]
	s_mul_i32 s22, s36, 0x3600
	v_lshlrev_b64 v[140:141], 1, v[140:141]
	s_mul_hi_i32 s20, s36, 0x3600
	s_add_u32 s24, s94, s22
	v_lshl_add_u64 v[142:143], s[34:35], 0, v[140:141]
	v_lshl_add_u64 v[140:141], s[62:63], 0, v[140:141]
	s_addc_u32 s25, s95, s20
	global_load_ushort v205, v[142:143], off
	global_load_ushort v207, v[140:141], off
; #define PIN8(a, o) asm volatile("" : "+v"(a[o]), "+v"(a[o + 1]), "+v"(a[o + 2]), "+v"(a[o + 3]), "+v"(a[o + 4]), "+v"(a[o + 5]), "+v"(a[o + 6]), "+v"(a[o + 7]))
; #define PIN8(a) asm volatile("" : "+v"(a[0]), "+v"(a[1]), "+v"(a[2]), "+v"(a[3]))
; __device__ void phase_combine(const P& p, int l, int ntok, float* lds) {
;     ...
;       for (int i = 0; i < 4; ++i) {
;         int row = r0 + i0 + i, t = tb + i0 + i;
;         y0[i] = or0[(size_t)row * 512 + tid]; y1[i] = or1[(size_t)row * 512 + tid];
;         const u16* pv = p.projb + (size_t)row * PROJP + O_RKV + 1024 + tid;
;         vc[i] = pv[0]; vp[i] = pv[t > 0 ? -PROJP : 0]; vn[i] = pv[t < T - 1 ? PROJP : 0];
;         sf[i] = p.sbon[(size_t)row * 8 + wv]; sb[i] = p.sbon[(size_t)NT * 8 + (size_t)row * 8 + wv];
;         size_t ob = (size_t)row * 512 + hh * 128 + lane;
;         a0[i] = om0[ob]; a1[i] = om1[ob]; a2[i] = om0[ob + 64]; a3[i] = om1[ob + 64];
;         const u16* pg = p.projb + (size_t)row * PROJP + gch;
;         g0r[i] = pg[0]; g1r[i] = pg[64];
;         cbr[i] = p.projb[(size_t)row * PROJP + O_CB + tid];
;       }
;       {
;         const u16* pc = p.projb + (size_t)(r0 + i0) * PROJP;
; #pragma unroll
;         for (int j = 0; j < 6; ++j) {
;           int t = tb + i0 + j - 1;
;           int off = (t < 0 ? 0 : (t > T - 1 ? T - 1 : t)) - (tb + i0);
;           const u16* pr = pc + (long)off * PROJP;
;           ucc[j] = pr[O_CC + tid]; uch[j] = pr[O_CH + tid];
;         }
;       }
;       PIN8(y0); PIN8(y1); PIN8(sf); PIN8(sb); PIN8(a0); PIN8(a1); PIN8(a2); PIN8(a3);
;       PIN8(vc); PIN8(vp); PIN8(vn); PIN8(g0r); PIN8(g1r); PIN8(cbr); PIN8(ucc); PIN8(uch);
;       asm volatile("" : "+v"(ucc[4]), "+v"(ucc[5]), "+v"(uch[4]), "+v"(uch[5]));
;       {
;         float gate[4];
; #pragma unroll
;         for (int i = 0; i < 4; ++i) gate[i] = 0.f;
; #pragma unroll
;         for (int m = 0; m < 96; m += 4) {
; #pragma unroll
;           for (int i = 0; i < 4; ++i) {
;             float4 s = *reinterpret_cast<const float4*>(sig + (i0 + i) * 96 + m);
;             gate[i] += s.x * g2r[m] + s.y * g2r[m + 1] + s.z * g2r[m + 2] + s.w * g2r[m + 3];
;           }
;         }
	v_lshl_add_u64 v[140:141], s[24:25], 0, v[22:23]
	v_add_co_u32_e32 v142, vcc, s75, v140
	s_cmp_lt_u32 s26, s57
	s_nop 0
	v_addc_co_u32_e32 v143, vcc, 0, v141, vcc
	s_cselect_b64 vcc, -1, 0
	s_and_b64 s[30:31], vcc, exec
	v_lshl_add_u64 v[22:23], v[140:141], 0, s[68:69]
	s_cselect_b32 s28, 0x3600, 0
	v_lshl_add_u64 v[22:23], v[22:23], 0, s[28:29]
	global_load_ushort v200, v[142:143], off offset:64
	global_load_ushort v203, v[22:23], off
	v_mov_b32_e32 v143, s1
	v_or_b32_e32 v142, s0, v10
	v_min_i32_e32 v139, s57, v139
	v_lshlrev_b64 v[142:143], 1, v[142:143]
	v_add_co_u32_e64 v140, s[0:1], s96, v140
	v_cndmask_b32_e64 v139, v139, 0, s[52:53]
	v_lshl_add_u64 v[144:145], v[6:7], 0, v[142:143]
	v_lshl_add_u64 v[142:143], v[8:9], 0, v[142:143]
	v_addc_co_u32_e64 v141, s[0:1], 0, v141, s[0:1]
	v_subrev_u32_e32 v139, s2, v139
	global_load_ushort v155, v[144:145], off
	global_load_ushort v153, v[142:143], off
	global_load_ushort v156, v[144:145], off offset:128
	global_load_ushort v154, v[142:143], off offset:128
	global_load_ushort v152, v134, s[24:25]
	global_load_ushort v149, v134, s[24:25] offset:128
	global_load_ushort v135, v[140:141], off offset:3136
	v_mad_i64_i32 v[140:141], s[0:1], v139, s61, v[0:1]
	v_add_co_u32_e64 v140, s[0:1], s78, v140
	s_lshl_b64 s[30:31], s[36:37], 5
	s_nop 0
	v_addc_co_u32_e64 v141, s[0:1], 0, v141, s[0:1]
	global_load_ushort v139, v[140:141], off offset:64
	s_nop 0
	global_load_ushort v140, v[140:141], off offset:1088
	v_mov_b32_e32 v141, s57
	v_sub_u32_e64 v141, s2, v141 clamp
	v_sub_u32_e32 v141, 0, v141
	v_mad_i64_i32 v[142:143], s[0:1], v141, s61, v[0:1]
	v_add_co_u32_e64 v142, s[0:1], s78, v142
	s_add_u32 s30, s10, s30
	s_nop 0
	v_addc_co_u32_e64 v143, s[0:1], 0, v143, s[0:1]
	s_addc_u32 s31, s11, s31
	s_min_u32 s0, s3, s57
	s_sub_i32 s0, s0, s2
	global_load_ushort v147, v[142:143], off offset:64
	global_load_ushort v148, v[142:143], off offset:1088
	v_mad_i64_i32 v[142:143], s[0:1], s0, v179, v[0:1]
	v_add_co_u32_e64 v142, s[0:1], s78, v142
	v_lshl_add_u64 v[22:23], s[30:31], 0, v[16:17]
	s_nop 0
	v_addc_co_u32_e64 v143, s[0:1], 0, v143, s[0:1]
	s_min_u32 s0, s23, s57
	s_sub_i32 s0, s0, s2
	global_load_ushort v150, v[142:143], off offset:64
	global_load_ushort v151, v[142:143], off offset:1088
	v_mad_i64_i32 v[142:143], s[0:1], s0, v179, v[0:1]
	v_add_co_u32_e64 v142, s[0:1], s78, v142
	s_waitcnt vmcnt(25)
	v_mov_b32_e32 v216, v197
	v_addc_co_u32_e64 v143, s[0:1], 0, v143, s[0:1]
	s_min_u32 s0, s26, s57
	s_sub_i32 s0, s0, s2
	global_load_ushort v145, v[142:143], off offset:64
	global_load_ushort v146, v[142:143], off offset:1088
	v_mad_i64_i32 v[142:143], s[0:1], s0, v179, v[0:1]
	v_add_co_u32_e64 v214, s[0:1], s78, v142
	s_nop 1
	v_addc_co_u32_e64 v215, s[0:1], 0, v143, s[0:1]
	s_add_i32 s0, s2, 4
	s_min_u32 s0, s0, s57
	s_sub_i32 s0, s0, s2
	v_mad_i64_i32 v[0:1], s[0:1], s0, v179, v[0:1]
	v_add_co_u32_e64 v0, s[0:1], s78, v0
	global_load_ushort v143, v[214:215], off offset:64
	global_load_ushort v144, v[214:215], off offset:1088
	v_addc_co_u32_e64 v1, s[0:1], 0, v1, s[0:1]
	global_load_ushort v141, v[0:1], off offset:64
	global_load_ushort v142, v[0:1], off offset:1088
	global_load_dword v218, v[2:3], off
	global_load_dword v214, v[22:23], off
	global_load_dword v215, v[20:21], off
	global_load_dword v217, v[18:19], off
	v_add_co_u32_e64 v0, s[0:1], s66, v2
	s_lshl_b64 s[2:3], s[48:49], 12
	s_nop 0
	v_addc_co_u32_e64 v1, s[0:1], 0, v3, s[0:1]
	global_load_dword v219, v[0:1], off
	v_add_co_u32_e64 v0, s[0:1], s66, v22
	s_nop 1
	v_addc_co_u32_e64 v1, s[0:1], 0, v23, s[0:1]
	global_load_dword v22, v[0:1], off
	v_add_co_u32_e64 v0, s[0:1], s66, v20
	s_nop 1
	v_addc_co_u32_e64 v1, s[0:1], 0, v21, s[0:1]
	global_load_dword v23, v[0:1], off
	v_add_co_u32_e64 v0, s[0:1], s66, v18
	v_mov_b32_e32 v21, v198
	s_nop 0
	v_addc_co_u32_e64 v1, s[0:1], 0, v19, s[0:1]
	s_mul_i32 s0, s60, 0x180
	s_add_i32 s0, s0, 0
	global_load_dword v20, v[0:1], off
	v_mov_b32_e32 v18, v199
	v_mov_b32_e32 v19, s0
	s_waitcnt lgkmcnt(0)
	ds_read_b128 v[220:223], v19
	ds_read_b128 v[224:227], v19 offset:384
	ds_read_b128 v[228:231], v19 offset:768
	ds_read_b128 v[232:235], v19 offset:1152
	ds_read_b128 v[244:247], v19 offset:16
	ds_read_b128 v[248:251], v19 offset:400
	ds_read_b128 v[252:255], v19 offset:784
	ds_read_b128 v[0:3], v19 offset:1168
	s_waitcnt lgkmcnt(4)
	v_mul_f32_e32 v221, v91, v221
	v_mul_f32_e32 v225, v91, v225
	v_mul_f32_e32 v229, v91, v229
	v_mul_f32_e32 v233, v91, v233
	v_fmac_f32_e32 v221, v90, v220
	v_fmac_f32_e32 v225, v90, v224
	v_fmac_f32_e32 v229, v90, v228
	v_fmac_f32_e32 v233, v90, v232
	v_fmac_f32_e32 v221, v32, v222
	v_fmac_f32_e32 v225, v32, v226
	v_fmac_f32_e32 v229, v32, v230
	v_fmac_f32_e32 v233, v32, v234
	v_fmac_f32_e32 v221, v92, v223
	v_fmac_f32_e32 v225, v92, v227
	v_fmac_f32_e32 v229, v92, v231
	v_fmac_f32_e32 v233, v92, v235
	v_add_f32_e32 v241, 0, v221
	v_add_f32_e32 v242, 0, v225
	v_add_f32_e32 v243, 0, v229
	v_add_f32_e32 v236, 0, v233
	ds_read_b128 v[220:223], v19 offset:32
	ds_read_b128 v[224:227], v19 offset:416
	ds_read_b128 v[228:231], v19 offset:800
	ds_read_b128 v[232:235], v19 offset:1184
	s_waitcnt lgkmcnt(4)
	v_mul_f32_e32 v245, v78, v245
	v_mul_f32_e32 v249, v78, v249
	v_mul_f32_e32 v253, v78, v253
	v_mul_f32_e32 v1, v78, v1
	v_fmac_f32_e32 v245, v33, v244
	v_fmac_f32_e32 v249, v33, v248
	v_fmac_f32_e32 v253, v33, v252
	v_fmac_f32_e32 v1, v33, v0
	v_fmac_f32_e32 v245, v79, v246
	v_fmac_f32_e32 v249, v79, v250
	v_fmac_f32_e32 v253, v79, v254
	v_fmac_f32_e32 v1, v79, v2
	v_fmac_f32_e32 v245, v93, v247
	v_fmac_f32_e32 v249, v93, v251
	v_fmac_f32_e32 v253, v93, v255
	v_fmac_f32_e32 v1, v93, v3
	v_add_f32_e32 v241, v241, v245
	v_add_f32_e32 v242, v242, v249
	v_add_f32_e32 v243, v243, v253
	v_add_f32_e32 v236, v236, v1
	ds_read_b128 v[244:247], v19 offset:48
	ds_read_b128 v[248:251], v19 offset:432
	ds_read_b128 v[252:255], v19 offset:816
	ds_read_b128 v[0:3], v19 offset:1200
	s_waitcnt lgkmcnt(4)
; __device__ void phase_combine(const P& p, int l, int ntok, float* lds) {
;     ...
;         float gate[4];
; #pragma unroll
;         for (int i = 0; i < 4; ++i) gate[i] = 0.f;
; #pragma unroll
;         for (int m = 0; m < 96; m += 4) {
; #pragma unroll
;           for (int i = 0; i < 4; ++i) {
;             float4 s = *reinterpret_cast<const float4*>(sig + (i0 + i) * 96 + m);
;             gate[i] += s.x * g2r[m] + s.y * g2r[m + 1] + s.z * g2r[m + 2] + s.w * g2r[m + 3];
;           }
;         }
	v_mul_f32_e32 v221, v81, v221
	v_mul_f32_e32 v225, v81, v225
	v_mul_f32_e32 v229, v81, v229
	v_mul_f32_e32 v233, v81, v233
	v_fmac_f32_e32 v221, v80, v220
	v_fmac_f32_e32 v225, v80, v224
	v_fmac_f32_e32 v229, v80, v228
	v_fmac_f32_e32 v233, v80, v232
	v_fmac_f32_e32 v221, v82, v222
	v_fmac_f32_e32 v225, v82, v226
	v_fmac_f32_e32 v229, v82, v230
	v_fmac_f32_e32 v233, v82, v234
	v_fmac_f32_e32 v221, v11, v223
	v_fmac_f32_e32 v225, v11, v227
	v_fmac_f32_e32 v229, v11, v231
	v_fmac_f32_e32 v233, v11, v235
	v_add_f32_e32 v241, v241, v221
	v_add_f32_e32 v242, v242, v225
	v_add_f32_e32 v243, v243, v229
	v_add_f32_e32 v236, v236, v233
	ds_read_b128 v[220:223], v19 offset:64
	ds_read_b128 v[224:227], v19 offset:448
	ds_read_b128 v[228:231], v19 offset:832
	ds_read_b128 v[232:235], v19 offset:1216
	s_waitcnt lgkmcnt(4)
	v_mul_f32_e32 v245, v84, v245
	v_mul_f32_e32 v249, v84, v249
	v_mul_f32_e32 v253, v84, v253
	v_mul_f32_e32 v1, v84, v1
	v_fmac_f32_e32 v245, v83, v244
	v_fmac_f32_e32 v249, v83, v248
	v_fmac_f32_e32 v253, v83, v252
	v_fmac_f32_e32 v1, v83, v0
	v_fmac_f32_e32 v245, v85, v246
	v_fmac_f32_e32 v249, v85, v250
	v_fmac_f32_e32 v253, v85, v254
	v_fmac_f32_e32 v1, v85, v2
	v_fmac_f32_e32 v245, v94, v247
	v_fmac_f32_e32 v249, v94, v251
	v_fmac_f32_e32 v253, v94, v255
	v_fmac_f32_e32 v1, v94, v3
	v_add_f32_e32 v241, v241, v245
	v_add_f32_e32 v242, v242, v249
	v_add_f32_e32 v243, v243, v253
	v_add_f32_e32 v236, v236, v1
	ds_read_b128 v[244:247], v19 offset:80
	ds_read_b128 v[248:251], v19 offset:464
	ds_read_b128 v[252:255], v19 offset:848
	ds_read_b128 v[0:3], v19 offset:1232
	s_waitcnt lgkmcnt(4)
	v_mul_f32_e32 v221, v87, v221
	v_mul_f32_e32 v225, v87, v225
	v_mul_f32_e32 v229, v87, v229
	v_mul_f32_e32 v233, v87, v233
	v_fmac_f32_e32 v221, v86, v220
	v_fmac_f32_e32 v225, v86, v224
	v_fmac_f32_e32 v229, v86, v228
	v_fmac_f32_e32 v233, v86, v232
	v_fmac_f32_e32 v221, v88, v222
	v_fmac_f32_e32 v225, v88, v226
	v_fmac_f32_e32 v229, v88, v230
	v_fmac_f32_e32 v233, v88, v234
	v_fmac_f32_e32 v221, v95, v223
	v_fmac_f32_e32 v225, v95, v227
	v_fmac_f32_e32 v229, v95, v231
	v_fmac_f32_e32 v233, v95, v235
	v_add_f32_e32 v241, v241, v221
	v_add_f32_e32 v242, v242, v225
	v_add_f32_e32 v243, v243, v229
	v_add_f32_e32 v236, v236, v233
	ds_read_b128 v[220:223], v19 offset:96
	ds_read_b128 v[224:227], v19 offset:480
	ds_read_b128 v[228:231], v19 offset:864
	ds_read_b128 v[232:235], v19 offset:1248
	s_waitcnt lgkmcnt(4)
	v_mul_f32_e32 v245, v26, v245
	v_mul_f32_e32 v249, v26, v249
	v_mul_f32_e32 v253, v26, v253
	v_mul_f32_e32 v1, v26, v1
	v_fmac_f32_e32 v245, v89, v244
	v_fmac_f32_e32 v249, v89, v248
	v_fmac_f32_e32 v253, v89, v252
	v_fmac_f32_e32 v1, v89, v0
	v_fmac_f32_e32 v245, v27, v246
	v_fmac_f32_e32 v249, v27, v250
	v_fmac_f32_e32 v253, v27, v254
	v_fmac_f32_e32 v1, v27, v2
	v_fmac_f32_e32 v245, v24, v247
	v_fmac_f32_e32 v249, v24, v251
	v_fmac_f32_e32 v253, v24, v255
	v_fmac_f32_e32 v1, v24, v3
	v_add_f32_e32 v241, v241, v245
	v_add_f32_e32 v242, v242, v249
	v_add_f32_e32 v243, v243, v253
	v_add_f32_e32 v236, v236, v1
	ds_read_b128 v[244:247], v19 offset:112
	ds_read_b128 v[248:251], v19 offset:496
	ds_read_b128 v[252:255], v19 offset:880
	ds_read_b128 v[0:3], v19 offset:1264
	s_waitcnt lgkmcnt(4)
	v_mul_f32_e32 v221, v30, v221
	v_mul_f32_e32 v225, v30, v225
	v_mul_f32_e32 v229, v30, v229
	v_mul_f32_e32 v233, v30, v233
	v_fmac_f32_e32 v221, v25, v220
	v_fmac_f32_e32 v225, v25, v224
	v_fmac_f32_e32 v229, v25, v228
	v_fmac_f32_e32 v233, v25, v232
	v_fmac_f32_e32 v221, v31, v222
	v_fmac_f32_e32 v225, v31, v226
	v_fmac_f32_e32 v229, v31, v230
	v_fmac_f32_e32 v233, v31, v234
	v_fmac_f32_e32 v221, v103, v223
	v_fmac_f32_e32 v225, v103, v227
	v_fmac_f32_e32 v229, v103, v231
	v_fmac_f32_e32 v233, v103, v235
	v_add_f32_e32 v241, v241, v221
	v_add_f32_e32 v242, v242, v225
	v_add_f32_e32 v243, v243, v229
	v_add_f32_e32 v236, v236, v233
	ds_read_b128 v[220:223], v19 offset:128
	ds_read_b128 v[224:227], v19 offset:512
	ds_read_b128 v[228:231], v19 offset:896
	ds_read_b128 v[232:235], v19 offset:1280
	s_waitcnt lgkmcnt(4)
	v_mul_f32_e32 v245, v34, v245
	v_mul_f32_e32 v249, v34, v249
	v_mul_f32_e32 v253, v34, v253
	v_mul_f32_e32 v1, v34, v1
	v_fmac_f32_e32 v245, v96, v244
	v_fmac_f32_e32 v249, v96, v248
	v_fmac_f32_e32 v253, v96, v252
	v_fmac_f32_e32 v1, v96, v0
	v_fmac_f32_e32 v245, v35, v246
	v_fmac_f32_e32 v249, v35, v250
	v_fmac_f32_e32 v253, v35, v254
	v_fmac_f32_e32 v1, v35, v2
	v_fmac_f32_e32 v245, v28, v247
	v_fmac_f32_e32 v249, v28, v251
	v_fmac_f32_e32 v253, v28, v255
	v_fmac_f32_e32 v1, v28, v3
	v_add_f32_e32 v241, v241, v245
	v_add_f32_e32 v242, v242, v249
	v_add_f32_e32 v243, v243, v253
	v_add_f32_e32 v236, v236, v1
	ds_read_b128 v[244:247], v19 offset:144
	ds_read_b128 v[248:251], v19 offset:528
	ds_read_b128 v[252:255], v19 offset:912
	ds_read_b128 v[0:3], v19 offset:1296
	s_waitcnt lgkmcnt(4)
	v_mul_f32_e32 v221, v38, v221
	v_mul_f32_e32 v225, v38, v225
	v_mul_f32_e32 v229, v38, v229
	v_mul_f32_e32 v233, v38, v233
	v_fmac_f32_e32 v221, v97, v220
	v_fmac_f32_e32 v225, v97, v224
	v_fmac_f32_e32 v229, v97, v228
	v_fmac_f32_e32 v233, v97, v232
	v_fmac_f32_e32 v221, v39, v222
	v_fmac_f32_e32 v225, v39, v226
	v_fmac_f32_e32 v229, v39, v230
	v_fmac_f32_e32 v233, v39, v234
	v_fmac_f32_e32 v221, v29, v223
	v_fmac_f32_e32 v225, v29, v227
	v_fmac_f32_e32 v229, v29, v231
	v_fmac_f32_e32 v233, v29, v235
	v_add_f32_e32 v241, v241, v221
	v_add_f32_e32 v242, v242, v225
	v_add_f32_e32 v243, v243, v229
	v_add_f32_e32 v236, v236, v233
	ds_read_b128 v[220:223], v19 offset:160
	ds_read_b128 v[224:227], v19 offset:544
	ds_read_b128 v[228:231], v19 offset:928
	ds_read_b128 v[232:235], v19 offset:1312
	s_waitcnt lgkmcnt(4)
; __device__ void phase_combine(const P& p, int l, int ntok, float* lds) {
;     ...
;         float gate[4];
; #pragma unroll
;         for (int i = 0; i < 4; ++i) gate[i] = 0.f;
; #pragma unroll
;         for (int m = 0; m < 96; m += 4) {
; #pragma unroll
;           for (int i = 0; i < 4; ++i) {
;             float4 s = *reinterpret_cast<const float4*>(sig + (i0 + i) * 96 + m);
;             gate[i] += s.x * g2r[m] + s.y * g2r[m + 1] + s.z * g2r[m + 2] + s.w * g2r[m + 3];
;           }
;         }
	v_mul_f32_e32 v245, v42, v245
	v_mul_f32_e32 v249, v42, v249
	v_mul_f32_e32 v253, v42, v253
	v_mul_f32_e32 v1, v42, v1
	v_fmac_f32_e32 v245, v98, v244
	v_fmac_f32_e32 v249, v98, v248
	v_fmac_f32_e32 v253, v98, v252
	v_fmac_f32_e32 v1, v98, v0
	v_fmac_f32_e32 v245, v43, v246
	v_fmac_f32_e32 v249, v43, v250
	v_fmac_f32_e32 v253, v43, v254
	v_fmac_f32_e32 v1, v43, v2
	v_fmac_f32_e32 v245, v36, v247
	v_fmac_f32_e32 v249, v36, v251
	v_fmac_f32_e32 v253, v36, v255
	v_fmac_f32_e32 v1, v36, v3
	v_add_f32_e32 v241, v241, v245
	v_add_f32_e32 v242, v242, v249
	v_add_f32_e32 v243, v243, v253
	v_add_f32_e32 v236, v236, v1
	ds_read_b128 v[244:247], v19 offset:176
	ds_read_b128 v[248:251], v19 offset:560
	ds_read_b128 v[252:255], v19 offset:944
	ds_read_b128 v[0:3], v19 offset:1328
	s_waitcnt lgkmcnt(4)
	v_mul_f32_e32 v221, v46, v221
	v_mul_f32_e32 v225, v46, v225
	v_mul_f32_e32 v229, v46, v229
	v_mul_f32_e32 v233, v46, v233
	v_fmac_f32_e32 v221, v99, v220
	v_fmac_f32_e32 v225, v99, v224
	v_fmac_f32_e32 v229, v99, v228
	v_fmac_f32_e32 v233, v99, v232
	v_fmac_f32_e32 v221, v47, v222
	v_fmac_f32_e32 v225, v47, v226
	v_fmac_f32_e32 v229, v47, v230
	v_fmac_f32_e32 v233, v47, v234
	v_fmac_f32_e32 v221, v37, v223
	v_fmac_f32_e32 v225, v37, v227
	v_fmac_f32_e32 v229, v37, v231
	v_fmac_f32_e32 v233, v37, v235
	v_add_f32_e32 v241, v241, v221
	v_add_f32_e32 v242, v242, v225
	v_add_f32_e32 v243, v243, v229
	v_add_f32_e32 v236, v236, v233
	ds_read_b128 v[220:223], v19 offset:192
	ds_read_b128 v[224:227], v19 offset:576
	ds_read_b128 v[228:231], v19 offset:960
	ds_read_b128 v[232:235], v19 offset:1344
	s_waitcnt lgkmcnt(4)
	v_mul_f32_e32 v245, v50, v245
	v_mul_f32_e32 v249, v50, v249
	v_mul_f32_e32 v253, v50, v253
	v_mul_f32_e32 v1, v50, v1
	v_fmac_f32_e32 v245, v100, v244
	v_fmac_f32_e32 v249, v100, v248
	v_fmac_f32_e32 v253, v100, v252
	v_fmac_f32_e32 v1, v100, v0
	v_fmac_f32_e32 v245, v51, v246
	v_fmac_f32_e32 v249, v51, v250
	v_fmac_f32_e32 v253, v51, v254
	v_fmac_f32_e32 v1, v51, v2
	v_fmac_f32_e32 v245, v40, v247
	v_fmac_f32_e32 v249, v40, v251
	v_fmac_f32_e32 v253, v40, v255
	v_fmac_f32_e32 v1, v40, v3
	v_add_f32_e32 v241, v241, v245
	v_add_f32_e32 v242, v242, v249
	v_add_f32_e32 v243, v243, v253
	v_add_f32_e32 v236, v236, v1
	ds_read_b128 v[244:247], v19 offset:208
	ds_read_b128 v[248:251], v19 offset:592
	ds_read_b128 v[252:255], v19 offset:976
	ds_read_b128 v[0:3], v19 offset:1360
	s_waitcnt lgkmcnt(4)
	v_mul_f32_e32 v221, v56, v221
	v_mul_f32_e32 v225, v56, v225
	v_mul_f32_e32 v229, v56, v229
	v_mul_f32_e32 v233, v56, v233
	v_fmac_f32_e32 v221, v101, v220
	v_fmac_f32_e32 v225, v101, v224
	v_fmac_f32_e32 v229, v101, v228
	v_fmac_f32_e32 v233, v101, v232
	v_fmac_f32_e32 v221, v57, v222
	v_fmac_f32_e32 v225, v57, v226
	v_fmac_f32_e32 v229, v57, v230
	v_fmac_f32_e32 v233, v57, v234
	v_fmac_f32_e32 v221, v41, v223
	v_fmac_f32_e32 v225, v41, v227
	v_fmac_f32_e32 v229, v41, v231
	v_fmac_f32_e32 v233, v41, v235
	v_add_f32_e32 v241, v241, v221
	v_add_f32_e32 v242, v242, v225
	v_add_f32_e32 v243, v243, v229
	v_add_f32_e32 v236, v236, v233
	ds_read_b128 v[220:223], v19 offset:224
	ds_read_b128 v[224:227], v19 offset:608
	ds_read_b128 v[228:231], v19 offset:992
	ds_read_b128 v[232:235], v19 offset:1376
	s_waitcnt lgkmcnt(4)
	v_mul_f32_e32 v245, v60, v245
	v_mul_f32_e32 v249, v60, v249
	v_mul_f32_e32 v253, v60, v253
	v_mul_f32_e32 v1, v60, v1
	v_fmac_f32_e32 v245, v102, v244
	v_fmac_f32_e32 v249, v102, v248
	v_fmac_f32_e32 v253, v102, v252
	v_fmac_f32_e32 v1, v102, v0
	v_fmac_f32_e32 v245, v61, v246
	v_fmac_f32_e32 v249, v61, v250
	v_fmac_f32_e32 v253, v61, v254
	v_fmac_f32_e32 v1, v61, v2
	v_fmac_f32_e32 v245, v44, v247
	v_fmac_f32_e32 v249, v44, v251
	v_fmac_f32_e32 v253, v44, v255
	v_fmac_f32_e32 v1, v44, v3
	v_add_f32_e32 v241, v241, v245
	v_add_f32_e32 v242, v242, v249
	v_add_f32_e32 v243, v243, v253
	v_add_f32_e32 v236, v236, v1
	ds_read_b128 v[244:247], v19 offset:240
	ds_read_b128 v[248:251], v19 offset:624
	ds_read_b128 v[252:255], v19 offset:1008
	ds_read_b128 v[0:3], v19 offset:1392
	s_waitcnt lgkmcnt(4)
	v_mul_f32_e32 v221, v48, v221
	v_mul_f32_e32 v225, v48, v225
	v_mul_f32_e32 v229, v48, v229
	v_mul_f32_e32 v233, v48, v233
	v_fmac_f32_e32 v221, v45, v220
	v_fmac_f32_e32 v225, v45, v224
	v_fmac_f32_e32 v229, v45, v228
	v_fmac_f32_e32 v233, v45, v232
	v_fmac_f32_e32 v221, v49, v222
	v_fmac_f32_e32 v225, v49, v226
	v_fmac_f32_e32 v229, v49, v230
	v_fmac_f32_e32 v233, v49, v234
	v_fmac_f32_e32 v221, v54, v223
	v_fmac_f32_e32 v225, v54, v227
	v_fmac_f32_e32 v229, v54, v231
	v_fmac_f32_e32 v233, v54, v235
	v_add_f32_e32 v241, v241, v221
	v_add_f32_e32 v242, v242, v225
	v_add_f32_e32 v243, v243, v229
	v_add_f32_e32 v236, v236, v233
	ds_read_b128 v[220:223], v19 offset:256
	ds_read_b128 v[224:227], v19 offset:640
	ds_read_b128 v[228:231], v19 offset:1024
	ds_read_b128 v[232:235], v19 offset:1408
	s_waitcnt lgkmcnt(4)
	v_mul_f32_e32 v245, v53, v245
	v_mul_f32_e32 v249, v53, v249
	v_mul_f32_e32 v253, v53, v253
	v_mul_f32_e32 v1, v53, v1
	v_fmac_f32_e32 v245, v52, v244
	v_fmac_f32_e32 v249, v52, v248
	v_fmac_f32_e32 v253, v52, v252
	v_fmac_f32_e32 v1, v52, v0
	v_fmac_f32_e32 v245, v58, v246
	v_fmac_f32_e32 v249, v58, v250
	v_fmac_f32_e32 v253, v58, v254
	v_fmac_f32_e32 v1, v58, v2
	v_fmac_f32_e32 v245, v55, v247
	v_fmac_f32_e32 v249, v55, v251
	v_fmac_f32_e32 v253, v55, v255
	v_fmac_f32_e32 v1, v55, v3
	v_add_f32_e32 v241, v241, v245
	v_add_f32_e32 v242, v242, v249
	v_add_f32_e32 v243, v243, v253
	v_add_f32_e32 v236, v236, v1
	ds_read_b128 v[244:247], v19 offset:272
	ds_read_b128 v[248:251], v19 offset:656
	ds_read_b128 v[252:255], v19 offset:1040
	ds_read_b128 v[0:3], v19 offset:1424
	s_waitcnt lgkmcnt(4)
; __device__ void phase_combine(const P& p, int l, int ntok, float* lds) {
;     ...
;         float gate[4];
; #pragma unroll
;         for (int i = 0; i < 4; ++i) gate[i] = 0.f;
; #pragma unroll
;         for (int m = 0; m < 96; m += 4) {
; #pragma unroll
;           for (int i = 0; i < 4; ++i) {
;             float4 s = *reinterpret_cast<const float4*>(sig + (i0 + i) * 96 + m);
;             gate[i] += s.x * g2r[m] + s.y * g2r[m + 1] + s.z * g2r[m + 2] + s.w * g2r[m + 3];
;           }
;         }
	v_mul_f32_e32 v221, v64, v221
	v_mul_f32_e32 v225, v64, v225
	v_mul_f32_e32 v229, v64, v229
	v_mul_f32_e32 v233, v64, v233
	v_fmac_f32_e32 v221, v59, v220
	v_fmac_f32_e32 v225, v59, v224
	v_fmac_f32_e32 v229, v59, v228
	v_fmac_f32_e32 v233, v59, v232
	v_fmac_f32_e32 v221, v65, v222
	v_fmac_f32_e32 v225, v65, v226
	v_fmac_f32_e32 v229, v65, v230
	v_fmac_f32_e32 v233, v65, v234
	v_fmac_f32_e32 v221, v62, v223
	v_fmac_f32_e32 v225, v62, v227
	v_fmac_f32_e32 v229, v62, v231
	v_fmac_f32_e32 v233, v62, v235
	v_add_f32_e32 v241, v241, v221
	v_add_f32_e32 v242, v242, v225
	v_add_f32_e32 v243, v243, v229
	v_add_f32_e32 v236, v236, v233
	ds_read_b128 v[220:223], v19 offset:288
	ds_read_b128 v[224:227], v19 offset:672
	ds_read_b128 v[228:231], v19 offset:1056
	ds_read_b128 v[232:235], v19 offset:1440
	s_waitcnt lgkmcnt(4)
	v_mul_f32_e32 v245, v67, v245
	v_mul_f32_e32 v249, v67, v249
	v_mul_f32_e32 v253, v67, v253
	v_mul_f32_e32 v1, v67, v1
	v_fmac_f32_e32 v245, v66, v244
	v_fmac_f32_e32 v249, v66, v248
	v_fmac_f32_e32 v253, v66, v252
	v_fmac_f32_e32 v1, v66, v0
	v_fmac_f32_e32 v245, v70, v246
	v_fmac_f32_e32 v249, v70, v250
	v_fmac_f32_e32 v253, v70, v254
	v_fmac_f32_e32 v1, v70, v2
	v_fmac_f32_e32 v245, v63, v247
	v_fmac_f32_e32 v249, v63, v251
	v_fmac_f32_e32 v253, v63, v255
	v_fmac_f32_e32 v1, v63, v3
	v_add_f32_e32 v241, v241, v245
	v_add_f32_e32 v242, v242, v249
	v_add_f32_e32 v243, v243, v253
	v_add_f32_e32 v236, v236, v1
	ds_read_b128 v[244:247], v19 offset:304
	ds_read_b128 v[248:251], v19 offset:688
	ds_read_b128 v[252:255], v19 offset:1072
	ds_read_b128 v[0:3], v19 offset:1456
	s_waitcnt lgkmcnt(4)
	v_mul_f32_e32 v221, v74, v221
	v_mul_f32_e32 v225, v74, v225
	v_mul_f32_e32 v229, v74, v229
	v_mul_f32_e32 v233, v74, v233
	v_fmac_f32_e32 v221, v71, v220
	v_fmac_f32_e32 v225, v71, v224
	v_fmac_f32_e32 v229, v71, v228
	v_fmac_f32_e32 v233, v71, v232
	v_fmac_f32_e32 v221, v75, v222
	v_fmac_f32_e32 v225, v75, v226
	v_fmac_f32_e32 v229, v75, v230
	v_fmac_f32_e32 v233, v75, v234
	v_fmac_f32_e32 v221, v68, v223
	v_fmac_f32_e32 v225, v68, v227
	v_fmac_f32_e32 v229, v68, v231
	v_fmac_f32_e32 v233, v68, v235
	v_add_f32_e32 v241, v241, v221
	v_add_f32_e32 v242, v242, v225
	v_add_f32_e32 v243, v243, v229
	v_add_f32_e32 v236, v236, v233
	ds_read_b128 v[220:223], v19 offset:320
	ds_read_b128 v[224:227], v19 offset:704
	ds_read_b128 v[228:231], v19 offset:1088
	ds_read_b128 v[232:235], v19 offset:1472
	s_waitcnt lgkmcnt(4)
	v_mul_f32_e32 v245, v105, v245
	v_mul_f32_e32 v249, v105, v249
	v_mul_f32_e32 v253, v105, v253
	v_mul_f32_e32 v1, v105, v1
	v_fmac_f32_e32 v245, v104, v244
	v_fmac_f32_e32 v249, v104, v248
	v_fmac_f32_e32 v253, v104, v252
	v_fmac_f32_e32 v1, v104, v0
	v_fmac_f32_e32 v245, v106, v246
	v_fmac_f32_e32 v249, v106, v250
	v_fmac_f32_e32 v253, v106, v254
	v_fmac_f32_e32 v1, v106, v2
	v_fmac_f32_e32 v245, v69, v247
	v_fmac_f32_e32 v249, v69, v251
	v_fmac_f32_e32 v253, v69, v255
	v_fmac_f32_e32 v1, v69, v3
	v_add_f32_e32 v241, v241, v245
	v_add_f32_e32 v242, v242, v249
	v_add_f32_e32 v243, v243, v253
	v_add_f32_e32 v236, v236, v1
	ds_read_b128 v[244:247], v19 offset:336
	ds_read_b128 v[248:251], v19 offset:720
	ds_read_b128 v[252:255], v19 offset:1104
	ds_read_b128 v[0:3], v19 offset:1488
	s_waitcnt lgkmcnt(4)
	v_mul_f32_e32 v221, v108, v221
	v_mul_f32_e32 v225, v108, v225
	v_mul_f32_e32 v229, v108, v229
	v_mul_f32_e32 v233, v108, v233
	v_fmac_f32_e32 v221, v107, v220
	v_fmac_f32_e32 v225, v107, v224
	v_fmac_f32_e32 v229, v107, v228
	v_fmac_f32_e32 v233, v107, v232
	v_fmac_f32_e32 v221, v109, v222
	v_fmac_f32_e32 v225, v109, v226
	v_fmac_f32_e32 v229, v109, v230
	v_fmac_f32_e32 v233, v109, v234
	v_fmac_f32_e32 v221, v72, v223
	v_fmac_f32_e32 v225, v72, v227
	v_fmac_f32_e32 v229, v72, v231
	v_fmac_f32_e32 v233, v72, v235
	v_add_f32_e32 v241, v241, v221
	v_add_f32_e32 v242, v242, v225
	v_add_f32_e32 v243, v243, v229
	v_add_f32_e32 v236, v236, v233
	ds_read_b128 v[220:223], v19 offset:352
	ds_read_b128 v[224:227], v19 offset:736
	ds_read_b128 v[228:231], v19 offset:1120
	ds_read_b128 v[232:235], v19 offset:1504
	s_waitcnt lgkmcnt(4)
	v_mul_f32_e32 v245, v111, v245
	v_mul_f32_e32 v249, v111, v249
	v_mul_f32_e32 v253, v111, v253
	v_mul_f32_e32 v1, v111, v1
	v_fmac_f32_e32 v245, v110, v244
	v_fmac_f32_e32 v249, v110, v248
	v_fmac_f32_e32 v253, v110, v252
	v_fmac_f32_e32 v1, v110, v0
	v_fmac_f32_e32 v245, v112, v246
	v_fmac_f32_e32 v249, v112, v250
	v_fmac_f32_e32 v253, v112, v254
	v_fmac_f32_e32 v1, v112, v2
	v_fmac_f32_e32 v245, v73, v247
	v_fmac_f32_e32 v249, v73, v251
	v_fmac_f32_e32 v253, v73, v255
	v_fmac_f32_e32 v1, v73, v3
	v_add_f32_e32 v241, v241, v245
	v_add_f32_e32 v242, v242, v249
	v_add_f32_e32 v243, v243, v253
	v_add_f32_e32 v236, v236, v1
	ds_read_b128 v[244:247], v19 offset:368
	ds_read_b128 v[248:251], v19 offset:752
	ds_read_b128 v[252:255], v19 offset:1136
	ds_read_b128 v[0:3], v19 offset:1520
	s_waitcnt lgkmcnt(4)
	v_mul_f32_e32 v221, v77, v221
	v_mul_f32_e32 v225, v77, v225
	v_mul_f32_e32 v229, v77, v229
	v_mul_f32_e32 v233, v77, v233
	v_fmac_f32_e32 v221, v76, v220
	v_fmac_f32_e32 v225, v76, v224
	v_fmac_f32_e32 v229, v76, v228
	v_fmac_f32_e32 v233, v76, v232
	v_fmac_f32_e32 v221, v113, v222
	v_fmac_f32_e32 v225, v113, v226
	v_fmac_f32_e32 v229, v113, v230
	v_fmac_f32_e32 v233, v113, v234
	v_fmac_f32_e32 v221, v116, v223
	v_fmac_f32_e32 v225, v116, v227
	v_fmac_f32_e32 v229, v116, v231
	v_fmac_f32_e32 v233, v116, v235
	v_add_f32_e32 v241, v241, v221
	v_add_f32_e32 v242, v242, v225
	v_add_f32_e32 v243, v243, v229
	v_add_f32_e32 v236, v236, v233
	s_waitcnt lgkmcnt(0)
; __device__ __forceinline__ float bf2f(u16 v) { return __uint_as_float(((unsigned)v) << 16); }
; __device__ void phase_combine(const P& p, int l, int ntok, float* lds) {
;     ...
;         float gate[4];
; #pragma unroll
;         for (int i = 0; i < 4; ++i) gate[i] = 0.f;
; #pragma unroll
;         for (int m = 0; m < 96; m += 4) {
; #pragma unroll
;           for (int i = 0; i < 4; ++i) {
;             float4 s = *reinterpret_cast<const float4*>(sig + (i0 + i) * 96 + m);
;             gate[i] += s.x * g2r[m] + s.y * g2r[m + 1] + s.z * g2r[m + 2] + s.w * g2r[m + 3];
;           }
;         }
; #pragma unroll
;         for (int i = 0; i < 4; ++i) {
;           int row = r0 + i0 + i, t = tb + i0 + i;
;           float yv = bf2f((u16)y0[i]) + bf2f((u16)y1[i]);
;           float mean = wave_sum_b(yv) * (1.f / 64.f);
;           float d = yv - mean;
;           float var = wave_sum_b(d * d) * (1.f / 64.f);
;           float yn = d * rsqrtf(var + 64e-5f) * gnw + gnb;
;           float v_c = bf2f((u16)vc[i]), v_p = t > 0 ? bf2f((u16)vp[i]) : 0.f, v_n = t < T - 1 ? bf2f((u16)vn[i]) : 0.f;
;           float vf = v_c + (v_p - v_c) * muvf, vb = v_c + (v_n - v_c) * muvb;
;           float bonus = sf[i] * vf + sb[i] * vb;
;           p.nbuf[(size_t)row * D + 1536 + tid] = f2bf((yn + bonus) * gate[i]);
;         }
	v_mul_f32_e32 v245, v115, v245
	v_mul_f32_e32 v249, v115, v249
	v_mul_f32_e32 v253, v115, v253
	v_mul_f32_e32 v1, v115, v1
	v_fmac_f32_e32 v245, v114, v244
	v_fmac_f32_e32 v249, v114, v248
	v_fmac_f32_e32 v253, v114, v252
	v_fmac_f32_e32 v1, v114, v0
	v_fmac_f32_e32 v245, v117, v246
	v_fmac_f32_e32 v249, v117, v250
	v_fmac_f32_e32 v253, v117, v254
	v_fmac_f32_e32 v1, v117, v2
	v_fmac_f32_e32 v245, v118, v247
	v_fmac_f32_e32 v249, v118, v251
	v_fmac_f32_e32 v253, v118, v255
	v_fmac_f32_e32 v1, v118, v3
	v_add_f32_e32 v221, v241, v245
	v_add_f32_e32 v222, v242, v249
	v_add_f32_e32 v223, v243, v253
	v_add_f32_e32 v0, v236, v1
	s_waitcnt vmcnt(30)
	s_waitcnt vmcnt(29)
	s_waitcnt vmcnt(4)
	s_waitcnt vmcnt(0)
	v_lshlrev_b32_e32 v197, 16, v197
	v_lshlrev_b32_e32 v192, 16, v192
	v_lshlrev_b32_e32 v164, 16, v164
	v_lshlrev_b32_e32 v158, 16, v158
	v_lshlrev_b32_e32 v152, 16, v152
	v_lshlrev_b32_e32 v138, 16, v138
	v_lshlrev_b32_e32 v1, 16, v201
	v_lshlrev_b32_e32 v2, 16, v202
	v_add_f32_e32 v1, v2, v1
	v_mov_b32_e32 v3, v129
	s_nop 0
	v_add_f32_dpp v2, v1, v1 quad_perm:[1,0,3,2] row_mask:0xf bank_mask:0xf bound_ctrl:1
	s_nop 1
	v_add_f32_dpp v2, v2, v2 quad_perm:[2,3,0,1] row_mask:0xf bank_mask:0xf bound_ctrl:1
	s_nop 1
	v_add_f32_dpp v2, v2, v2 row_half_mirror row_mask:0xf bank_mask:0xf bound_ctrl:1
	s_nop 1
	v_add_f32_dpp v2, v2, v2 row_mirror row_mask:0xf bank_mask:0xf bound_ctrl:1
	s_nop 1
	v_mov_b32_dpp v3, v2 row_bcast:15 row_mask:0xa bank_mask:0xf
	v_add_f32_e32 v2, v2, v3
	v_mov_b32_e32 v3, v129
	s_nop 1
	v_mov_b32_dpp v3, v2 row_bcast:31 row_mask:0xc bank_mask:0xf
	v_add_f32_e32 v2, v2, v3
	v_mov_b32_e32 v3, v129
	v_readlane_b32 s0, v2, 63
	s_nop 1
	v_fmac_f32_e32 v1, s0, v180
	v_mul_f32_e32 v2, v1, v1
	s_nop 1
	v_mov_b32_dpp v2, v2 quad_perm:[1,0,3,2] row_mask:0xf bank_mask:0xf bound_ctrl:1
	v_fmac_f32_e32 v2, v1, v1
	s_nop 1
	v_add_f32_dpp v2, v2, v2 quad_perm:[2,3,0,1] row_mask:0xf bank_mask:0xf bound_ctrl:1
	s_nop 1
	v_add_f32_dpp v2, v2, v2 row_half_mirror row_mask:0xf bank_mask:0xf bound_ctrl:1
	s_nop 1
	v_add_f32_dpp v2, v2, v2 row_mirror row_mask:0xf bank_mask:0xf bound_ctrl:1
	s_nop 1
	v_mov_b32_dpp v3, v2 row_bcast:15 row_mask:0xa bank_mask:0xf
	v_add_f32_e32 v2, v2, v3
	v_mov_b32_e32 v3, v129
	s_nop 1
	v_mov_b32_dpp v3, v2 row_bcast:31 row_mask:0xc bank_mask:0xf
	v_add_f32_e32 v2, v2, v3
	s_nop 0
	v_readlane_b32 s0, v2, 63
	s_nop 1
	v_fma_f32 v2, s0, v181, v170
	v_cmp_gt_f32_e64 s[0:1], s33, v2
	v_mul_f32_e32 v3, 0x4b800000, v2
	s_nop 0
	v_cndmask_b32_e64 v2, v2, v3, s[0:1]
	v_rsq_f32_e32 v2, v2
	s_nop 0
	v_mul_f32_e32 v3, 0x45800000, v2
	v_cndmask_b32_e64 v2, v2, v3, s[0:1]
	v_mul_f32_e32 v1, v1, v2
	v_lshlrev_b32_e32 v2, 16, v18
	v_lshlrev_b32_e32 v3, 16, v208
	v_lshlrev_b32_e32 v18, 16, v210
	v_cndmask_b32_e64 v3, v3, 0, s[52:53]
	v_cndmask_b32_e64 v18, 0, v18, s[44:45]
	v_sub_f32_e32 v3, v3, v2
	v_sub_f32_e32 v18, v18, v2
	v_fma_f32 v3, v121, v3, v2
	v_fmac_f32_e32 v2, v122, v18
	v_mul_f32_e32 v2, v219, v2
	v_fma_f32 v1, v119, v1, v120
	v_fmac_f32_e32 v2, v218, v3
	v_add_f32_e32 v1, v2, v1
	v_mul_f32_e32 v1, v221, v1
	v_bfe_u32 v2, v1, 16, 1
	s_lshl_b64 s[44:45], s[46:47], 12
	v_add3_u32 v1, v1, v2, s21
	v_lshl_add_u64 v[18:19], v[14:15], 0, s[44:45]
	global_store_short_d16_hi v[18:19], v1, off offset:3072
	v_lshlrev_b32_e32 v1, 16, v212
	v_lshlrev_b32_e32 v2, 16, v213
	v_add_f32_e32 v1, v2, v1
	v_mov_b32_e32 v3, v129
	s_nop 0
	v_add_f32_dpp v2, v1, v1 quad_perm:[1,0,3,2] row_mask:0xf bank_mask:0xf bound_ctrl:1
	s_nop 1
	v_add_f32_dpp v2, v2, v2 quad_perm:[2,3,0,1] row_mask:0xf bank_mask:0xf bound_ctrl:1
	s_nop 1
	v_add_f32_dpp v2, v2, v2 row_half_mirror row_mask:0xf bank_mask:0xf bound_ctrl:1
	s_nop 1
	v_add_f32_dpp v2, v2, v2 row_mirror row_mask:0xf bank_mask:0xf bound_ctrl:1
	s_nop 1
	v_mov_b32_dpp v3, v2 row_bcast:15 row_mask:0xa bank_mask:0xf
	v_add_f32_e32 v2, v2, v3
	v_mov_b32_e32 v3, v129
	s_nop 1
	v_mov_b32_dpp v3, v2 row_bcast:31 row_mask:0xc bank_mask:0xf
	v_add_f32_e32 v2, v2, v3
	v_mov_b32_e32 v3, v129
	v_readlane_b32 s0, v2, 63
	s_nop 1
	v_fmac_f32_e32 v1, s0, v180
	v_mul_f32_e32 v2, v1, v1
	s_nop 1
	v_mov_b32_dpp v2, v2 quad_perm:[1,0,3,2] row_mask:0xf bank_mask:0xf bound_ctrl:1
	v_fmac_f32_e32 v2, v1, v1
	s_nop 1
	v_add_f32_dpp v2, v2, v2 quad_perm:[2,3,0,1] row_mask:0xf bank_mask:0xf bound_ctrl:1
	s_nop 1
	v_add_f32_dpp v2, v2, v2 row_half_mirror row_mask:0xf bank_mask:0xf bound_ctrl:1
	s_nop 1
	v_add_f32_dpp v2, v2, v2 row_mirror row_mask:0xf bank_mask:0xf bound_ctrl:1
	s_nop 1
	v_mov_b32_dpp v3, v2 row_bcast:15 row_mask:0xa bank_mask:0xf
	v_add_f32_e32 v2, v2, v3
	v_mov_b32_e32 v3, v129
	s_nop 1
	v_mov_b32_dpp v3, v2 row_bcast:31 row_mask:0xc bank_mask:0xf
	v_add_f32_e32 v2, v2, v3
	s_nop 0
	v_readlane_b32 s0, v2, 63
	s_nop 1
	v_fma_f32 v2, s0, v181, v170
	v_cmp_gt_f32_e64 s[0:1], s33, v2
	v_mul_f32_e32 v3, 0x4b800000, v2
	s_nop 0
	v_cndmask_b32_e64 v2, v2, v3, s[0:1]
	v_rsq_f32_e32 v2, v2
	s_nop 0
	v_mul_f32_e32 v3, 0x45800000, v2
	v_cndmask_b32_e64 v2, v2, v3, s[0:1]
	v_mul_f32_e32 v1, v1, v2
	v_lshlrev_b32_e32 v2, 16, v21
	v_lshlrev_b32_e32 v21, 16, v206
	v_lshlrev_b32_e32 v3, 16, v199
	v_cndmask_b32_e64 v21, 0, v21, s[42:43]
	v_sub_f32_e32 v3, v3, v2
	v_sub_f32_e32 v21, v21, v2
	v_fma_f32 v3, v121, v3, v2
	v_fmac_f32_e32 v2, v122, v21
	v_mul_f32_e32 v2, v20, v2
	v_fma_f32 v1, v119, v1, v120
	v_fmac_f32_e32 v2, v217, v3
	v_add_f32_e32 v1, v2, v1
	v_mul_f32_e32 v1, v222, v1
	v_bfe_u32 v2, v1, 16, 1
	s_lshl_b64 s[42:43], s[50:51], 12
	v_add3_u32 v1, v1, v2, s21
	v_lshl_add_u64 v[20:21], v[14:15], 0, s[42:43]
	global_store_short_d16_hi v[20:21], v1, off offset:3072
	v_lshlrev_b32_e32 v1, 16, v209
; __device__ __forceinline__ float bf2f(u16 v) { return __uint_as_float(((unsigned)v) << 16); }
; __device__ __forceinline__ float siluf_(float x) { return x / (1.f + __expf(-x)); }
; __device__ void phase_combine(const P& p, int l, int ntok, float* lds) {
;     ...
; #pragma unroll
;         for (int i = 0; i < 4; ++i) {
;           int row = r0 + i0 + i, t = tb + i0 + i;
;           float yv = bf2f((u16)y0[i]) + bf2f((u16)y1[i]);
;           float mean = wave_sum_b(yv) * (1.f / 64.f);
;           float d = yv - mean;
;           float var = wave_sum_b(d * d) * (1.f / 64.f);
;           float yn = d * rsqrtf(var + 64e-5f) * gnw + gnb;
;           float v_c = bf2f((u16)vc[i]), v_p = t > 0 ? bf2f((u16)vp[i]) : 0.f, v_n = t < T - 1 ? bf2f((u16)vn[i]) : 0.f;
;           float vf = v_c + (v_p - v_c) * muvf, vb = v_c + (v_n - v_c) * muvb;
;           float bonus = sf[i] * vf + sb[i] * vb;
;           p.nbuf[(size_t)row * D + 1536 + tid] = f2bf((yn + bonus) * gate[i]);
;         }
;       }
; #pragma unroll
;       for (int i = 0; i < 4; ++i) {
;         int row = r0 + i0 + i;
;         float o0 = bf2f((u16)a0[i]) + bf2f((u16)a1[i]), o1 = bf2f((u16)a2[i]) + bf2f((u16)a3[i]);
;         float ss = wave_sum_b(o0 * o0 + o1 * o1);
;         float rstd = rsqrtf(ss * (1.f / 128.f) + 1e-6f);
;         u16* dst = p.nbuf + (size_t)row * D + mixer * 512 + hh * 128 + lane;
;         dst[0] = f2bf(o0 * rstd * ng0 * siluf_(bf2f((u16)g0r[i])));
;         dst[64] = f2bf(o1 * rstd * ng1 * siluf_(bf2f((u16)g1r[i])));
	v_lshlrev_b32_e32 v2, 16, v211
	v_add_f32_e32 v1, v2, v1
	v_mov_b32_e32 v3, v129
	s_nop 0
	v_add_f32_dpp v2, v1, v1 quad_perm:[1,0,3,2] row_mask:0xf bank_mask:0xf bound_ctrl:1
	s_nop 1
	v_add_f32_dpp v2, v2, v2 quad_perm:[2,3,0,1] row_mask:0xf bank_mask:0xf bound_ctrl:1
	s_nop 1
	v_add_f32_dpp v2, v2, v2 row_half_mirror row_mask:0xf bank_mask:0xf bound_ctrl:1
	s_nop 1
	v_add_f32_dpp v2, v2, v2 row_mirror row_mask:0xf bank_mask:0xf bound_ctrl:1
	s_nop 1
	v_mov_b32_dpp v3, v2 row_bcast:15 row_mask:0xa bank_mask:0xf
	v_add_f32_e32 v2, v2, v3
	v_mov_b32_e32 v3, v129
	s_nop 1
	v_mov_b32_dpp v3, v2 row_bcast:31 row_mask:0xc bank_mask:0xf
	v_add_f32_e32 v2, v2, v3
	v_mov_b32_e32 v3, v129
	v_readlane_b32 s0, v2, 63
	s_nop 1
	v_fmac_f32_e32 v1, s0, v180
	v_mul_f32_e32 v2, v1, v1
	s_nop 1
	v_mov_b32_dpp v2, v2 quad_perm:[1,0,3,2] row_mask:0xf bank_mask:0xf bound_ctrl:1
	v_fmac_f32_e32 v2, v1, v1
	s_nop 1
	v_add_f32_dpp v2, v2, v2 quad_perm:[2,3,0,1] row_mask:0xf bank_mask:0xf bound_ctrl:1
	s_nop 1
	v_add_f32_dpp v2, v2, v2 row_half_mirror row_mask:0xf bank_mask:0xf bound_ctrl:1
	s_nop 1
	v_add_f32_dpp v2, v2, v2 row_mirror row_mask:0xf bank_mask:0xf bound_ctrl:1
	s_nop 1
	v_mov_b32_dpp v3, v2 row_bcast:15 row_mask:0xa bank_mask:0xf
	v_add_f32_e32 v2, v2, v3
	v_mov_b32_e32 v3, v129
	s_nop 1
	v_mov_b32_dpp v3, v2 row_bcast:31 row_mask:0xc bank_mask:0xf
	v_add_f32_e32 v2, v2, v3
	s_nop 0
	v_readlane_b32 s0, v2, 63
	s_nop 1
	v_fma_f32 v2, s0, v181, v170
	v_cmp_gt_f32_e64 s[0:1], s33, v2
	v_mul_f32_e32 v3, 0x4b800000, v2
	s_nop 0
	v_cndmask_b32_e64 v2, v2, v3, s[0:1]
	v_rsq_f32_e32 v2, v2
	s_nop 0
	v_mul_f32_e32 v3, 0x45800000, v2
	v_cndmask_b32_e64 v2, v2, v3, s[0:1]
	v_lshlrev_b32_e32 v3, 16, v198
	v_lshlrev_b32_e32 v198, 16, v204
	v_mul_f32_e32 v1, v1, v2
	v_lshlrev_b32_e32 v2, 16, v216
	v_cndmask_b32_e64 v198, 0, v198, s[40:41]
	v_sub_f32_e32 v3, v3, v2
	v_sub_f32_e32 v198, v198, v2
	v_fma_f32 v3, v121, v3, v2
	v_fmac_f32_e32 v2, v122, v198
	v_mul_f32_e32 v2, v23, v2
	v_fma_f32 v1, v119, v1, v120
	v_fmac_f32_e32 v2, v215, v3
	v_add_f32_e32 v1, v2, v1
	v_mul_f32_e32 v1, v223, v1
	v_bfe_u32 v2, v1, 16, 1
	v_add3_u32 v1, v1, v2, s21
	v_lshl_add_u64 v[2:3], v[14:15], 0, s[2:3]
	global_store_short_d16_hi v[2:3], v1, off offset:3072
	v_lshlrev_b32_e32 v1, 16, v205
	v_lshlrev_b32_e32 v23, 16, v207
	v_add_f32_e32 v1, v23, v1
	v_mov_b32_e32 v198, v129
	s_nop 0
	v_add_f32_dpp v23, v1, v1 quad_perm:[1,0,3,2] row_mask:0xf bank_mask:0xf bound_ctrl:1
	s_nop 1
	v_add_f32_dpp v23, v23, v23 quad_perm:[2,3,0,1] row_mask:0xf bank_mask:0xf bound_ctrl:1
	s_nop 1
	v_add_f32_dpp v23, v23, v23 row_half_mirror row_mask:0xf bank_mask:0xf bound_ctrl:1
	s_nop 1
	v_add_f32_dpp v23, v23, v23 row_mirror row_mask:0xf bank_mask:0xf bound_ctrl:1
	s_nop 1
	v_mov_b32_dpp v198, v23 row_bcast:15 row_mask:0xa bank_mask:0xf
	v_add_f32_e32 v23, v23, v198
	v_mov_b32_e32 v198, v129
	s_nop 1
	v_mov_b32_dpp v198, v23 row_bcast:31 row_mask:0xc bank_mask:0xf
	v_add_f32_e32 v23, v23, v198
	v_mov_b32_e32 v198, v129
	v_readlane_b32 s0, v23, 63
	s_nop 1
	v_fmac_f32_e32 v1, s0, v180
	v_mul_f32_e32 v23, v1, v1
	s_nop 1
	v_mov_b32_dpp v23, v23 quad_perm:[1,0,3,2] row_mask:0xf bank_mask:0xf bound_ctrl:1
	v_fmac_f32_e32 v23, v1, v1
	s_nop 1
	v_add_f32_dpp v23, v23, v23 quad_perm:[2,3,0,1] row_mask:0xf bank_mask:0xf bound_ctrl:1
	s_nop 1
	v_add_f32_dpp v23, v23, v23 row_half_mirror row_mask:0xf bank_mask:0xf bound_ctrl:1
	s_nop 1
	v_add_f32_dpp v23, v23, v23 row_mirror row_mask:0xf bank_mask:0xf bound_ctrl:1
	s_nop 1
	v_mov_b32_dpp v198, v23 row_bcast:15 row_mask:0xa bank_mask:0xf
	v_add_f32_e32 v23, v23, v198
	v_mov_b32_e32 v198, v129
	s_nop 1
	v_mov_b32_dpp v198, v23 row_bcast:31 row_mask:0xc bank_mask:0xf
	v_add_f32_e32 v23, v23, v198
	s_nop 0
	v_readlane_b32 s0, v23, 63
	s_nop 1
	v_fma_f32 v23, s0, v181, v170
	v_cmp_gt_f32_e64 s[0:1], s33, v23
	v_mul_f32_e32 v198, 0x4b800000, v23
	s_nop 0
	v_cndmask_b32_e64 v23, v23, v198, s[0:1]
	v_rsq_f32_e32 v23, v23
	s_nop 0
	v_mul_f32_e32 v198, 0x45800000, v23
	v_cndmask_b32_e64 v23, v23, v198, s[0:1]
	v_lshlrev_b32_e32 v198, 16, v203
	v_mul_f32_e32 v1, v1, v23
	v_lshlrev_b32_e32 v23, 16, v200
	v_cndmask_b32_e32 v198, 0, v198, vcc
	v_sub_f32_e32 v197, v197, v23
	v_sub_f32_e32 v198, v198, v23
	v_fma_f32 v197, v121, v197, v23
	v_fmac_f32_e32 v23, v122, v198
	v_mul_f32_e32 v22, v22, v23
	v_fma_f32 v1, v119, v1, v120
	v_fmac_f32_e32 v22, v214, v197
	v_add_f32_e32 v1, v22, v1
	v_mul_f32_e32 v0, v0, v1
	v_bfe_u32 v1, v0, 16, 1
	s_lshl_b64 s[0:1], s[36:37], 12
	v_add3_u32 v22, v0, v1, s21
	v_lshl_add_u64 v[0:1], v[14:15], 0, s[0:1]
	global_store_short_d16_hi v[0:1], v22, off offset:3072
	v_lshlrev_b32_e32 v22, 16, v195
	v_lshlrev_b32_e32 v23, 16, v196
	v_lshlrev_b32_e32 v196, 16, v193
	v_lshlrev_b32_e32 v197, 16, v194
	v_pk_add_f32 v[22:23], v[22:23], v[196:197]
	v_mul_f32_e32 v196, 0xbfb8aa3b, v192
	v_pk_mul_f32 v[194:195], v[22:23], v[22:23]
	v_exp_f32_e32 v196, v196
	v_add_f32_e32 v193, v194, v195
	v_mov_b32_e32 v194, v129
	v_add_f32_e32 v196, 1.0, v196
	v_add_f32_dpp v193, v193, v193 quad_perm:[1,0,3,2] row_mask:0xf bank_mask:0xf bound_ctrl:1
	v_div_scale_f32 v197, s[22:23], v196, v196, v192
	s_nop 0
	v_add_f32_dpp v193, v193, v193 quad_perm:[2,3,0,1] row_mask:0xf bank_mask:0xf bound_ctrl:1
	v_rcp_f32_e32 v198, v197
	s_nop 0
	v_add_f32_dpp v193, v193, v193 row_half_mirror row_mask:0xf bank_mask:0xf bound_ctrl:1
	v_fma_f32 v199, -v197, v198, 1.0
	s_nop 0
	v_add_f32_dpp v193, v193, v193 row_mirror row_mask:0xf bank_mask:0xf bound_ctrl:1
	v_fmac_f32_e32 v198, v199, v198
	s_nop 0
	v_mov_b32_dpp v194, v193 row_bcast:15 row_mask:0xa bank_mask:0xf
	v_add_f32_e32 v193, v193, v194
; __device__ __forceinline__ float bf2f(u16 v) { return __uint_as_float(((unsigned)v) << 16); }
; __device__ __forceinline__ float siluf_(float x) { return x / (1.f + __expf(-x)); }
; __device__ void phase_combine(const P& p, int l, int ntok, float* lds) {
;     ...
; #pragma unroll
;       for (int i = 0; i < 4; ++i) {
;         int row = r0 + i0 + i;
;         float o0 = bf2f((u16)a0[i]) + bf2f((u16)a1[i]), o1 = bf2f((u16)a2[i]) + bf2f((u16)a3[i]);
;         float ss = wave_sum_b(o0 * o0 + o1 * o1);
;         float rstd = rsqrtf(ss * (1.f / 128.f) + 1e-6f);
;         u16* dst = p.nbuf + (size_t)row * D + mixer * 512 + hh * 128 + lane;
;         dst[0] = f2bf(o0 * rstd * ng0 * siluf_(bf2f((u16)g0r[i])));
;         dst[64] = f2bf(o1 * rstd * ng1 * siluf_(bf2f((u16)g1r[i])));
;       }
	v_mov_b32_e32 v194, v129
	s_nop 1
	v_mov_b32_dpp v194, v193 row_bcast:31 row_mask:0xc bank_mask:0xf
	v_add_f32_e32 v193, v193, v194
	s_nop 0
	v_readlane_b32 s20, v193, 63
	s_nop 1
	v_fma_f32 v193, s20, v182, v169
	v_cmp_gt_f32_e32 vcc, s33, v193
	v_mul_f32_e32 v194, 0x4b800000, v193
	s_nop 0
	v_cndmask_b32_e32 v193, v193, v194, vcc
	v_rsq_f32_e32 v193, v193
	s_nop 0
	v_mul_f32_e32 v194, 0x45800000, v193
	v_cndmask_b32_e32 v193, v193, v194, vcc
	v_div_scale_f32 v199, vcc, v192, v196, v192
	v_mul_f32_e32 v200, v199, v198
	v_fma_f32 v201, -v197, v200, v199
	v_fmac_f32_e32 v200, v201, v198
	v_fma_f32 v197, -v197, v200, v199
	v_mul_f32_e32 v22, v22, v193
	v_div_fmas_f32 v197, v197, v198, v200
	v_mul_f32_e32 v22, v126, v22
	v_div_fixup_f32 v192, v197, v196, v192
	v_mul_f32_e32 v22, v192, v22
	v_bfe_u32 v192, v22, 16, 1
	v_lshl_add_u64 v[194:195], v[12:13], 0, s[44:45]
	v_add3_u32 v22, v22, v192, s21
	global_store_short_d16_hi v[194:195], v22, off
	v_mul_f32_e32 v22, v23, v193
	v_lshlrev_b32_e32 v23, 16, v191
	v_mul_f32_e32 v191, 0xbfb8aa3b, v23
	v_exp_f32_e32 v191, v191
	v_mul_f32_e32 v22, v127, v22
	v_add_f32_e32 v191, 1.0, v191
	v_div_scale_f32 v192, s[22:23], v191, v191, v23
	v_rcp_f32_e32 v193, v192
	s_nop 0
	v_fma_f32 v196, -v192, v193, 1.0
	v_fmac_f32_e32 v193, v196, v193
	v_div_scale_f32 v196, vcc, v23, v191, v23
	v_mul_f32_e32 v197, v196, v193
	v_fma_f32 v198, -v192, v197, v196
	v_fmac_f32_e32 v197, v198, v193
	v_fma_f32 v192, -v192, v197, v196
	v_div_fmas_f32 v192, v192, v193, v197
	v_div_fixup_f32 v23, v192, v191, v23
	v_mul_f32_e32 v22, v23, v22
	v_bfe_u32 v23, v22, 16, 1
	v_add3_u32 v22, v22, v23, s21
	global_store_short_d16_hi v[194:195], v22, off offset:128
	v_lshlrev_b32_e32 v22, 16, v167
	v_lshlrev_b32_e32 v23, 16, v190
	v_lshlrev_b32_e32 v190, 16, v165
	v_lshlrev_b32_e32 v191, 16, v166
	v_pk_add_f32 v[22:23], v[22:23], v[190:191]
	v_mul_f32_e32 v190, 0xbfb8aa3b, v164
	v_pk_mul_f32 v[166:167], v[22:23], v[22:23]
	v_exp_f32_e32 v190, v190
	v_add_f32_e32 v165, v166, v167
	v_mov_b32_e32 v166, v129
	v_add_f32_e32 v190, 1.0, v190
	v_add_f32_dpp v165, v165, v165 quad_perm:[1,0,3,2] row_mask:0xf bank_mask:0xf bound_ctrl:1
	v_div_scale_f32 v191, s[22:23], v190, v190, v164
	s_nop 0
	v_add_f32_dpp v165, v165, v165 quad_perm:[2,3,0,1] row_mask:0xf bank_mask:0xf bound_ctrl:1
	v_rcp_f32_e32 v192, v191
	s_nop 0
	v_add_f32_dpp v165, v165, v165 row_half_mirror row_mask:0xf bank_mask:0xf bound_ctrl:1
	v_fma_f32 v193, -v191, v192, 1.0
	s_nop 0
	v_add_f32_dpp v165, v165, v165 row_mirror row_mask:0xf bank_mask:0xf bound_ctrl:1
	v_fmac_f32_e32 v192, v193, v192
	s_nop 0
	v_mov_b32_dpp v166, v165 row_bcast:15 row_mask:0xa bank_mask:0xf
	v_add_f32_e32 v165, v165, v166
	v_mov_b32_e32 v166, v129
	s_nop 1
	v_mov_b32_dpp v166, v165 row_bcast:31 row_mask:0xc bank_mask:0xf
	v_add_f32_e32 v165, v165, v166
	s_nop 0
	v_readlane_b32 s20, v165, 63
	s_nop 1
	v_fma_f32 v165, s20, v182, v169
	v_cmp_gt_f32_e32 vcc, s33, v165
	v_mul_f32_e32 v166, 0x4b800000, v165
	s_nop 0
	v_cndmask_b32_e32 v165, v165, v166, vcc
	v_rsq_f32_e32 v165, v165
	s_nop 0
	v_mul_f32_e32 v166, 0x45800000, v165
	v_cndmask_b32_e32 v165, v165, v166, vcc
	v_div_scale_f32 v193, vcc, v164, v190, v164
	v_mul_f32_e32 v194, v193, v192
	v_fma_f32 v195, -v191, v194, v193
	v_fmac_f32_e32 v194, v195, v192
	v_fma_f32 v191, -v191, v194, v193
	v_mul_f32_e32 v22, v22, v165
	v_div_fmas_f32 v191, v191, v192, v194
	v_mul_f32_e32 v22, v126, v22
	v_div_fixup_f32 v164, v191, v190, v164
	v_mul_f32_e32 v22, v164, v22
	v_bfe_u32 v164, v22, 16, 1
	v_lshl_add_u64 v[166:167], v[12:13], 0, s[42:43]
	v_add3_u32 v22, v22, v164, s21
	global_store_short_d16_hi v[166:167], v22, off
	v_mul_f32_e32 v22, v23, v165
	v_lshlrev_b32_e32 v23, 16, v163
	v_mul_f32_e32 v163, 0xbfb8aa3b, v23
	v_exp_f32_e32 v163, v163
	v_mul_f32_e32 v22, v127, v22
	v_add_f32_e32 v163, 1.0, v163
	v_div_scale_f32 v164, s[22:23], v163, v163, v23
	v_rcp_f32_e32 v165, v164
	s_nop 0
	v_fma_f32 v190, -v164, v165, 1.0
	v_fmac_f32_e32 v165, v190, v165
	v_div_scale_f32 v190, vcc, v23, v163, v23
	v_mul_f32_e32 v191, v190, v165
	v_fma_f32 v192, -v164, v191, v190
	v_fmac_f32_e32 v191, v192, v165
	v_fma_f32 v164, -v164, v191, v190
	v_div_fmas_f32 v164, v164, v165, v191
	v_div_fixup_f32 v23, v164, v163, v23
	v_mul_f32_e32 v22, v23, v22
	v_bfe_u32 v23, v22, 16, 1
	v_add3_u32 v22, v22, v23, s21
	global_store_short_d16_hi v[166:167], v22, off offset:128
	v_lshlrev_b32_e32 v22, 16, v161
	v_lshlrev_b32_e32 v23, 16, v162
	v_lshlrev_b32_e32 v162, 16, v159
	v_lshlrev_b32_e32 v163, 16, v160
	v_pk_add_f32 v[22:23], v[22:23], v[162:163]
	v_mul_f32_e32 v162, 0xbfb8aa3b, v158
	v_pk_mul_f32 v[160:161], v[22:23], v[22:23]
	v_exp_f32_e32 v162, v162
	v_add_f32_e32 v159, v160, v161
	v_mov_b32_e32 v160, v129
	v_add_f32_e32 v162, 1.0, v162
	v_add_f32_dpp v159, v159, v159 quad_perm:[1,0,3,2] row_mask:0xf bank_mask:0xf bound_ctrl:1
	s_nop 1
	v_add_f32_dpp v159, v159, v159 quad_perm:[2,3,0,1] row_mask:0xf bank_mask:0xf bound_ctrl:1
	s_nop 1
	v_add_f32_dpp v159, v159, v159 row_half_mirror row_mask:0xf bank_mask:0xf bound_ctrl:1
	s_nop 1
	v_add_f32_dpp v159, v159, v159 row_mirror row_mask:0xf bank_mask:0xf bound_ctrl:1
	s_nop 1
	v_mov_b32_dpp v160, v159 row_bcast:15 row_mask:0xa bank_mask:0xf
	v_add_f32_e32 v159, v159, v160
	v_mov_b32_e32 v160, v129
	s_nop 1
	v_mov_b32_dpp v160, v159 row_bcast:31 row_mask:0xc bank_mask:0xf
	v_add_f32_e32 v159, v159, v160
	s_nop 0
	v_readlane_b32 s20, v159, 63
	s_nop 1
	v_fma_f32 v159, s20, v182, v169
	v_cmp_gt_f32_e32 vcc, s33, v159
	v_mul_f32_e32 v160, 0x4b800000, v159
	s_nop 0
	v_cndmask_b32_e32 v159, v159, v160, vcc
	v_rsq_f32_e32 v159, v159
	s_nop 0
; __device__ __forceinline__ float bf2f(u16 v) { return __uint_as_float(((unsigned)v) << 16); }
; __device__ __forceinline__ float siluf_(float x) { return x / (1.f + __expf(-x)); }
; __device__ void phase_combine(const P& p, int l, int ntok, float* lds) {
;     ...
; #pragma unroll
;       for (int i = 0; i < 4; ++i) {
;         int row = r0 + i0 + i;
;         float o0 = bf2f((u16)a0[i]) + bf2f((u16)a1[i]), o1 = bf2f((u16)a2[i]) + bf2f((u16)a3[i]);
;         float ss = wave_sum_b(o0 * o0 + o1 * o1);
;         float rstd = rsqrtf(ss * (1.f / 128.f) + 1e-6f);
;         u16* dst = p.nbuf + (size_t)row * D + mixer * 512 + hh * 128 + lane;
;         dst[0] = f2bf(o0 * rstd * ng0 * siluf_(bf2f((u16)g0r[i])));
;         dst[64] = f2bf(o1 * rstd * ng1 * siluf_(bf2f((u16)g1r[i])));
;       }
; #pragma unroll
;       for (int i = 0; i < 4; ++i) {
;         int tr = (tb + i0 + i) & (RL - 1);
;         float up = tr != 0 ? bf2f((u16)ucc[i]) * bf2f((u16)uch[i]) : 0.f;
;         float uc = bf2f((u16)ucc[i + 1]) * bf2f((u16)uch[i + 1]);
;         float un = tr != RL - 1 ? bf2f((u16)ucc[i + 2]) * bf2f((u16)uch[i + 2]) : 0.f;
;         float cv = scw0 * up + scw1 * uc + scw2 * un;
;         p.nbuf[(size_t)(r0 + i0 + i) * D + 1024 + tid] = f2bf(bf2f((u16)cbr[i]) * cv);
;       }
	v_mul_f32_e32 v160, 0x45800000, v159
	v_cndmask_b32_e32 v159, v159, v160, vcc
	v_lshl_add_u64 v[160:161], v[12:13], 0, s[2:3]
	v_div_scale_f32 v163, s[2:3], v162, v162, v158
	v_rcp_f32_e32 v164, v163
	v_mul_f32_e32 v22, v22, v159
	v_mul_f32_e32 v22, v126, v22
	v_fma_f32 v165, -v163, v164, 1.0
	v_fmac_f32_e32 v164, v165, v164
	v_div_scale_f32 v165, vcc, v158, v162, v158
	v_mul_f32_e32 v166, v165, v164
	v_fma_f32 v167, -v163, v166, v165
	v_fmac_f32_e32 v166, v167, v164
	v_fma_f32 v163, -v163, v166, v165
	v_div_fmas_f32 v163, v163, v164, v166
	v_div_fixup_f32 v158, v163, v162, v158
	v_mul_f32_e32 v22, v158, v22
	v_bfe_u32 v158, v22, 16, 1
	v_add3_u32 v22, v22, v158, s21
	global_store_short_d16_hi v[160:161], v22, off
	v_mul_f32_e32 v22, v23, v159
	v_lshlrev_b32_e32 v23, 16, v157
	v_mul_f32_e32 v157, 0xbfb8aa3b, v23
	v_exp_f32_e32 v157, v157
	v_mul_f32_e32 v22, v127, v22
	v_add_f32_e32 v157, 1.0, v157
	v_div_scale_f32 v158, s[2:3], v157, v157, v23
	v_rcp_f32_e32 v159, v158
	s_nop 0
	v_fma_f32 v162, -v158, v159, 1.0
	v_fmac_f32_e32 v159, v162, v159
	v_div_scale_f32 v162, vcc, v23, v157, v23
	v_mul_f32_e32 v163, v162, v159
	v_fma_f32 v164, -v158, v163, v162
	v_fmac_f32_e32 v163, v164, v159
	v_fma_f32 v158, -v158, v163, v162
	v_div_fmas_f32 v158, v158, v159, v163
	v_div_fixup_f32 v23, v158, v157, v23
	v_mul_f32_e32 v22, v23, v22
	v_bfe_u32 v23, v22, 16, 1
	v_add3_u32 v22, v22, v23, s21
	global_store_short_d16_hi v[160:161], v22, off offset:128
	v_lshlrev_b32_e32 v22, 16, v155
	v_lshlrev_b32_e32 v23, 16, v156
	v_lshlrev_b32_e32 v156, 16, v153
	v_lshlrev_b32_e32 v157, 16, v154
	v_pk_add_f32 v[22:23], v[22:23], v[156:157]
	v_mul_f32_e32 v156, 0xbfb8aa3b, v152
	v_pk_mul_f32 v[154:155], v[22:23], v[22:23]
	v_exp_f32_e32 v156, v156
	v_add_f32_e32 v153, v154, v155
	v_mov_b32_e32 v154, v129
	v_add_f32_e32 v156, 1.0, v156
	v_add_f32_dpp v153, v153, v153 quad_perm:[1,0,3,2] row_mask:0xf bank_mask:0xf bound_ctrl:1
	s_nop 1
	v_add_f32_dpp v153, v153, v153 quad_perm:[2,3,0,1] row_mask:0xf bank_mask:0xf bound_ctrl:1
	s_nop 1
	v_add_f32_dpp v153, v153, v153 row_half_mirror row_mask:0xf bank_mask:0xf bound_ctrl:1
	s_nop 1
	v_add_f32_dpp v153, v153, v153 row_mirror row_mask:0xf bank_mask:0xf bound_ctrl:1
	s_nop 1
	v_mov_b32_dpp v154, v153 row_bcast:15 row_mask:0xa bank_mask:0xf
	v_add_f32_e32 v153, v153, v154
	v_mov_b32_e32 v154, v129
	s_nop 1
	v_mov_b32_dpp v154, v153 row_bcast:31 row_mask:0xc bank_mask:0xf
	v_add_f32_e32 v153, v153, v154
	s_nop 0
	v_readlane_b32 s2, v153, 63
	s_nop 1
	v_fma_f32 v153, s2, v182, v169
	v_cmp_gt_f32_e32 vcc, s33, v153
	v_mul_f32_e32 v154, 0x4b800000, v153
	s_nop 0
	v_cndmask_b32_e32 v153, v153, v154, vcc
	v_rsq_f32_e32 v153, v153
	s_nop 0
	v_mul_f32_e32 v154, 0x45800000, v153
	v_cndmask_b32_e32 v153, v153, v154, vcc
	v_lshl_add_u64 v[154:155], v[12:13], 0, s[0:1]
	v_div_scale_f32 v157, s[0:1], v156, v156, v152
	v_rcp_f32_e32 v158, v157
	v_mul_f32_e32 v22, v22, v153
	v_mul_f32_e32 v22, v126, v22
	v_fma_f32 v159, -v157, v158, 1.0
	v_fmac_f32_e32 v158, v159, v158
	v_div_scale_f32 v159, vcc, v152, v156, v152
	v_mul_f32_e32 v160, v159, v158
	v_fma_f32 v161, -v157, v160, v159
	v_fmac_f32_e32 v160, v161, v158
	v_fma_f32 v157, -v157, v160, v159
	v_div_fmas_f32 v157, v157, v158, v160
	v_div_fixup_f32 v152, v157, v156, v152
	v_mul_f32_e32 v22, v152, v22
	v_bfe_u32 v152, v22, 16, 1
	v_add3_u32 v22, v22, v152, s21
	global_store_short_d16_hi v[154:155], v22, off
	v_mul_f32_e32 v22, v23, v153
	v_lshlrev_b32_e32 v23, 16, v149
	v_mul_f32_e32 v149, 0xbfb8aa3b, v23
	v_exp_f32_e32 v149, v149
	v_mul_f32_e32 v22, v127, v22
	v_add_f32_e32 v149, 1.0, v149
	v_div_scale_f32 v152, s[0:1], v149, v149, v23
	v_rcp_f32_e32 v153, v152
	s_and_b32 s0, s46, s58
	s_cmp_lg_u32 s0, 0
	v_fma_f32 v156, -v152, v153, 1.0
	v_fmac_f32_e32 v153, v156, v153
	v_div_scale_f32 v156, vcc, v23, v149, v23
	v_mul_f32_e32 v157, v156, v153
	v_fma_f32 v158, -v152, v157, v156
	v_fmac_f32_e32 v157, v158, v153
	v_fma_f32 v152, -v152, v157, v156
	v_div_fmas_f32 v152, v152, v153, v157
	v_div_fixup_f32 v23, v152, v149, v23
	v_mul_f32_e32 v22, v23, v22
	v_bfe_u32 v23, v22, 16, 1
	v_add3_u32 v22, v22, v23, s21
	global_store_short_d16_hi v[154:155], v22, off offset:128
	v_lshlrev_b32_e32 v22, 16, v139
	v_lshlrev_b32_e32 v23, 16, v140
	v_mul_f32_e32 v22, v22, v23
	s_cselect_b64 vcc, -1, 0
	v_cndmask_b32_e32 v22, 0, v22, vcc
	v_lshlrev_b32_e32 v23, 16, v147
	v_lshlrev_b32_e32 v139, 16, v148
	v_mul_f32_e32 v23, v23, v139
	v_lshlrev_b32_e32 v139, 16, v150
	v_lshlrev_b32_e32 v140, 16, v151
	v_mul_f32_e32 v22, v123, v22
	v_mul_f32_e32 v139, v139, v140
	v_fmac_f32_e32 v22, v124, v23
	v_fmac_f32_e32 v22, v125, v139
	v_mul_f32_e32 v22, v22, v138
	v_bfe_u32 v138, v22, 16, 1
	v_add3_u32 v22, v22, v138, s21
	global_store_short_d16_hi v[18:19], v22, off offset:2048
	v_lshlrev_b32_e32 v18, 16, v145
	v_lshlrev_b32_e32 v19, 16, v146
	v_mul_f32_e32 v18, v18, v19
	v_mul_f32_e32 v19, v124, v139
	v_fmac_f32_e32 v19, v123, v23
	v_fmac_f32_e32 v19, v125, v18
	v_lshlrev_b32_e32 v22, 16, v137
	v_mul_f32_e32 v19, v19, v22
	v_bfe_u32 v22, v19, 16, 1
	v_add3_u32 v19, v19, v22, s21
	global_store_short_d16_hi v[20:21], v19, off offset:2048
	v_lshlrev_b32_e32 v19, 16, v143
	v_lshlrev_b32_e32 v20, 16, v144
	v_mul_f32_e32 v19, v19, v20
	v_mul_f32_e32 v20, v124, v18
	v_fmac_f32_e32 v20, v123, v139
	v_fmac_f32_e32 v20, v125, v19
	v_lshlrev_b32_e32 v21, 16, v136
	v_mul_f32_e32 v20, v20, v21
	v_bfe_u32 v21, v20, 16, 1
	v_add3_u32 v20, v20, v21, s21
	s_and_b32 s0, s36, s58
	global_store_short_d16_hi v[2:3], v20, off offset:2048
	v_lshlrev_b32_e32 v2, 16, v141
	v_lshlrev_b32_e32 v3, 16, v142
	s_cmp_lg_u32 s0, s58
	v_mul_f32_e32 v2, v2, v3
	s_cselect_b64 vcc, -1, 0
	v_mul_f32_e32 v3, v124, v19
	v_cndmask_b32_e32 v2, 0, v2, vcc
	v_fmac_f32_e32 v3, v123, v18
	v_fmac_f32_e32 v3, v125, v2
	v_lshlrev_b32_e32 v2, 16, v135
	v_mul_f32_e32 v2, v3, v2
	v_bfe_u32 v3, v2, 16, 1
	s_add_i32 s0, s60, 4
	v_add3_u32 v2, v2, v3, s21
	s_cmp_gt_u32 s60, 11
	s_mov_b32 s60, s0
	global_store_short_d16_hi v[0:1], v2, off offset:2048
	s_cbranch_scc0 .LBB0_94
	v_readlane_b32 s0, v240, 4
	v_readlane_b32 s1, v240, 5
	s_load_dword s0, s[0:1], 0x0
	s_movk_i32 s33, 0x3600
	s_waitcnt lgkmcnt(0)
	s_add_i32 s55, s0, s55
	s_cmp_ge_i32 s55, s72
	s_cbranch_scc0 .LBB0_90

; #define LBAR() do { asm volatile("s_waitcnt lgkmcnt(0)" ::: "memory"); __builtin_amdgcn_s_barrier(); asm volatile("" ::: "memory"); } while (0)
; #define LAS __attribute__((address_space(3)))
; #define GL_LDV(V, j_) do { \
;     V.f0 = L128(bq, (j_) * GL_VB); V.f1 = L128(bq, (j_) * GL_VB + 16); V.k0 = L128(bq, (j_) * GL_VB + 256); V.k1 = L128(bq, (j_) * GL_VB + 272); \
;     V.q0 = L128(bq, (j_) * GL_VB + 512); V.q1 = L128(bq, (j_) * GL_VB + 528); V.vv = L32(bv, (j_) * GL_VB + GL_OFF_V); V.kq = L32(bc, (j_) * GL_VB + GL_OFF_S); } while (0)
; #define GL_PIN(V) asm volatile("" : "+v"(V.f0), "+v"(V.f1), "+v"(V.k0), "+v"(V.k1), "+v"(V.q0), "+v"(V.q1), "+v"(V.vv), "+v"(V.kq), "+v"(S2[0]), "+v"(S2[1]), "+v"(S2[2]), "+v"(S2[3]))
; #define GL_2(jA, jB) GL_LDV(B, jA + 1); __builtin_amdgcn_sched_barrier(0); GL_STEP(A, jA); GL_PIN(B); \
;                      GL_LDV(A, jB + 1); __builtin_amdgcn_sched_barrier(0); GL_STEP(B, jB); GL_PIN(A);
; template <int NW>
; __device__ void scan_gla(const P& p, int l, int b, int h, int dir, int part, LAS char* lds) {
;     ...
;   gl_load<TPW, NCOL>(p, b, ch, vch, lane, dir, 0, wv, R);
;   GL_PREP(0);
;   gl_load<TPW, NCOL>(p, b, ch, vch, lane, dir, 1, wv, R);
;   LBAR();
;   for (int g = 0; g < NCHK; ++g) {
;     LAS char* vbuf = lds + (g & 1) * TC * GL_VB;
;     LAS float* obuf = (LAS float*)(lds + GL_OFF_Y + (g & 1) * TC * NCOL * 4);
;     {
;       GlVec A, B;
;       LAS char* bq = vbuf + dq * 32; LAS char* bv = vbuf + col * 4; LAS char* bc = vbuf;
;       GL_LDV(A, 0); GL_PIN(A);
; #pragma unroll 1
;       for (int s8 = 0; s8 < TC; s8 += 8) {
;         float ykeep = 0.f;
;         GL_2(0, 1) GL_2(2, 3) GL_2(4, 5) GL_2(6, 7)
.LBB0_171:
	v_add_u32_e32 v92, 0x15400, v89
	v_add_u32_e32 v93, 0x15400, v90
	v_add_u32_e32 v94, 0x15400, v88
	ds_read_b32 v121, v94 offset:1808
	ds_read_b32 v120, v93 offset:1680
	ds_read_b128 v[96:99], v92 offset:1440
	ds_read_b128 v[100:103], v92 offset:1424
	ds_read_b128 v[104:107], v92 offset:1184
	ds_read_b128 v[108:111], v92 offset:1168
	ds_read_b128 v[112:115], v92 offset:928
	ds_read_b128 v[116:119], v92 offset:912
	v_pk_mul_f32 v[22:23], v[22:23], v[30:31]
	v_pk_mul_f32 v[4:5], v[4:5], v[32:33]
	v_pk_fma_f32 v[20:21], v[20:21], v[28:29], v[22:23]
	s_nop 0
	v_pk_fma_f32 v[12:13], v[12:13], v[32:33], v[20:21]
	v_pk_fma_f32 v[32:33], v[0:1], v[36:37], v[4:5] op_sel_hi:[1,0,1]
	v_pk_fma_f32 v[12:13], v[14:15], v[34:35], v[12:13]
	v_pk_mul_f32 v[0:1], v[6:7], v[34:35]
	v_pk_mul_f32 v[14:15], v[16:17], v[28:29]
	v_pk_fma_f32 v[34:35], v[2:3], v[36:37], v[0:1] op_sel_hi:[1,0,1]
	v_add_f32_e32 v0, v12, v13
	v_pk_fma_f32 v[28:29], v[8:9], v[36:37], v[14:15] op_sel_hi:[1,0,1]
	v_pk_mul_f32 v[8:9], v[18:19], v[30:31]
	v_add_f32_dpp v0, v0, v0 quad_perm:[1,0,3,2] row_mask:0xf bank_mask:0xf bound_ctrl:1
	v_pk_fma_f32 v[30:31], v[10:11], v[36:37], v[8:9] op_sel_hi:[1,0,1]
	s_nop 0
	v_add_f32_dpp v0, v0, v0 quad_perm:[2,3,0,1] row_mask:0xf bank_mask:0xf bound_ctrl:1
	s_nop 1
	v_add_f32_dpp v0, v0, v0 row_half_mirror row_mask:0xf bank_mask:0xf bound_ctrl:1
	v_fmac_f32_e32 v0, v36, v95
	v_cndmask_b32_e64 v95, 0, v0, s[42:43]
	s_waitcnt lgkmcnt(0)
	ds_read_b32 v122, v94 offset:2720
	ds_read_b32 v36, v93 offset:2592
	ds_read_b128 v[0:3], v92 offset:2352
	ds_read_b128 v[4:7], v92 offset:2336
	ds_read_b128 v[8:11], v92 offset:2096
	ds_read_b128 v[12:15], v92 offset:2080
	ds_read_b128 v[16:19], v92 offset:1840
	ds_read_b128 v[20:23], v92 offset:1824
	v_pk_mul_f32 v[102:103], v[30:31], v[102:103]
	s_nop 0
	v_pk_fma_f32 v[100:101], v[28:29], v[100:101], v[102:103]
	s_nop 0
	v_pk_fma_f32 v[96:97], v[32:33], v[96:97], v[100:101]
	s_nop 0
	v_pk_fma_f32 v[96:97], v[34:35], v[98:99], v[96:97]
	v_pk_mul_f32 v[98:99], v[108:109], v[120:121] op_sel_hi:[1,0]
	s_nop 0
	v_pk_fma_f32 v[116:117], v[28:29], v[116:117], v[98:99]
	v_pk_mul_f32 v[28:29], v[110:111], v[120:121] op_sel_hi:[1,0]
	s_nop 0
	v_pk_fma_f32 v[118:119], v[30:31], v[118:119], v[28:29]
	v_pk_mul_f32 v[28:29], v[104:105], v[120:121] op_sel_hi:[1,0]
	s_nop 0
	v_pk_fma_f32 v[112:113], v[32:33], v[112:113], v[28:29]
	v_pk_mul_f32 v[28:29], v[106:107], v[120:121] op_sel_hi:[1,0]
	s_nop 0
	v_pk_fma_f32 v[114:115], v[34:35], v[114:115], v[28:29]
	v_add_f32_e32 v28, v96, v97
	s_nop 1
	v_add_f32_dpp v28, v28, v28 quad_perm:[1,0,3,2] row_mask:0xf bank_mask:0xf bound_ctrl:1
	s_waitcnt lgkmcnt(0)
	s_nop 0
	v_add_f32_dpp v28, v28, v28 quad_perm:[2,3,0,1] row_mask:0xf bank_mask:0xf bound_ctrl:1
	s_nop 1
	v_add_f32_dpp v28, v28, v28 row_half_mirror row_mask:0xf bank_mask:0xf bound_ctrl:1
	v_fmac_f32_e32 v28, v120, v121
	v_cndmask_b32_e64 v95, v95, v28, s[44:45]
	ds_read_b32 v121, v94 offset:3632
	ds_read_b32 v120, v93 offset:3504
	ds_read_b128 v[28:31], v92 offset:3264
	ds_read_b128 v[32:35], v92 offset:3248
	ds_read_b128 v[96:99], v92 offset:3008
	ds_read_b128 v[100:103], v92 offset:2992
	ds_read_b128 v[104:107], v92 offset:2752
	ds_read_b128 v[108:111], v92 offset:2736
	v_pk_mul_f32 v[6:7], v[118:119], v[6:7]
	s_nop 0
	v_pk_fma_f32 v[4:5], v[116:117], v[4:5], v[6:7]
	s_nop 0
	v_pk_fma_f32 v[0:1], v[112:113], v[0:1], v[4:5]
	s_nop 0
	v_pk_fma_f32 v[0:1], v[114:115], v[2:3], v[0:1]
	v_pk_mul_f32 v[2:3], v[12:13], v[36:37] op_sel_hi:[1,0]
	v_add_f32_e32 v0, v0, v1
	v_pk_fma_f32 v[116:117], v[116:117], v[20:21], v[2:3]
	v_pk_mul_f32 v[2:3], v[14:15], v[36:37] op_sel_hi:[1,0]
	v_add_f32_dpp v0, v0, v0 quad_perm:[1,0,3,2] row_mask:0xf bank_mask:0xf bound_ctrl:1
	v_pk_fma_f32 v[118:119], v[118:119], v[22:23], v[2:3]
	v_pk_mul_f32 v[2:3], v[8:9], v[36:37] op_sel_hi:[1,0]
	v_add_f32_dpp v0, v0, v0 quad_perm:[2,3,0,1] row_mask:0xf bank_mask:0xf bound_ctrl:1
	v_pk_fma_f32 v[112:113], v[112:113], v[16:17], v[2:3]
	v_pk_mul_f32 v[2:3], v[10:11], v[36:37] op_sel_hi:[1,0]
	v_add_f32_dpp v0, v0, v0 row_half_mirror row_mask:0xf bank_mask:0xf bound_ctrl:1
	v_fmac_f32_e32 v0, v36, v122
	v_pk_fma_f32 v[114:115], v[114:115], v[18:19], v[2:3]
	v_cndmask_b32_e64 v95, v95, v0, s[46:47]
	s_waitcnt lgkmcnt(0)
	ds_read_b32 v122, v94 offset:4544
	ds_read_b32 v36, v93 offset:4416
	ds_read_b128 v[0:3], v92 offset:4176
	ds_read_b128 v[4:7], v92 offset:4160
	ds_read_b128 v[8:11], v92 offset:3920
	ds_read_b128 v[12:15], v92 offset:3904
	ds_read_b128 v[16:19], v92 offset:3664
	ds_read_b128 v[20:23], v92 offset:3648
	v_pk_mul_f32 v[34:35], v[118:119], v[34:35]
	s_nop 0
	v_pk_fma_f32 v[32:33], v[116:117], v[32:33], v[34:35]
	s_nop 0
	v_pk_fma_f32 v[28:29], v[112:113], v[28:29], v[32:33]
	s_nop 0
	v_pk_fma_f32 v[28:29], v[114:115], v[30:31], v[28:29]
	v_pk_mul_f32 v[30:31], v[100:101], v[120:121] op_sel_hi:[1,0]
	v_add_f32_e32 v28, v28, v29
	v_pk_fma_f32 v[116:117], v[116:117], v[108:109], v[30:31]
	v_pk_mul_f32 v[30:31], v[102:103], v[120:121] op_sel_hi:[1,0]
	v_add_f32_dpp v28, v28, v28 quad_perm:[1,0,3,2] row_mask:0xf bank_mask:0xf bound_ctrl:1
	v_pk_fma_f32 v[118:119], v[118:119], v[110:111], v[30:31]
	v_pk_mul_f32 v[30:31], v[96:97], v[120:121] op_sel_hi:[1,0]
	v_add_f32_dpp v28, v28, v28 quad_perm:[2,3,0,1] row_mask:0xf bank_mask:0xf bound_ctrl:1
	v_pk_fma_f32 v[112:113], v[112:113], v[104:105], v[30:31]
	v_pk_mul_f32 v[30:31], v[98:99], v[120:121] op_sel_hi:[1,0]
	v_add_f32_dpp v28, v28, v28 row_half_mirror row_mask:0xf bank_mask:0xf bound_ctrl:1
	v_fmac_f32_e32 v28, v120, v121
	v_pk_fma_f32 v[114:115], v[114:115], v[106:107], v[30:31]
	v_cndmask_b32_e64 v95, v95, v28, s[48:49]
	s_waitcnt lgkmcnt(0)
; #define LBAR() do { asm volatile("s_waitcnt lgkmcnt(0)" ::: "memory"); __builtin_amdgcn_s_barrier(); asm volatile("" ::: "memory"); } while (0)
; #define LAS __attribute__((address_space(3)))
; #define GL_LDV(V, j_) do { \
;     V.f0 = L128(bq, (j_) * GL_VB); V.f1 = L128(bq, (j_) * GL_VB + 16); V.k0 = L128(bq, (j_) * GL_VB + 256); V.k1 = L128(bq, (j_) * GL_VB + 272); \
;     V.q0 = L128(bq, (j_) * GL_VB + 512); V.q1 = L128(bq, (j_) * GL_VB + 528); V.vv = L32(bv, (j_) * GL_VB + GL_OFF_V); V.kq = L32(bc, (j_) * GL_VB + GL_OFF_S); } while (0)
; #define GL_PIN(V) asm volatile("" : "+v"(V.f0), "+v"(V.f1), "+v"(V.k0), "+v"(V.k1), "+v"(V.q0), "+v"(V.q1), "+v"(V.vv), "+v"(V.kq), "+v"(S2[0]), "+v"(S2[1]), "+v"(S2[2]), "+v"(S2[3]))
; #define GL_2(jA, jB) GL_LDV(B, jA + 1); __builtin_amdgcn_sched_barrier(0); GL_STEP(A, jA); GL_PIN(B); \
;                      GL_LDV(A, jB + 1); __builtin_amdgcn_sched_barrier(0); GL_STEP(B, jB); GL_PIN(A);
; template <int NW>
; __device__ void scan_gla(const P& p, int l, int b, int h, int dir, int part, LAS char* lds) {
;     ...
;   gl_load<TPW, NCOL>(p, b, ch, vch, lane, dir, 0, wv, R);
;   GL_PREP(0);
;   gl_load<TPW, NCOL>(p, b, ch, vch, lane, dir, 1, wv, R);
;   LBAR();
;   for (int g = 0; g < NCHK; ++g) {
;     LAS char* vbuf = lds + (g & 1) * TC * GL_VB;
;     LAS float* obuf = (LAS float*)(lds + GL_OFF_Y + (g & 1) * TC * NCOL * 4);
;     {
;       GlVec A, B;
;       LAS char* bq = vbuf + dq * 32; LAS char* bv = vbuf + col * 4; LAS char* bc = vbuf;
;       GL_LDV(A, 0); GL_PIN(A);
; #pragma unroll 1
;       for (int s8 = 0; s8 < TC; s8 += 8) {
;         float ykeep = 0.f;
;         GL_2(0, 1) GL_2(2, 3) GL_2(4, 5) GL_2(6, 7)
;         obuf[(s8 + dq) * NCOL + col] = ykeep;
;         bq += 8 * GL_VB; bv += 8 * GL_VB; bc += 8 * GL_VB;
;       }
;     }
;     if (g + 1 < NCHK) GL_PREP(g + 1);
	ds_read_b32 v121, v94 offset:5456
	ds_read_b32 v120, v93 offset:5328
	ds_read_b128 v[28:31], v92 offset:5088
	ds_read_b128 v[32:35], v92 offset:5072
	ds_read_b128 v[96:99], v92 offset:4832
	ds_read_b128 v[100:103], v92 offset:4816
	ds_read_b128 v[104:107], v92 offset:4576
	ds_read_b128 v[108:111], v92 offset:4560
	v_pk_mul_f32 v[6:7], v[118:119], v[6:7]
	s_nop 0
	v_pk_fma_f32 v[4:5], v[116:117], v[4:5], v[6:7]
	s_nop 0
	v_pk_fma_f32 v[0:1], v[112:113], v[0:1], v[4:5]
	s_nop 0
	v_pk_fma_f32 v[0:1], v[114:115], v[2:3], v[0:1]
	v_pk_mul_f32 v[2:3], v[12:13], v[36:37] op_sel_hi:[1,0]
	v_add_f32_e32 v0, v0, v1
	v_pk_fma_f32 v[116:117], v[116:117], v[20:21], v[2:3]
	v_pk_mul_f32 v[2:3], v[14:15], v[36:37] op_sel_hi:[1,0]
	v_add_f32_dpp v0, v0, v0 quad_perm:[1,0,3,2] row_mask:0xf bank_mask:0xf bound_ctrl:1
	v_pk_fma_f32 v[118:119], v[118:119], v[22:23], v[2:3]
	v_pk_mul_f32 v[2:3], v[8:9], v[36:37] op_sel_hi:[1,0]
	v_add_f32_dpp v0, v0, v0 quad_perm:[2,3,0,1] row_mask:0xf bank_mask:0xf bound_ctrl:1
	v_pk_fma_f32 v[112:113], v[112:113], v[16:17], v[2:3]
	v_pk_mul_f32 v[2:3], v[10:11], v[36:37] op_sel_hi:[1,0]
	v_add_f32_dpp v0, v0, v0 row_half_mirror row_mask:0xf bank_mask:0xf bound_ctrl:1
	v_fmac_f32_e32 v0, v36, v122
	v_pk_fma_f32 v[114:115], v[114:115], v[18:19], v[2:3]
	v_cndmask_b32_e64 v36, v95, v0, s[50:51]
	s_waitcnt lgkmcnt(0)
	ds_read_b32 v123, v94 offset:6368
	ds_read_b32 v122, v93 offset:6240
	ds_read_b128 v[0:3], v92 offset:6000
	ds_read_b128 v[4:7], v92 offset:5984
	ds_read_b128 v[8:11], v92 offset:5744
	ds_read_b128 v[12:15], v92 offset:5728
	ds_read_b128 v[16:19], v92 offset:5488
	ds_read_b128 v[20:23], v92 offset:5472
	v_pk_mul_f32 v[34:35], v[118:119], v[34:35]
	s_nop 0
	v_pk_fma_f32 v[32:33], v[116:117], v[32:33], v[34:35]
	s_nop 0
	v_pk_fma_f32 v[28:29], v[112:113], v[28:29], v[32:33]
	s_nop 0
	v_pk_fma_f32 v[28:29], v[114:115], v[30:31], v[28:29]
	v_pk_mul_f32 v[30:31], v[100:101], v[120:121] op_sel_hi:[1,0]
	v_add_f32_e32 v28, v28, v29
	v_pk_fma_f32 v[116:117], v[116:117], v[108:109], v[30:31]
	v_pk_mul_f32 v[30:31], v[102:103], v[120:121] op_sel_hi:[1,0]
	v_add_f32_dpp v28, v28, v28 quad_perm:[1,0,3,2] row_mask:0xf bank_mask:0xf bound_ctrl:1
	v_pk_fma_f32 v[118:119], v[118:119], v[110:111], v[30:31]
	v_pk_mul_f32 v[30:31], v[96:97], v[120:121] op_sel_hi:[1,0]
	v_add_f32_dpp v28, v28, v28 quad_perm:[2,3,0,1] row_mask:0xf bank_mask:0xf bound_ctrl:1
	v_pk_fma_f32 v[112:113], v[112:113], v[104:105], v[30:31]
	v_pk_mul_f32 v[30:31], v[98:99], v[120:121] op_sel_hi:[1,0]
	v_add_f32_dpp v28, v28, v28 row_half_mirror row_mask:0xf bank_mask:0xf bound_ctrl:1
	v_fmac_f32_e32 v28, v120, v121
	v_pk_fma_f32 v[114:115], v[114:115], v[106:107], v[30:31]
	v_cndmask_b32_e64 v121, v36, v28, s[52:53]
	s_waitcnt lgkmcnt(0)
	ds_read_b32 v124, v94 offset:7280
	ds_read_b32 v120, v93 offset:7152
	ds_read_b128 v[28:31], v92 offset:6912
	ds_read_b128 v[32:35], v92 offset:6896
	ds_read_b128 v[96:99], v92 offset:6656
	ds_read_b128 v[100:103], v92 offset:6640
	ds_read_b128 v[104:107], v92 offset:6400
	ds_read_b128 v[108:111], v92 offset:6384
	v_pk_mul_f32 v[6:7], v[118:119], v[6:7]
	s_nop 0
	v_pk_fma_f32 v[4:5], v[116:117], v[4:5], v[6:7]
	s_nop 0
	v_pk_fma_f32 v[0:1], v[112:113], v[0:1], v[4:5]
	s_nop 0
	v_pk_fma_f32 v[0:1], v[114:115], v[2:3], v[0:1]
	v_pk_mul_f32 v[2:3], v[12:13], v[122:123] op_sel_hi:[1,0]
	v_add_f32_e32 v0, v0, v1
	v_pk_fma_f32 v[116:117], v[116:117], v[20:21], v[2:3]
	v_pk_mul_f32 v[2:3], v[14:15], v[122:123] op_sel_hi:[1,0]
	v_add_f32_dpp v125, v0, v0 quad_perm:[1,0,3,2] row_mask:0xf bank_mask:0xf bound_ctrl:1
	v_pk_fma_f32 v[118:119], v[118:119], v[22:23], v[2:3]
	v_pk_mul_f32 v[2:3], v[8:9], v[122:123] op_sel_hi:[1,0]
	s_nop 0
	v_pk_fma_f32 v[112:113], v[112:113], v[16:17], v[2:3]
	v_pk_mul_f32 v[2:3], v[10:11], v[122:123] op_sel_hi:[1,0]
	s_nop 0
	v_pk_fma_f32 v[114:115], v[114:115], v[18:19], v[2:3]
	s_waitcnt lgkmcnt(0)
	ds_read_b32 v95, v94 offset:8192
	ds_read_b32 v36, v93 offset:8064
	ds_read_b128 v[12:15], v92 offset:7824
	ds_read_b128 v[20:23], v92 offset:7808
	ds_read_b128 v[0:3], v92 offset:7568
	ds_read_b128 v[8:11], v92 offset:7552
	ds_read_b128 v[4:7], v92 offset:7312
	ds_read_b128 v[16:19], v92 offset:7296
	v_add_f32_dpp v92, v125, v125 quad_perm:[2,3,0,1] row_mask:0xf bank_mask:0xf bound_ctrl:1
	s_nop 1
	v_add_f32_dpp v92, v92, v92 row_half_mirror row_mask:0xf bank_mask:0xf bound_ctrl:1
	v_fmac_f32_e32 v92, v122, v123
	v_cndmask_b32_e64 v94, v121, v92, s[54:55]
	v_pk_mul_f32 v[34:35], v[118:119], v[34:35]
	s_add_i32 s30, s30, 8
	v_pk_fma_f32 v[32:33], v[116:117], v[32:33], v[34:35]
	v_pk_mul_f32 v[34:35], v[98:99], v[120:121] op_sel_hi:[1,0]
	v_pk_fma_f32 v[28:29], v[112:113], v[28:29], v[32:33]
	v_pk_mul_f32 v[32:33], v[96:97], v[120:121] op_sel_hi:[1,0]
	v_pk_fma_f32 v[92:93], v[114:115], v[30:31], v[28:29]
	v_pk_mul_f32 v[28:29], v[100:101], v[120:121] op_sel_hi:[1,0]
	v_add_f32_e32 v92, v92, v93
	v_pk_mul_f32 v[30:31], v[102:103], v[120:121] op_sel_hi:[1,0]
	v_pk_fma_f32 v[28:29], v[116:117], v[108:109], v[28:29]
	v_add_f32_dpp v92, v92, v92 quad_perm:[1,0,3,2] row_mask:0xf bank_mask:0xf bound_ctrl:1
	v_pk_fma_f32 v[30:31], v[118:119], v[110:111], v[30:31]
	v_pk_fma_f32 v[32:33], v[112:113], v[104:105], v[32:33]
	v_add_f32_dpp v92, v92, v92 quad_perm:[2,3,0,1] row_mask:0xf bank_mask:0xf bound_ctrl:1
	v_pk_fma_f32 v[34:35], v[114:115], v[106:107], v[34:35]
	v_add_u32_e32 v93, 0, v91
	v_add_f32_dpp v92, v92, v92 row_half_mirror row_mask:0xf bank_mask:0xf bound_ctrl:1
	v_fmac_f32_e32 v92, v120, v124
	v_cndmask_b32_e64 v92, v94, v92, s[56:57]
	v_add_u32_e32 v89, 0x1c80, v89
	v_add_u32_e32 v90, 0x1c80, v90
	v_add_u32_e32 v88, 0x1c80, v88
	v_add_u32_e32 v91, 0x400, v91
	s_cmp_gt_u32 s30, 23
	s_waitcnt lgkmcnt(0)
	ds_write_b32 v93, v92
	s_cbranch_scc0 .LBB0_171
	s_add_i32 s30, s27, 1
	s_cmpk_lg_i32 s27, 0x87
	s_cbranch_scc0 .LBB0_206
	s_lshl_b32 s20, s30, 5
	s_and_b32 s20, s20, 32
	s_mulk_i32 s20, 0x390
	s_waitcnt vmcnt(39)
	v_lshlrev_b32_e32 v0, 16, v42
	v_mul_f32_e32 v2, 0x3e000000, v0
	v_add_u32_e32 v0, s20, v41
	s_waitcnt vmcnt(38)
	v_lshlrev_b32_e32 v3, 16, v43
	v_lshl_add_u32 v1, v37, 2, v0
	s_waitcnt vmcnt(36)
	v_mul_f32_e32 v2, v45, v2
	ds_write2st64_b32 v1, v45, v3 offset1:1
	ds_write_b32 v1, v2 offset:512
	s_and_saveexec_b64 s[36:37], s[38:39]
	v_lshlrev_b32_e32 v2, 16, v44
	ds_write_b32 v1, v2 offset:768
	s_or_b64 exec, exec, s[36:37]
	s_and_saveexec_b64 s[36:37], s[40:41]
	s_cbranch_execz .LBB0_177
	s_waitcnt vmcnt(35)
	ds_write_b32 v0, v46 offset:896

; #define G_STAGE(bufoff, gbase, voff) do { _Pragma("unroll") for (int _i = 0; _i < 2; ++_i) \
;     __builtin_amdgcn_global_load_lds((const unsigned*)((const char*)(gbase) + (voff)[_i]), (LAS unsigned*)(lds + (bufoff) + ldsw + _i * 8192), 16, 0, 0); } while (0)
; #define G_LDA(dst, b, h) do { _Pragma("unroll") for (int m = 0; m < 4; ++m) _Pragma("unroll") for (int k = 0; k < 2; ++k) dst[m][k] = *(const LAS bf16x8*)(lds + G_SA(b, h) + aoff + m * 2048 + k * 1024); } while (0)
; #define G_LDB(dst, b, h) do { _Pragma("unroll") for (int n = 0; n < 2; ++n) _Pragma("unroll") for (int k = 0; k < 2; ++k) dst[n][k] = *(const LAS bf16x8*)(lds + G_SB(b, h) + boff + n * 2048 + k * 1024); } while (0)
; #define G_WAIT_V(n) asm volatile("s_waitcnt vmcnt(" #n ")" ::: "memory")
; #define G_WAIT_L(n) asm volatile("s_waitcnt lgkmcnt(" #n ")" ::: "memory")
; #define G_BAR __builtin_amdgcn_s_barrier()
; template <class Epi>
; __device__ __forceinline__ void gemm_phase(LAS unsigned char* lds, const u16* gA, const u16* gBt, int M, int N, int K, const Epi& E) {
;     ...
;     for (int t = 0; t < nt; t += 2) {
;       const bool last = (t == nt - 2);
;       const char* a1 = cA + (size_t)(t + 1) * kstep;
;       const char* a2 = last ? nA : cA + (size_t)(t + 2) * kstep; const char* b2 = last ? nB : cB + (size_t)(t + 2) * kstep;
;       const char* a3 = a2 + kstep; const char* b3 = b2 + kstep;
;       G_LDB(B0, 0, 0); G_SCHED; G_LDA(At, 0, 0); G_STAGE(G_SA(1, 1), a1 + hstep, voffA);
;       G_WAIT_L(8); G_BAR; G_WAIT_L(0); G_MMA(0, 0, At, B0); G_BAR; G_SCHED;
;       G_LDB(B1, 0, 1); G_STAGE(G_SB(0, 0), b2, voffB);
;       G_BAR; G_WAIT_L(0); G_MMA(0, 1, At, B1); G_BAR;
;       G_LDA(At, 0, 1); G_STAGE(G_SA(0, 0), a2, voffA);
;       G_BAR; G_WAIT_L(0); G_MMA(1, 0, At, B0); G_BAR; G_SCHED;
;       G_STAGE(G_SB(0, 1), b2 + hstep, voffB);
;       G_WAIT_V(6); G_BAR; G_MMA(1, 1, At, B1); G_BAR;
;       G_LDB(B0, 1, 0); G_SCHED; G_LDA(At, 1, 0); G_STAGE(G_SA(0, 1), a2 + hstep, voffA);
;       G_WAIT_L(8); G_BAR; G_WAIT_L(0); G_MMA(0, 0, At, B0); G_BAR; G_SCHED;
;       G_LDB(B1, 1, 1); G_STAGE(G_SB(1, 0), b3, voffB);
;       G_BAR; G_WAIT_L(0); G_MMA(0, 1, At, B1); G_BAR;
;       G_LDA(At, 1, 1); G_STAGE(G_SA(1, 0), a3, voffA);
;       G_BAR; G_WAIT_L(0); G_MMA(1, 0, At, B0); G_BAR; G_SCHED;
;       G_STAGE(G_SB(1, 1), b3 + hstep, voffB);
;       G_WAIT_V(6); G_BAR; G_MMA(1, 1, At, B1); G_BAR;
.LBB0_370:
	s_add_u32 s20, s42, 0xfff80080
	s_addc_u32 s22, s43, -1
	s_add_i32 s24, 0, 0x10000
	v_add_u32_e32 v156, s24, v145
	ds_read_b128 v[140:143], v156
	ds_read_b128 v[148:151], v156 offset:1024
	ds_read_b128 v[152:155], v156 offset:2048
	ds_read_b128 v[156:159], v156 offset:3072
	s_cmp_eq_u32 s58, 28
	s_cselect_b32 s47, s3, s22
	s_cselect_b32 s46, s54, s20
	s_cselect_b32 s45, s1, s57
	s_cselect_b32 s44, s55, s56
	v_lshl_add_u64 v[214:215], s[42:43], 0, v[136:137]
	s_add_i32 m0, s27, 0xc000
	ds_read_b128 v[160:163], v147
	ds_read_b128 v[164:167], v147 offset:1024
	ds_read_b128 v[190:193], v147 offset:2048
	ds_read_b128 v[194:197], v147 offset:3072
	ds_read_b128 v[198:201], v147 offset:4096
	ds_read_b128 v[202:205], v147 offset:5120
	ds_read_b128 v[206:209], v147 offset:6144
	ds_read_b128 v[210:213], v147 offset:7168
	global_load_lds_dwordx4 v[214:215], off
	v_lshl_add_u64 v[214:215], s[42:43], 0, v[138:139]
	s_add_i32 m0, s27, 0xe000
	s_nop 0
	global_load_lds_dwordx4 v[214:215], off
	s_waitcnt lgkmcnt(8)
	s_barrier
	s_waitcnt lgkmcnt(0)
	s_setprio 1
	s_waitcnt lgkmcnt(0)
	v_mfma_f32_16x16x32_bf16 v[124:127], v[140:143], v[160:163], v[124:127]
	v_mfma_f32_16x16x32_bf16 v[120:123], v[152:155], v[160:163], v[120:123]
	v_mfma_f32_16x16x32_bf16 v[112:115], v[140:143], v[190:193], v[112:115]
	v_mfma_f32_16x16x32_bf16 v[104:107], v[152:155], v[190:193], v[104:107]
	v_mfma_f32_16x16x32_bf16 v[96:99], v[140:143], v[198:201], v[96:99]
	v_mfma_f32_16x16x32_bf16 v[88:91], v[152:155], v[198:201], v[88:91]
	v_mfma_f32_16x16x32_bf16 v[80:83], v[140:143], v[206:209], v[80:83]
	v_mfma_f32_16x16x32_bf16 v[72:75], v[152:155], v[206:209], v[72:75]
	v_mfma_f32_16x16x32_bf16 v[124:127], v[148:151], v[164:167], v[124:127]
	v_mfma_f32_16x16x32_bf16 v[120:123], v[156:159], v[164:167], v[120:123]
	v_mfma_f32_16x16x32_bf16 v[112:115], v[148:151], v[194:197], v[112:115]
	v_mfma_f32_16x16x32_bf16 v[104:107], v[156:159], v[194:197], v[104:107]
	v_mfma_f32_16x16x32_bf16 v[96:99], v[148:151], v[202:205], v[96:99]
	v_mfma_f32_16x16x32_bf16 v[88:91], v[156:159], v[202:205], v[88:91]
	v_mfma_f32_16x16x32_bf16 v[80:83], v[148:151], v[210:213], v[80:83]
	v_mfma_f32_16x16x32_bf16 v[72:75], v[156:159], v[210:213], v[72:75]
	s_setprio 0
	s_barrier
	s_add_i32 s20, 0, 0x14000
	s_add_i32 s22, s24, s26
	v_add_u32_e32 v226, s20, v145
	v_lshl_add_u64 v[230:231], s[44:45], 0, v[128:129]
	s_mov_b32 m0, s22
	ds_read_b128 v[214:217], v226
	ds_read_b128 v[218:221], v226 offset:1024
	ds_read_b128 v[222:225], v226 offset:2048
	ds_read_b128 v[226:229], v226 offset:3072
	global_load_lds_dwordx4 v[230:231], off
	v_lshl_add_u64 v[232:233], s[44:45], 0, v[134:135]
	s_add_i32 m0, s22, 0x2000
	s_nop 0
	global_load_lds_dwordx4 v[232:233], off
	s_barrier
	s_waitcnt lgkmcnt(0)
	s_setprio 1
	s_waitcnt lgkmcnt(0)
	v_mfma_f32_16x16x32_bf16 v[116:119], v[214:217], v[160:163], v[116:119]
	v_mfma_f32_16x16x32_bf16 v[108:111], v[222:225], v[160:163], v[108:111]
	v_mfma_f32_16x16x32_bf16 v[100:103], v[214:217], v[190:193], v[100:103]
	v_mfma_f32_16x16x32_bf16 v[92:95], v[222:225], v[190:193], v[92:95]
	v_mfma_f32_16x16x32_bf16 v[84:87], v[214:217], v[198:201], v[84:87]
	v_mfma_f32_16x16x32_bf16 v[76:79], v[222:225], v[198:201], v[76:79]
	v_mfma_f32_16x16x32_bf16 v[68:71], v[214:217], v[206:209], v[68:71]
	v_mfma_f32_16x16x32_bf16 v[64:67], v[222:225], v[206:209], v[64:67]
	v_mfma_f32_16x16x32_bf16 v[116:119], v[218:221], v[164:167], v[116:119]
	v_mfma_f32_16x16x32_bf16 v[108:111], v[226:229], v[164:167], v[108:111]
	v_mfma_f32_16x16x32_bf16 v[100:103], v[218:221], v[194:197], v[100:103]
	v_mfma_f32_16x16x32_bf16 v[92:95], v[226:229], v[194:197], v[92:95]
	v_mfma_f32_16x16x32_bf16 v[84:87], v[218:221], v[202:205], v[84:87]
	v_mfma_f32_16x16x32_bf16 v[76:79], v[226:229], v[202:205], v[76:79]
	v_mfma_f32_16x16x32_bf16 v[68:71], v[218:221], v[210:213], v[68:71]
	v_mfma_f32_16x16x32_bf16 v[64:67], v[226:229], v[210:213], v[64:67]
	s_setprio 0
	s_mov_b32 m0, s27
	v_lshl_add_u64 v[234:235], s[46:47], 0, v[128:129]
	s_barrier
	ds_read_b128 v[160:163], v147 offset:16384
	ds_read_b128 v[164:167], v147 offset:17408
	ds_read_b128 v[190:193], v147 offset:18432
	ds_read_b128 v[194:197], v147 offset:19456
	ds_read_b128 v[198:201], v147 offset:20480
	ds_read_b128 v[202:205], v147 offset:21504
	ds_read_b128 v[206:209], v147 offset:22528
	ds_read_b128 v[210:213], v147 offset:23552
	global_load_lds_dwordx4 v[234:235], off
	v_lshl_add_u64 v[236:237], s[46:47], 0, v[134:135]
	s_mov_b32 m0, s28
	s_nop 0
	global_load_lds_dwordx4 v[236:237], off
	s_barrier
	s_waitcnt lgkmcnt(0)
	s_setprio 1
	s_waitcnt lgkmcnt(0)
	v_mfma_f32_16x16x32_bf16 v[60:63], v[140:143], v[160:163], v[60:63]
	v_mfma_f32_16x16x32_bf16 v[56:59], v[152:155], v[160:163], v[56:59]
	v_mfma_f32_16x16x32_bf16 v[48:51], v[140:143], v[190:193], v[48:51]
	v_mfma_f32_16x16x32_bf16 v[40:43], v[152:155], v[190:193], v[40:43]
	v_mfma_f32_16x16x32_bf16 v[32:35], v[140:143], v[198:201], v[32:35]
	v_mfma_f32_16x16x32_bf16 v[24:27], v[152:155], v[198:201], v[24:27]
	v_mfma_f32_16x16x32_bf16 v[16:19], v[140:143], v[206:209], v[16:19]
	v_mfma_f32_16x16x32_bf16 v[8:11], v[152:155], v[206:209], v[8:11]
	v_mfma_f32_16x16x32_bf16 v[60:63], v[148:151], v[164:167], v[60:63]
	v_mfma_f32_16x16x32_bf16 v[56:59], v[156:159], v[164:167], v[56:59]
	v_mfma_f32_16x16x32_bf16 v[48:51], v[148:151], v[194:197], v[48:51]
	v_mfma_f32_16x16x32_bf16 v[40:43], v[156:159], v[194:197], v[40:43]
	v_mfma_f32_16x16x32_bf16 v[32:35], v[148:151], v[202:205], v[32:35]
	v_mfma_f32_16x16x32_bf16 v[24:27], v[156:159], v[202:205], v[24:27]
	v_mfma_f32_16x16x32_bf16 v[16:19], v[148:151], v[210:213], v[16:19]
	v_mfma_f32_16x16x32_bf16 v[8:11], v[156:159], v[210:213], v[8:11]
	s_setprio 0
	s_barrier
; #define G_STAGE(bufoff, gbase, voff) do { _Pragma("unroll") for (int _i = 0; _i < 2; ++_i) \
;     __builtin_amdgcn_global_load_lds((const unsigned*)((const char*)(gbase) + (voff)[_i]), (LAS unsigned*)(lds + (bufoff) + ldsw + _i * 8192), 16, 0, 0); } while (0)
; #define G_LDA(dst, b, h) do { _Pragma("unroll") for (int m = 0; m < 4; ++m) _Pragma("unroll") for (int k = 0; k < 2; ++k) dst[m][k] = *(const LAS bf16x8*)(lds + G_SA(b, h) + aoff + m * 2048 + k * 1024); } while (0)
; #define G_LDB(dst, b, h) do { _Pragma("unroll") for (int n = 0; n < 2; ++n) _Pragma("unroll") for (int k = 0; k < 2; ++k) dst[n][k] = *(const LAS bf16x8*)(lds + G_SB(b, h) + boff + n * 2048 + k * 1024); } while (0)
; #define G_WAIT_V(n) asm volatile("s_waitcnt vmcnt(" #n ")" ::: "memory")
; #define G_WAIT_L(n) asm volatile("s_waitcnt lgkmcnt(" #n ")" ::: "memory")
; #define G_BAR __builtin_amdgcn_s_barrier()
; template <class Epi>
; __device__ __forceinline__ void gemm_phase(LAS unsigned char* lds, const u16* gA, const u16* gBt, int M, int N, int K, const Epi& E) {
;     ...
;     for (int t = 0; t < nt; t += 2) {
;       const bool last = (t == nt - 2);
;       const char* a1 = cA + (size_t)(t + 1) * kstep;
;       const char* a2 = last ? nA : cA + (size_t)(t + 2) * kstep; const char* b2 = last ? nB : cB + (size_t)(t + 2) * kstep;
;       const char* a3 = a2 + kstep; const char* b3 = b2 + kstep;
;       G_LDB(B0, 0, 0); G_SCHED; G_LDA(At, 0, 0); G_STAGE(G_SA(1, 1), a1 + hstep, voffA);
;       G_WAIT_L(8); G_BAR; G_WAIT_L(0); G_MMA(0, 0, At, B0); G_BAR; G_SCHED;
;       G_LDB(B1, 0, 1); G_STAGE(G_SB(0, 0), b2, voffB);
;       G_BAR; G_WAIT_L(0); G_MMA(0, 1, At, B1); G_BAR;
;       G_LDA(At, 0, 1); G_STAGE(G_SA(0, 0), a2, voffA);
;       G_BAR; G_WAIT_L(0); G_MMA(1, 0, At, B0); G_BAR; G_SCHED;
;       G_STAGE(G_SB(0, 1), b2 + hstep, voffB);
;       G_WAIT_V(6); G_BAR; G_MMA(1, 1, At, B1); G_BAR;
;       G_LDB(B0, 1, 0); G_SCHED; G_LDA(At, 1, 0); G_STAGE(G_SA(0, 1), a2 + hstep, voffA);
;       G_WAIT_L(8); G_BAR; G_WAIT_L(0); G_MMA(0, 0, At, B0); G_BAR; G_SCHED;
;       G_LDB(B1, 1, 1); G_STAGE(G_SB(1, 0), b3, voffB);
;       G_BAR; G_WAIT_L(0); G_MMA(0, 1, At, B1); G_BAR;
;       G_LDA(At, 1, 1); G_STAGE(G_SA(1, 0), a3, voffA);
;       G_BAR; G_WAIT_L(0); G_MMA(1, 0, At, B0); G_BAR; G_SCHED;
;       G_STAGE(G_SB(1, 1), b3 + hstep, voffB);
;       G_WAIT_V(6); G_BAR; G_MMA(1, 1, At, B1); G_BAR;
	s_add_u32 s24, s44, 0x80000
	s_addc_u32 s25, s45, 0
	s_add_i32 s20, s20, s26
	v_lshl_add_u64 v[140:141], s[24:25], 0, v[128:129]
	s_mov_b32 m0, s20
	s_nop 0
	global_load_lds_dwordx4 v[140:141], off
	v_lshl_add_u64 v[140:141], s[24:25], 0, v[134:135]
	s_add_i32 m0, s20, 0x2000
	s_nop 0
	global_load_lds_dwordx4 v[140:141], off
	s_waitcnt vmcnt(6)
	s_barrier
	s_setprio 1
	v_mfma_f32_16x16x32_bf16 v[52:55], v[214:217], v[160:163], v[52:55]
	v_mfma_f32_16x16x32_bf16 v[44:47], v[222:225], v[160:163], v[44:47]
	v_mfma_f32_16x16x32_bf16 v[36:39], v[214:217], v[190:193], v[36:39]
	v_mfma_f32_16x16x32_bf16 v[28:31], v[222:225], v[190:193], v[28:31]
	v_mfma_f32_16x16x32_bf16 v[20:23], v[214:217], v[198:201], v[20:23]
	v_mfma_f32_16x16x32_bf16 v[12:15], v[222:225], v[198:201], v[12:15]
	v_mfma_f32_16x16x32_bf16 v[4:7], v[214:217], v[206:209], v[4:7]
	v_mfma_f32_16x16x32_bf16 v[0:3], v[222:225], v[206:209], v[0:3]
	v_mfma_f32_16x16x32_bf16 v[52:55], v[218:221], v[164:167], v[52:55]
	v_mfma_f32_16x16x32_bf16 v[44:47], v[226:229], v[164:167], v[44:47]
	v_mfma_f32_16x16x32_bf16 v[36:39], v[218:221], v[194:197], v[36:39]
	v_mfma_f32_16x16x32_bf16 v[28:31], v[226:229], v[194:197], v[28:31]
	v_mfma_f32_16x16x32_bf16 v[20:23], v[218:221], v[202:205], v[20:23]
	v_mfma_f32_16x16x32_bf16 v[12:15], v[226:229], v[202:205], v[12:15]
	v_mfma_f32_16x16x32_bf16 v[4:7], v[218:221], v[210:213], v[4:7]
	v_mfma_f32_16x16x32_bf16 v[0:3], v[226:229], v[210:213], v[0:3]
	s_setprio 0
	s_add_i32 s20, 0, 0x18000
	v_add_u32_e32 v156, s20, v145
	s_barrier
	ds_read_b128 v[140:143], v156
	ds_read_b128 v[148:151], v156 offset:1024
	ds_read_b128 v[152:155], v156 offset:2048
	ds_read_b128 v[156:159], v156 offset:3072
	s_add_u32 s24, s46, 0x80000
	s_addc_u32 s25, s47, 0
	s_mov_b32 m0, s33
	v_lshl_add_u64 v[214:215], s[24:25], 0, v[128:129]
	ds_read_b128 v[160:163], v147 offset:32768
	ds_read_b128 v[164:167], v147 offset:33792
	ds_read_b128 v[190:193], v147 offset:34816
	ds_read_b128 v[194:197], v147 offset:35840
	ds_read_b128 v[198:201], v147 offset:36864
	ds_read_b128 v[202:205], v147 offset:37888
	ds_read_b128 v[206:209], v147 offset:38912
	ds_read_b128 v[210:213], v147 offset:39936
	global_load_lds_dwordx4 v[214:215], off
	v_lshl_add_u64 v[214:215], s[24:25], 0, v[134:135]
	s_mov_b32 m0, s48
	s_nop 0
	global_load_lds_dwordx4 v[214:215], off
	s_waitcnt lgkmcnt(8)
	s_barrier
	s_waitcnt lgkmcnt(0)
	s_setprio 1
	s_waitcnt lgkmcnt(0)
	v_mfma_f32_16x16x32_bf16 v[124:127], v[140:143], v[160:163], v[124:127]
	v_mfma_f32_16x16x32_bf16 v[120:123], v[152:155], v[160:163], v[120:123]
	v_mfma_f32_16x16x32_bf16 v[112:115], v[140:143], v[190:193], v[112:115]
	v_mfma_f32_16x16x32_bf16 v[104:107], v[152:155], v[190:193], v[104:107]
	v_mfma_f32_16x16x32_bf16 v[96:99], v[140:143], v[198:201], v[96:99]
	v_mfma_f32_16x16x32_bf16 v[88:91], v[152:155], v[198:201], v[88:91]
	v_mfma_f32_16x16x32_bf16 v[80:83], v[140:143], v[206:209], v[80:83]
	v_mfma_f32_16x16x32_bf16 v[72:75], v[152:155], v[206:209], v[72:75]
	v_mfma_f32_16x16x32_bf16 v[124:127], v[148:151], v[164:167], v[124:127]
	v_mfma_f32_16x16x32_bf16 v[120:123], v[156:159], v[164:167], v[120:123]
	v_mfma_f32_16x16x32_bf16 v[112:115], v[148:151], v[194:197], v[112:115]
	v_mfma_f32_16x16x32_bf16 v[104:107], v[156:159], v[194:197], v[104:107]
	v_mfma_f32_16x16x32_bf16 v[96:99], v[148:151], v[202:205], v[96:99]
	v_mfma_f32_16x16x32_bf16 v[88:91], v[156:159], v[202:205], v[88:91]
	v_mfma_f32_16x16x32_bf16 v[80:83], v[148:151], v[210:213], v[80:83]
	v_mfma_f32_16x16x32_bf16 v[72:75], v[156:159], v[210:213], v[72:75]
	s_setprio 0
	s_barrier
	s_add_i32 s22, 0, 0x1c000
	s_add_i32 s20, s20, s26
	v_add_u32_e32 v226, s22, v145
	v_lshl_add_u64 v[230:231], v[230:231], 0, s[34:35]
	s_mov_b32 m0, s20
	ds_read_b128 v[214:217], v226
	ds_read_b128 v[218:221], v226 offset:1024
	ds_read_b128 v[222:225], v226 offset:2048
	ds_read_b128 v[226:229], v226 offset:3072
	global_load_lds_dwordx4 v[230:231], off
	v_lshl_add_u64 v[230:231], v[232:233], 0, s[34:35]
	s_add_i32 m0, s20, 0x2000
	s_nop 0
	global_load_lds_dwordx4 v[230:231], off
	s_barrier
	s_waitcnt lgkmcnt(0)
	s_setprio 1
	s_waitcnt lgkmcnt(0)
	v_mfma_f32_16x16x32_bf16 v[116:119], v[214:217], v[160:163], v[116:119]
	v_mfma_f32_16x16x32_bf16 v[108:111], v[222:225], v[160:163], v[108:111]
	v_mfma_f32_16x16x32_bf16 v[100:103], v[214:217], v[190:193], v[100:103]
	v_mfma_f32_16x16x32_bf16 v[92:95], v[222:225], v[190:193], v[92:95]
	v_mfma_f32_16x16x32_bf16 v[84:87], v[214:217], v[198:201], v[84:87]
	v_mfma_f32_16x16x32_bf16 v[76:79], v[222:225], v[198:201], v[76:79]
	v_mfma_f32_16x16x32_bf16 v[68:71], v[214:217], v[206:209], v[68:71]
	v_mfma_f32_16x16x32_bf16 v[64:67], v[222:225], v[206:209], v[64:67]
	v_mfma_f32_16x16x32_bf16 v[116:119], v[218:221], v[164:167], v[116:119]
	v_mfma_f32_16x16x32_bf16 v[108:111], v[226:229], v[164:167], v[108:111]
	v_mfma_f32_16x16x32_bf16 v[100:103], v[218:221], v[194:197], v[100:103]
	v_mfma_f32_16x16x32_bf16 v[92:95], v[226:229], v[194:197], v[92:95]
	v_mfma_f32_16x16x32_bf16 v[84:87], v[218:221], v[202:205], v[84:87]
	v_mfma_f32_16x16x32_bf16 v[76:79], v[226:229], v[202:205], v[76:79]
	v_mfma_f32_16x16x32_bf16 v[68:71], v[218:221], v[210:213], v[68:71]
	v_mfma_f32_16x16x32_bf16 v[64:67], v[226:229], v[210:213], v[64:67]
	s_setprio 0
	s_mov_b32 m0, s50
	v_lshl_add_u64 v[230:231], v[234:235], 0, s[34:35]
	s_barrier
	ds_read_b128 v[160:163], v147 offset:49152
	ds_read_b128 v[164:167], v147 offset:50176
	ds_read_b128 v[190:193], v147 offset:51200
	ds_read_b128 v[194:197], v147 offset:52224
	ds_read_b128 v[198:201], v147 offset:53248
	ds_read_b128 v[202:205], v147 offset:54272
	ds_read_b128 v[206:209], v147 offset:55296
	ds_read_b128 v[210:213], v147 offset:56320
	global_load_lds_dwordx4 v[230:231], off
	v_lshl_add_u64 v[230:231], v[236:237], 0, s[34:35]
	s_mov_b32 m0, s51
	s_nop 0
	global_load_lds_dwordx4 v[230:231], off
	s_barrier
; __device__ __forceinline__ unsigned pk_bf16(float lo, float hi) { return (unsigned)f2bf(lo) | ((unsigned)f2bf(hi) << 16); }
; #define G_STAGE(bufoff, gbase, voff) do { _Pragma("unroll") for (int _i = 0; _i < 2; ++_i) \
;     __builtin_amdgcn_global_load_lds((const unsigned*)((const char*)(gbase) + (voff)[_i]), (LAS unsigned*)(lds + (bufoff) + ldsw + _i * 8192), 16, 0, 0); } while (0)
; #define G_LDA(dst, b, h) do { _Pragma("unroll") for (int m = 0; m < 4; ++m) _Pragma("unroll") for (int k = 0; k < 2; ++k) dst[m][k] = *(const LAS bf16x8*)(lds + G_SA(b, h) + aoff + m * 2048 + k * 1024); } while (0)
; #define G_LDB(dst, b, h) do { _Pragma("unroll") for (int n = 0; n < 2; ++n) _Pragma("unroll") for (int k = 0; k < 2; ++k) dst[n][k] = *(const LAS bf16x8*)(lds + G_SB(b, h) + boff + n * 2048 + k * 1024); } while (0)
; #define G_WAIT_V(n) asm volatile("s_waitcnt vmcnt(" #n ")" ::: "memory")
;   __device__ __forceinline__ void operator()(const f32x4 (&acc)[2][2][4][2], const Unit& u, int wr, int wc, int fr, int fq) const {
;     const int row0 = u.pm * BM + wr * 64 + fr, col0 = u.pn * BM + wc * 32 + 4 * fq;
; #pragma unroll
;     for (int ai = 0; ai < 2; ++ai)
; #pragma unroll
;       for (int m = 0; m < 4; ++m) {
;         u16* rowp = O + (size_t)(row0 + ai * HALF + m * 16) * PROJP + col0;
; #pragma unroll
;         for (int bj = 0; bj < 2; ++bj)
; #pragma unroll
;           for (int n = 0; n < 2; ++n) {
;             f32x4 v = acc[ai][bj][m][n];
;             uint2 w; w.x = pk_bf16(v[0], v[1]); w.y = pk_bf16(v[2], v[3]);
;             *reinterpret_cast<uint2*>(rowp + bj * HALF + n * 16) = w;
;           }
;       }
;   }
; template <class Epi>
; __device__ __forceinline__ void gemm_phase(LAS unsigned char* lds, const u16* gA, const u16* gBt, int M, int N, int K, const Epi& E) {
;     ...
;       G_WAIT_V(6); G_BAR; G_MMA(1, 1, At, B1); G_BAR;
;       G_LDB(B0, 1, 0); G_SCHED; G_LDA(At, 1, 0); G_STAGE(G_SA(0, 1), a2 + hstep, voffA);
;       G_WAIT_L(8); G_BAR; G_WAIT_L(0); G_MMA(0, 0, At, B0); G_BAR; G_SCHED;
;       G_LDB(B1, 1, 1); G_STAGE(G_SB(1, 0), b3, voffB);
;       G_BAR; G_WAIT_L(0); G_MMA(0, 1, At, B1); G_BAR;
;       G_LDA(At, 1, 1); G_STAGE(G_SA(1, 0), a3, voffA);
;       G_BAR; G_WAIT_L(0); G_MMA(1, 0, At, B0); G_BAR; G_SCHED;
;       G_STAGE(G_SB(1, 1), b3 + hstep, voffB);
;       G_WAIT_V(6); G_BAR; G_MMA(1, 1, At, B1); G_BAR;
;     }
	s_waitcnt lgkmcnt(0)
	s_setprio 1
	s_waitcnt lgkmcnt(0)
	v_mfma_f32_16x16x32_bf16 v[60:63], v[140:143], v[160:163], v[60:63]
	v_mfma_f32_16x16x32_bf16 v[56:59], v[152:155], v[160:163], v[56:59]
	v_mfma_f32_16x16x32_bf16 v[48:51], v[140:143], v[190:193], v[48:51]
	v_mfma_f32_16x16x32_bf16 v[40:43], v[152:155], v[190:193], v[40:43]
	v_mfma_f32_16x16x32_bf16 v[32:35], v[140:143], v[198:201], v[32:35]
	v_mfma_f32_16x16x32_bf16 v[24:27], v[152:155], v[198:201], v[24:27]
	v_mfma_f32_16x16x32_bf16 v[16:19], v[140:143], v[206:209], v[16:19]
	v_mfma_f32_16x16x32_bf16 v[8:11], v[152:155], v[206:209], v[8:11]
	v_mfma_f32_16x16x32_bf16 v[60:63], v[148:151], v[164:167], v[60:63]
	v_mfma_f32_16x16x32_bf16 v[56:59], v[156:159], v[164:167], v[56:59]
	v_mfma_f32_16x16x32_bf16 v[48:51], v[148:151], v[194:197], v[48:51]
	v_mfma_f32_16x16x32_bf16 v[40:43], v[156:159], v[194:197], v[40:43]
	v_mfma_f32_16x16x32_bf16 v[32:35], v[148:151], v[202:205], v[32:35]
	v_mfma_f32_16x16x32_bf16 v[24:27], v[156:159], v[202:205], v[24:27]
	v_mfma_f32_16x16x32_bf16 v[16:19], v[148:151], v[210:213], v[16:19]
	v_mfma_f32_16x16x32_bf16 v[8:11], v[156:159], v[210:213], v[8:11]
	s_setprio 0
	s_barrier
	s_add_u32 s24, s44, 0x80080
	s_addc_u32 s25, s45, 0
	s_add_i32 s20, s22, s26
	v_lshl_add_u64 v[140:141], s[24:25], 0, v[128:129]
	s_mov_b32 m0, s20
	s_nop 0
	global_load_lds_dwordx4 v[140:141], off
	v_lshl_add_u64 v[140:141], s[24:25], 0, v[134:135]
	s_add_i32 m0, s20, 0x2000
	s_nop 0
	global_load_lds_dwordx4 v[140:141], off
	s_waitcnt vmcnt(6)
	s_barrier
	s_setprio 1
	v_mfma_f32_16x16x32_bf16 v[52:55], v[214:217], v[160:163], v[52:55]
	v_mfma_f32_16x16x32_bf16 v[44:47], v[222:225], v[160:163], v[44:47]
	v_mfma_f32_16x16x32_bf16 v[36:39], v[214:217], v[190:193], v[36:39]
	v_mfma_f32_16x16x32_bf16 v[28:31], v[222:225], v[190:193], v[28:31]
	v_mfma_f32_16x16x32_bf16 v[20:23], v[214:217], v[198:201], v[20:23]
	v_mfma_f32_16x16x32_bf16 v[12:15], v[222:225], v[198:201], v[12:15]
	v_mfma_f32_16x16x32_bf16 v[4:7], v[214:217], v[206:209], v[4:7]
	v_mfma_f32_16x16x32_bf16 v[0:3], v[222:225], v[206:209], v[0:3]
	v_mfma_f32_16x16x32_bf16 v[52:55], v[218:221], v[164:167], v[52:55]
	v_mfma_f32_16x16x32_bf16 v[44:47], v[226:229], v[164:167], v[44:47]
	v_mfma_f32_16x16x32_bf16 v[36:39], v[218:221], v[194:197], v[36:39]
	v_mfma_f32_16x16x32_bf16 v[28:31], v[226:229], v[194:197], v[28:31]
	v_mfma_f32_16x16x32_bf16 v[20:23], v[218:221], v[202:205], v[20:23]
	v_mfma_f32_16x16x32_bf16 v[12:15], v[226:229], v[202:205], v[12:15]
	v_mfma_f32_16x16x32_bf16 v[4:7], v[218:221], v[210:213], v[4:7]
	v_mfma_f32_16x16x32_bf16 v[0:3], v[226:229], v[210:213], v[0:3]
	s_setprio 0
	s_add_i32 s58, s58, 2
	s_add_u32 s42, s42, 0x100
	s_addc_u32 s43, s43, 0
	s_add_u32 s56, s56, 0x100
	s_addc_u32 s57, s57, 0
	s_cmp_gt_u32 s58, 29
	s_barrier
	s_cbranch_scc0 .LBB0_370
	v_lshl_or_b32 v142, s30, 8, v146
	v_lshl_add_u32 v150, s31, 8, v144
	v_ashrrev_i32_e32 v143, 31, v142
	v_mov_b64_e32 v[140:141], s[94:95]
	s_movk_i32 s1, 0x3600
	v_mad_i64_i32 v[148:149], s[24:25], v150, s1, v[140:141]
	v_lshlrev_b64 v[142:143], 1, v[142:143]
	v_lshl_add_u64 v[148:149], v[148:149], 0, v[142:143]
	v_cvt_pk_bf16_f32 v124, v124, v125
	v_cvt_pk_bf16_f32 v125, v126, v127
	global_store_dwordx2 v[148:149], v[124:125], off
	v_cvt_pk_bf16_f32 v120, v120, v121
	v_cvt_pk_bf16_f32 v121, v122, v123
	global_store_dwordx2 v[148:149], v[120:121], off offset:32
	v_cvt_pk_bf16_f32 v116, v116, v117
	v_cvt_pk_bf16_f32 v117, v118, v119
	global_store_dwordx2 v[148:149], v[116:117], off offset:256
	v_and_b32_sdwa v117, v108, v172 dst_sel:DWORD dst_unused:UNUSED_PAD src0_sel:WORD_1 src1_sel:DWORD
	v_add3_u32 v108, v108, v117, s21
	v_and_b32_sdwa v117, v109, v172 dst_sel:DWORD dst_unused:UNUSED_PAD src0_sel:WORD_1 src1_sel:DWORD
	v_add3_u32 v109, v109, v117, s21
	v_and_b32_e32 v116, 0xffff0000, v109
	v_cvt_pk_bf16_f32 v109, v110, v111
	v_and_b32_sdwa v110, v114, v172 dst_sel:DWORD dst_unused:UNUSED_PAD src0_sel:WORD_1 src1_sel:DWORD
	v_or_b32_sdwa v108, v116, v108 dst_sel:DWORD dst_unused:UNUSED_PAD src0_sel:DWORD src1_sel:WORD_1
	v_add3_u32 v110, v114, v110, s21
	v_and_b32_sdwa v111, v115, v172 dst_sel:DWORD dst_unused:UNUSED_PAD src0_sel:WORD_1 src1_sel:DWORD
	global_store_dwordx2 v[148:149], v[108:109], off offset:288
	v_or_b32_e32 v108, 16, v150
	v_add3_u32 v111, v115, v111, s21
	v_mad_i64_i32 v[108:109], s[24:25], v108, s1, v[140:141]
	v_and_b32_e32 v111, 0xffff0000, v111
	v_lshl_add_u64 v[108:109], v[108:109], 0, v[142:143]
	v_or_b32_sdwa v111, v111, v110 dst_sel:DWORD dst_unused:UNUSED_PAD src0_sel:DWORD src1_sel:WORD_1
	v_cvt_pk_bf16_f32 v110, v112, v113
	global_store_dwordx2 v[108:109], v[110:111], off
	v_cvt_pk_bf16_f32 v104, v104, v105
	v_cvt_pk_bf16_f32 v105, v106, v107
	global_store_dwordx2 v[108:109], v[104:105], off offset:32
	v_cvt_pk_bf16_f32 v100, v100, v101
	v_cvt_pk_bf16_f32 v101, v102, v103
	global_store_dwordx2 v[108:109], v[100:101], off offset:256
	v_and_b32_sdwa v101, v92, v172 dst_sel:DWORD dst_unused:UNUSED_PAD src0_sel:WORD_1 src1_sel:DWORD
	v_add3_u32 v92, v92, v101, s21
	v_and_b32_sdwa v101, v93, v172 dst_sel:DWORD dst_unused:UNUSED_PAD src0_sel:WORD_1 src1_sel:DWORD
	v_add3_u32 v93, v93, v101, s21
	v_and_b32_e32 v100, 0xffff0000, v93
	v_cvt_pk_bf16_f32 v93, v94, v95
	v_and_b32_sdwa v94, v98, v172 dst_sel:DWORD dst_unused:UNUSED_PAD src0_sel:WORD_1 src1_sel:DWORD
	v_or_b32_sdwa v92, v100, v92 dst_sel:DWORD dst_unused:UNUSED_PAD src0_sel:DWORD src1_sel:WORD_1
	v_add3_u32 v94, v98, v94, s21
	v_and_b32_sdwa v95, v99, v172 dst_sel:DWORD dst_unused:UNUSED_PAD src0_sel:WORD_1 src1_sel:DWORD
	global_store_dwordx2 v[108:109], v[92:93], off offset:288
; __device__ __forceinline__ unsigned pk_bf16(float lo, float hi) { return (unsigned)f2bf(lo) | ((unsigned)f2bf(hi) << 16); }
; #define G_WAIT_V(n) asm volatile("s_waitcnt vmcnt(" #n ")" ::: "memory")
; #define G_BAR __builtin_amdgcn_s_barrier()
;   __device__ __forceinline__ void operator()(const f32x4 (&acc)[2][2][4][2], const Unit& u, int wr, int wc, int fr, int fq) const {
;     const int row0 = u.pm * BM + wr * 64 + fr, col0 = u.pn * BM + wc * 32 + 4 * fq;
; #pragma unroll
;     for (int ai = 0; ai < 2; ++ai)
; #pragma unroll
;       for (int m = 0; m < 4; ++m) {
;         u16* rowp = O + (size_t)(row0 + ai * HALF + m * 16) * PROJP + col0;
; #pragma unroll
;         for (int bj = 0; bj < 2; ++bj)
; #pragma unroll
;           for (int n = 0; n < 2; ++n) {
;             f32x4 v = acc[ai][bj][m][n];
;             uint2 w; w.x = pk_bf16(v[0], v[1]); w.y = pk_bf16(v[2], v[3]);
;             *reinterpret_cast<uint2*>(rowp + bj * HALF + n * 16) = w;
;           }
;       }
;   }
; template <class Epi>
; __device__ __forceinline__ void gemm_phase(LAS unsigned char* lds, const u16* gA, const u16* gBt, int M, int N, int K, const Epi& E) {
;     ...
;     E(acc, cur, wr, wc, fr, fq);
;     if (!has_next) break;
; #pragma unroll
;     for (int a = 0; a < 2; ++a)
; #pragma unroll
;       for (int b = 0; b < 2; ++b)
; #pragma unroll
;         for (int m = 0; m < 4; ++m)
; #pragma unroll
;           for (int n = 0; n < 2; ++n) acc[a][b][m][n] = (f32x4){0.f, 0.f, 0.f, 0.f};
;     cur = nxt; cA = nA; cB = nB; ++ui;
;   }
;   G_WAIT_V(0);
;   if (wr == 0) G_BAR;
	v_or_b32_e32 v92, 32, v150
	v_add3_u32 v95, v99, v95, s21
	v_mad_i64_i32 v[92:93], s[24:25], v92, s1, v[140:141]
	v_and_b32_e32 v95, 0xffff0000, v95
	v_lshl_add_u64 v[92:93], v[92:93], 0, v[142:143]
	v_or_b32_sdwa v95, v95, v94 dst_sel:DWORD dst_unused:UNUSED_PAD src0_sel:DWORD src1_sel:WORD_1
	v_cvt_pk_bf16_f32 v94, v96, v97
	global_store_dwordx2 v[92:93], v[94:95], off
	v_cvt_pk_bf16_f32 v88, v88, v89
	v_cvt_pk_bf16_f32 v89, v90, v91
	global_store_dwordx2 v[92:93], v[88:89], off offset:32
	v_cvt_pk_bf16_f32 v84, v84, v85
	v_cvt_pk_bf16_f32 v85, v86, v87
	global_store_dwordx2 v[92:93], v[84:85], off offset:256
	v_and_b32_sdwa v85, v76, v172 dst_sel:DWORD dst_unused:UNUSED_PAD src0_sel:WORD_1 src1_sel:DWORD
	v_add3_u32 v76, v76, v85, s21
	v_and_b32_sdwa v85, v77, v172 dst_sel:DWORD dst_unused:UNUSED_PAD src0_sel:WORD_1 src1_sel:DWORD
	v_add3_u32 v77, v77, v85, s21
	v_and_b32_e32 v84, 0xffff0000, v77
	v_cvt_pk_bf16_f32 v77, v78, v79
	v_and_b32_sdwa v78, v82, v172 dst_sel:DWORD dst_unused:UNUSED_PAD src0_sel:WORD_1 src1_sel:DWORD
	v_or_b32_sdwa v76, v84, v76 dst_sel:DWORD dst_unused:UNUSED_PAD src0_sel:DWORD src1_sel:WORD_1
	v_add3_u32 v78, v82, v78, s21
	v_and_b32_sdwa v79, v83, v172 dst_sel:DWORD dst_unused:UNUSED_PAD src0_sel:WORD_1 src1_sel:DWORD
	global_store_dwordx2 v[92:93], v[76:77], off offset:288
	v_or_b32_e32 v76, 48, v150
	v_add3_u32 v79, v83, v79, s21
	v_mad_i64_i32 v[76:77], s[24:25], v76, s1, v[140:141]
	v_and_b32_e32 v79, 0xffff0000, v79
	v_lshl_add_u64 v[76:77], v[76:77], 0, v[142:143]
	v_or_b32_sdwa v79, v79, v78 dst_sel:DWORD dst_unused:UNUSED_PAD src0_sel:DWORD src1_sel:WORD_1
	v_cvt_pk_bf16_f32 v78, v80, v81
	global_store_dwordx2 v[76:77], v[78:79], off
	v_cvt_pk_bf16_f32 v72, v72, v73
	v_cvt_pk_bf16_f32 v73, v74, v75
	global_store_dwordx2 v[76:77], v[72:73], off offset:32
	v_cvt_pk_bf16_f32 v68, v68, v69
	v_cvt_pk_bf16_f32 v69, v70, v71
	global_store_dwordx2 v[76:77], v[68:69], off offset:256
	v_cvt_pk_bf16_f32 v64, v64, v65
	v_cvt_pk_bf16_f32 v65, v66, v67
	global_store_dwordx2 v[76:77], v[64:65], off offset:288
	v_add_u32_e32 v64, 0x80, v150
	v_mad_i64_i32 v[64:65], s[24:25], v64, s1, v[140:141]
	v_lshl_add_u64 v[64:65], v[64:65], 0, v[142:143]
	v_cvt_pk_bf16_f32 v60, v60, v61
	v_cvt_pk_bf16_f32 v61, v62, v63
	global_store_dwordx2 v[64:65], v[60:61], off
	v_cvt_pk_bf16_f32 v56, v56, v57
	v_cvt_pk_bf16_f32 v57, v58, v59
	global_store_dwordx2 v[64:65], v[56:57], off offset:32
	v_cvt_pk_bf16_f32 v52, v52, v53
	v_cvt_pk_bf16_f32 v53, v54, v55
	global_store_dwordx2 v[64:65], v[52:53], off offset:256
	v_and_b32_sdwa v53, v44, v172 dst_sel:DWORD dst_unused:UNUSED_PAD src0_sel:WORD_1 src1_sel:DWORD
	v_add3_u32 v44, v44, v53, s21
	v_and_b32_sdwa v53, v45, v172 dst_sel:DWORD dst_unused:UNUSED_PAD src0_sel:WORD_1 src1_sel:DWORD
	v_add3_u32 v45, v45, v53, s21
	v_and_b32_e32 v52, 0xffff0000, v45
	v_cvt_pk_bf16_f32 v45, v46, v47
	v_and_b32_sdwa v46, v50, v172 dst_sel:DWORD dst_unused:UNUSED_PAD src0_sel:WORD_1 src1_sel:DWORD
	v_or_b32_sdwa v44, v52, v44 dst_sel:DWORD dst_unused:UNUSED_PAD src0_sel:DWORD src1_sel:WORD_1
	v_add3_u32 v46, v50, v46, s21
	v_and_b32_sdwa v47, v51, v172 dst_sel:DWORD dst_unused:UNUSED_PAD src0_sel:WORD_1 src1_sel:DWORD
	global_store_dwordx2 v[64:65], v[44:45], off offset:288
	v_add_u32_e32 v44, 0x90, v150
	v_add3_u32 v47, v51, v47, s21
	v_mad_i64_i32 v[44:45], s[24:25], v44, s1, v[140:141]
	v_and_b32_e32 v47, 0xffff0000, v47
	v_lshl_add_u64 v[44:45], v[44:45], 0, v[142:143]
	v_or_b32_sdwa v47, v47, v46 dst_sel:DWORD dst_unused:UNUSED_PAD src0_sel:DWORD src1_sel:WORD_1
	v_cvt_pk_bf16_f32 v46, v48, v49
	global_store_dwordx2 v[44:45], v[46:47], off
	v_cvt_pk_bf16_f32 v40, v40, v41
	v_cvt_pk_bf16_f32 v41, v42, v43
	global_store_dwordx2 v[44:45], v[40:41], off offset:32
	v_cvt_pk_bf16_f32 v36, v36, v37
	v_cvt_pk_bf16_f32 v37, v38, v39
	global_store_dwordx2 v[44:45], v[36:37], off offset:256
	v_and_b32_sdwa v37, v28, v172 dst_sel:DWORD dst_unused:UNUSED_PAD src0_sel:WORD_1 src1_sel:DWORD
	v_add3_u32 v28, v28, v37, s21
	v_and_b32_sdwa v37, v29, v172 dst_sel:DWORD dst_unused:UNUSED_PAD src0_sel:WORD_1 src1_sel:DWORD
	v_add3_u32 v29, v29, v37, s21
	v_and_b32_e32 v36, 0xffff0000, v29
	v_cvt_pk_bf16_f32 v29, v30, v31
	v_and_b32_sdwa v30, v34, v172 dst_sel:DWORD dst_unused:UNUSED_PAD src0_sel:WORD_1 src1_sel:DWORD
	v_or_b32_sdwa v28, v36, v28 dst_sel:DWORD dst_unused:UNUSED_PAD src0_sel:DWORD src1_sel:WORD_1
	v_add3_u32 v30, v34, v30, s21
	v_and_b32_sdwa v31, v35, v172 dst_sel:DWORD dst_unused:UNUSED_PAD src0_sel:WORD_1 src1_sel:DWORD
	global_store_dwordx2 v[44:45], v[28:29], off offset:288
	v_add_u32_e32 v28, 0xa0, v150
	v_add3_u32 v31, v35, v31, s21
	v_mad_i64_i32 v[28:29], s[24:25], v28, s1, v[140:141]
	v_and_b32_e32 v31, 0xffff0000, v31
	v_lshl_add_u64 v[28:29], v[28:29], 0, v[142:143]
	v_or_b32_sdwa v31, v31, v30 dst_sel:DWORD dst_unused:UNUSED_PAD src0_sel:DWORD src1_sel:WORD_1
	v_cvt_pk_bf16_f32 v30, v32, v33
	global_store_dwordx2 v[28:29], v[30:31], off
	v_cvt_pk_bf16_f32 v24, v24, v25
	v_cvt_pk_bf16_f32 v25, v26, v27
	global_store_dwordx2 v[28:29], v[24:25], off offset:32
	v_cvt_pk_bf16_f32 v20, v20, v21
	v_cvt_pk_bf16_f32 v21, v22, v23
	global_store_dwordx2 v[28:29], v[20:21], off offset:256
	v_and_b32_sdwa v21, v12, v172 dst_sel:DWORD dst_unused:UNUSED_PAD src0_sel:WORD_1 src1_sel:DWORD
	v_add3_u32 v12, v12, v21, s21
	v_and_b32_sdwa v21, v13, v172 dst_sel:DWORD dst_unused:UNUSED_PAD src0_sel:WORD_1 src1_sel:DWORD
	v_add3_u32 v13, v13, v21, s21
	v_and_b32_e32 v20, 0xffff0000, v13
	v_cvt_pk_bf16_f32 v13, v14, v15
	v_and_b32_sdwa v14, v18, v172 dst_sel:DWORD dst_unused:UNUSED_PAD src0_sel:WORD_1 src1_sel:DWORD
	v_or_b32_sdwa v12, v20, v12 dst_sel:DWORD dst_unused:UNUSED_PAD src0_sel:DWORD src1_sel:WORD_1
	v_add3_u32 v14, v18, v14, s21
	v_and_b32_sdwa v15, v19, v172 dst_sel:DWORD dst_unused:UNUSED_PAD src0_sel:WORD_1 src1_sel:DWORD
	global_store_dwordx2 v[28:29], v[12:13], off offset:288
	v_add_u32_e32 v12, 0xb0, v150
	v_add3_u32 v15, v19, v15, s21
	v_mad_i64_i32 v[12:13], s[24:25], v12, s1, v[140:141]
	v_and_b32_e32 v15, 0xffff0000, v15
	v_lshl_add_u64 v[12:13], v[12:13], 0, v[142:143]
	v_or_b32_sdwa v15, v15, v14 dst_sel:DWORD dst_unused:UNUSED_PAD src0_sel:DWORD src1_sel:WORD_1
	v_cvt_pk_bf16_f32 v14, v16, v17
	global_store_dwordx2 v[12:13], v[14:15], off
	v_cvt_pk_bf16_f32 v8, v8, v9
	v_cvt_pk_bf16_f32 v9, v10, v11
	global_store_dwordx2 v[12:13], v[8:9], off offset:32
	v_cvt_pk_bf16_f32 v4, v4, v5
	v_cvt_pk_bf16_f32 v5, v6, v7
	global_store_dwordx2 v[12:13], v[4:5], off offset:256
	v_cvt_pk_bf16_f32 v0, v0, v1
	v_cvt_pk_bf16_f32 v1, v2, v3
	s_and_b64 vcc, exec, s[38:39]
	s_mov_b32 s30, s0
	s_mov_b32 s31, s2
	s_mov_b64 s[44:45], s[40:41]
	s_mov_b64 s[42:43], s[36:37]
	global_store_dwordx2 v[12:13], v[0:1], off offset:288
	s_cbranch_vccz .LBB0_363
	s_waitcnt vmcnt(0)
	s_cmpk_gt_u32 s23, 0xff
	s_cbranch_scc1 .LBB0_374
	s_barrier

; #define LAS __attribute__((address_space(3)))
; __global__ void __launch_bounds__(NTHR, 2) mega(P p, int ph0, int ph1) {
;   extern __shared__ __attribute__((aligned(16))) char shm[];
;   volatile LAS unsigned* xst = (volatile LAS unsigned*)((LAS char*)shm + LDS_TOTAL - 16);
;   if (threadIdx.x < 4) xst[threadIdx.x] = 0u;
;   __syncthreads();
;   XcdBarrier xb = xcd_barrier_post(p.bar, xst);
	.amdhsa_kernel _Z4mega1Pii
		.amdhsa_group_segment_fixed_size 0
		.amdhsa_private_segment_fixed_size 0
		.amdhsa_kernarg_size 664
		.amdhsa_user_sgpr_count 2
		.amdhsa_user_sgpr_dispatch_ptr 0
		.amdhsa_user_sgpr_queue_ptr 0
		.amdhsa_user_sgpr_kernarg_segment_ptr 1
		.amdhsa_user_sgpr_dispatch_id 0
		.amdhsa_user_sgpr_kernarg_preload_length 0
		.amdhsa_user_sgpr_kernarg_preload_offset 0
		.amdhsa_user_sgpr_private_segment_size 0
		.amdhsa_uses_dynamic_stack 0
		.amdhsa_enable_private_segment 0
		.amdhsa_system_sgpr_workgroup_id_x 1
		.amdhsa_system_sgpr_workgroup_id_y 0
		.amdhsa_system_sgpr_workgroup_id_z 0
		.amdhsa_system_sgpr_workgroup_info 0
		.amdhsa_system_vgpr_workitem_id 2
		.amdhsa_next_free_vgpr 256
		.amdhsa_next_free_sgpr 98
		.amdhsa_accum_offset 256
		.amdhsa_reserve_vcc 1
		.amdhsa_float_round_mode_32 0
		.amdhsa_float_round_mode_16_64 0
		.amdhsa_float_denorm_mode_32 3
		.amdhsa_float_denorm_mode_16_64 3
		.amdhsa_dx10_clamp 1
		.amdhsa_ieee_mode 1
		.amdhsa_fp16_overflow 0
		.amdhsa_tg_split 0
		.amdhsa_exception_fp_ieee_invalid_op 0
		.amdhsa_exception_fp_denorm_src 0
		.amdhsa_exception_fp_ieee_div_zero 0
		.amdhsa_exception_fp_ieee_overflow 0
		.amdhsa_exception_fp_ieee_underflow 0
		.amdhsa_exception_fp_ieee_inexact 0
		.amdhsa_exception_int_div_zero 0
	.end_amdhsa_kernel

; #define LAS __attribute__((address_space(3)))
; __global__ void __launch_bounds__(NTHR, 2) mega(P p, int ph0, int ph1) {
;   extern __shared__ __attribute__((aligned(16))) char shm[];
;   volatile LAS unsigned* xst = (volatile LAS unsigned*)((LAS char*)shm + LDS_TOTAL - 16);
;   if (threadIdx.x < 4) xst[threadIdx.x] = 0u;
;   __syncthreads();
;   XcdBarrier xb = xcd_barrier_post(p.bar, xst);
amdhsa.kernels:
  - .agpr_count:     0
    .args:
      - .offset:         0
        .size:           400
        .value_kind:     by_value
      - .offset:         400
        .size:           4
        .value_kind:     by_value
      - .offset:         404
        .size:           4
        .value_kind:     by_value
      - .offset:         408
        .size:           4
        .value_kind:     hidden_block_count_x
      - .offset:         412
        .size:           4
        .value_kind:     hidden_block_count_y
      - .offset:         416
        .size:           4
        .value_kind:     hidden_block_count_z
      - .offset:         420
        .size:           2
        .value_kind:     hidden_group_size_x
      - .offset:         422
        .size:           2
        .value_kind:     hidden_group_size_y
      - .offset:         424
        .size:           2
        .value_kind:     hidden_group_size_z
      - .offset:         426
        .size:           2
        .value_kind:     hidden_remainder_x
      - .offset:         428
        .size:           2
        .value_kind:     hidden_remainder_y
      - .offset:         430
        .size:           2
        .value_kind:     hidden_remainder_z
      - .offset:         448
        .size:           8
        .value_kind:     hidden_global_offset_x
      - .offset:         456
        .size:           8
        .value_kind:     hidden_global_offset_y
      - .offset:         464
        .size:           8
        .value_kind:     hidden_global_offset_z
      - .offset:         472
        .size:           2
        .value_kind:     hidden_grid_dims
      - .offset:         496
        .size:           8
        .value_kind:     hidden_multigrid_sync_arg
      - .offset:         528
        .size:           4
        .value_kind:     hidden_dynamic_lds_size
    .group_segment_fixed_size: 0
    .kernarg_segment_align: 8
    .kernarg_segment_size: 664
    .language:       OpenCL C
    .language_version:
      - 2
      - 0
    .max_flat_workgroup_size: 512
    .name:           _Z4mega1Pii
    .private_segment_fixed_size: 0
    .sgpr_count:     104
    .sgpr_spill_count: 189
    .symbol:         _Z4mega1Pii.kd
    .uniform_work_group_size: 1
    .uses_dynamic_stack: false
    .vgpr_count:     256
    .vgpr_spill_count: 0
    .wavefront_size: 64
